# speedup vs baseline: 1.0143x; 1.0143x over previous
; __device__ __forceinline__ float fexp2(float x) { return __builtin_amdgcn_exp2f(x); }
; template <int DKA, int DKB, int DV, bool BAND, bool SINK> ...
;     ...
;           for (int ks = 0; ks < KS; ++ks) a = mfma16(kf[ks], qf[qb][ks], a);
;           s[qb][kb2] = a;
;         }
;       }
; #pragma unroll
;       for (int qb = 0; qb < 2; ++qb) {
;         float mx = mrun[qb];
;         const int qp = qpos0 + wave * 32 + qb * 16 + fr;
; #pragma unroll
;         for (int kb2 = 0; kb2 < 2; ++kb2)
; #pragma unroll
;           for (int j = 0; j < 4; ++j) {
;             float v = s[qb][kb2][j] * scale2;
;             if (BAND && k0 < 2048) {
;               int d = qp - (k0 + (kk * 2 + kb2) * 16 + fq * 4 + j);
;               if (d > 128 || d < -128) v = -1e30f;
;             }
;             s[qb][kb2][j] = v;
;             mx = fmaxf(mx, v);
;           }
;         mx = fmaxf(mx, __shfl_xor(mx, 16));
;         mx = fmaxf(mx, __shfl_xor(mx, 32));
;         const float alpha = fexp2(mrun[qb] - mx);
;         mrun[qb] = mx;
;         float ls = 0.f;
; #pragma unroll
;         for (int kb2 = 0; kb2 < 2; ++kb2)
; #pragma unroll
;           for (int j = 0; j < 4; ++j) {
;             float pv = fexp2(s[qb][kb2][j] - mx);
;             s[qb][kb2][j] = pv;
;             ls += pv;
;           }
;         lrun[qb] = lrun[qb] * alpha + ls;
;         if (__any(alpha != 1.f)) {
; #pragma unroll
;           for (int eb = 0; eb < EB; ++eb) {
;             o[qb][eb][0] *= alpha; o[qb][eb][1] *= alpha; o[qb][eb][2] *= alpha; o[qb][eb][3] *= alpha;
;           }
;         }
;       }
;       bf16x8 pf[2];
; #pragma unroll
;       for (int qb = 0; qb < 2; ++qb)
;         pf[qb] = mk8(pack2(s[qb][0][0], s[qb][0][1]), pack2(s[qb][0][2], s[qb][0][3]),
;                      pack2(s[qb][1][0], s[qb][1][1]), pack2(s[qb][1][2], s[qb][1][3]));
; #pragma unroll
;       for (int eb = 0; eb < EB; ++eb) {
;         const char* vrow = vbuf + (eb * 16 + fr) * 128 + (fq & 1) * 8;
;         uint2 v0 = *(const uint2*)(vrow + (((kk * 4 + (fq >> 1)) ^ swz8) * 16));
;         uint2 v1 = *(const uint2*)(vrow + (((kk * 4 + 2 + (fq >> 1)) ^ swz8) * 16));
;         bf16x8 vf = mk8(v0.x, v0.y, v1.x, v1.y);
; #pragma unroll
;         for (int qb = 0; qb < 2; ++qb) o[qb][eb] = mfma16(vf, pf[qb], o[qb][eb]);
;       }
.LBB0_517:
	s_and_b32 s6, s0, 0x2000
	v_add_u32_e32 v0, s6, v68
	s_waitcnt vmcnt(0)
	s_waitcnt lgkmcnt(0)
	s_barrier
	v_readfirstlane_b32 s6, v0
	v_add_u32_e32 v0, 0x4000, v0
	s_mov_b32 m0, s6
	v_readfirstlane_b32 s6, v0
	global_load_lds_dwordx4 v[62:63], off
	s_mov_b32 m0, s6
	v_cmp_lt_i32_e32 vcc, v200, v198
	global_load_lds_dwordx4 v[60:61], off
	s_add_i32 s1, s0, 0xffffe000
	v_cndmask_b32_e32 v0, v197, v200, vcc
	v_cmp_lt_i32_e32 vcc, v199, v198
	s_and_b32 s1, s1, 0x2000
	v_lshlrev_b32_e32 v92, 2, v0
	v_cndmask_b32_e32 v0, v197, v199, vcc
	v_lshlrev_b32_e32 v91, 2, v0
	v_or_b32_e32 v0, s1, v70
	v_add_u32_e32 v66, v0, v72
	ds_read_b128 v[52:55], v66
	v_add_u32_e32 v64, v0, v73
	ds_read_b128 v[56:59], v64
	s_waitcnt lgkmcnt(0)
	v_mfma_f32_16x16x32_bf16 v[80:83], v[52:55], v[8:11], 0
	v_mfma_f32_16x16x32_bf16 v[52:55], v[52:55], v[12:15], 0
	v_mfma_f32_16x16x32_bf16 v[80:83], v[56:59], v[4:7], v[80:83]
	v_mfma_f32_16x16x32_bf16 v[52:55], v[56:59], v[16:19], v[52:55]
	ds_read_b128 v[56:59], v66 offset:2048
	ds_read_b128 v[84:87], v64 offset:2048
	s_nop 4
	v_mul_f32_e32 v88, 0x3e38aa3b, v81
	v_mul_f32_e32 v89, 0x3e38aa3b, v82
	s_waitcnt lgkmcnt(0)
	v_mfma_f32_16x16x32_bf16 v[98:101], v[56:59], v[8:11], 0
	v_mul_f32_e32 v97, 0x3e38aa3b, v83
	v_mfma_f32_16x16x32_bf16 v[56:59], v[56:59], v[12:15], 0
	v_mfma_f32_16x16x32_bf16 v[98:101], v[84:87], v[4:7], v[98:101]
	v_mfma_f32_16x16x32_bf16 v[56:59], v[84:87], v[16:19], v[56:59]
	v_mul_f32_e32 v87, 0x3e38aa3b, v80
	v_max3_f32 v0, v74, v87, v88
	v_max3_f32 v0, v0, v89, v97
	s_nop 3
	v_mul_f32_e32 v98, 0x3e38aa3b, v98
	v_mul_f32_e32 v99, 0x3e38aa3b, v99
	v_max3_f32 v0, v0, v98, v99
	v_mul_f32_e32 v100, 0x3e38aa3b, v100
	v_mul_f32_e32 v101, 0x3e38aa3b, v101
	v_max3_f32 v0, v0, v100, v101
	v_mov_b32_e32 v2, v0
	s_waitcnt lgkmcnt(0)
	s_nop 1
	v_permlane16_swap_b32_e32 v0, v2
	v_max_f32_e32 v0, v0, v2
	v_mov_b32_e32 v2, v0
	s_waitcnt lgkmcnt(0)
	v_mov_b32_e32 v85, v0
	s_nop 1
	v_permlane32_swap_b32_e32 v85, v2
	v_max_f32_e32 v85, v85, v2
	v_sub_f32_e32 v0, v74, v85
	v_exp_f32_e32 v2, v0
	s_nop 0
	v_cmp_neq_f32_e32 vcc, 1.0, v2
	s_cbranch_vccz .LBB0_519
	v_pk_mul_f32 v[46:47], v[46:47], v[2:3] op_sel_hi:[1,0]
	v_pk_mul_f32 v[44:45], v[44:45], v[2:3] op_sel_hi:[1,0]
	v_pk_mul_f32 v[26:27], v[26:27], v[2:3] op_sel_hi:[1,0]
	v_pk_mul_f32 v[24:25], v[24:25], v[2:3] op_sel_hi:[1,0]
	v_pk_mul_f32 v[38:39], v[38:39], v[2:3] op_sel_hi:[1,0]
	v_pk_mul_f32 v[36:37], v[36:37], v[2:3] op_sel_hi:[1,0]
	v_pk_mul_f32 v[42:43], v[42:43], v[2:3] op_sel_hi:[1,0]
	v_pk_mul_f32 v[40:41], v[40:41], v[2:3] op_sel_hi:[1,0]
.LBB0_519:
	v_mul_f32_e32 v76, 0x3e38aa3b, v52
	v_mul_f32_e32 v74, 0x3e38aa3b, v53
	v_max3_f32 v0, v3, v76, v74
	v_mul_f32_e32 v75, 0x3e38aa3b, v54
	v_mul_f32_e32 v55, 0x3e38aa3b, v55
	v_max3_f32 v0, v0, v75, v55
	v_mul_f32_e32 v56, 0x3e38aa3b, v56
	v_mul_f32_e32 v53, 0x3e38aa3b, v57
	v_max3_f32 v0, v0, v56, v53
	v_mul_f32_e32 v54, 0x3e38aa3b, v58
	v_mul_f32_e32 v52, 0x3e38aa3b, v59
	v_max3_f32 v0, v0, v54, v52
	v_mov_b32_e32 v57, v0
	s_waitcnt lgkmcnt(0)
	s_nop 1
	v_permlane16_swap_b32_e32 v0, v57
	v_max_f32_e32 v0, v0, v57
	v_mov_b32_e32 v57, v0
	s_waitcnt lgkmcnt(0)
	v_mov_b32_e32 v86, v0
	s_nop 1
	v_permlane32_swap_b32_e32 v86, v57
	v_max_f32_e32 v86, v86, v57
	v_sub_f32_e32 v0, v3, v86
	v_exp_f32_e32 v0, v0
	s_nop 0
	v_cmp_neq_f32_e32 vcc, 1.0, v0
	s_cbranch_vccz .LBB0_521
	v_pk_mul_f32 v[34:35], v[34:35], v[0:1] op_sel_hi:[1,0]
	v_pk_mul_f32 v[32:33], v[32:33], v[0:1] op_sel_hi:[1,0]
	v_pk_mul_f32 v[22:23], v[22:23], v[0:1] op_sel_hi:[1,0]
	v_pk_mul_f32 v[20:21], v[20:21], v[0:1] op_sel_hi:[1,0]
	v_pk_mul_f32 v[30:31], v[30:31], v[0:1] op_sel_hi:[1,0]
	v_pk_mul_f32 v[28:29], v[28:29], v[0:1] op_sel_hi:[1,0]
	v_pk_mul_f32 v[50:51], v[50:51], v[0:1] op_sel_hi:[1,0]
	v_pk_mul_f32 v[48:49], v[48:49], v[0:1] op_sel_hi:[1,0]
.LBB0_521:
	v_sub_f32_e32 v3, v76, v86
	v_exp_f32_e32 v76, v3
	v_sub_f32_e32 v3, v74, v86
	v_exp_f32_e32 v77, v3
	v_sub_f32_e32 v3, v75, v86
	v_exp_f32_e32 v78, v3
	v_sub_f32_e32 v3, v55, v86
	v_exp_f32_e32 v80, v3
	v_sub_f32_e32 v3, v56, v86
	v_exp_f32_e32 v81, v3
	v_sub_f32_e32 v3, v53, v86
	v_exp_f32_e32 v82, v3
	v_sub_f32_e32 v3, v54, v86
	v_exp_f32_e32 v83, v3
	v_sub_f32_e32 v3, v52, v86
	v_exp_f32_e32 v84, v3
	v_sub_f32_e32 v3, v87, v85
	v_exp_f32_e32 v87, v3
	v_sub_f32_e32 v3, v88, v85
	v_exp_f32_e32 v88, v3
	v_sub_f32_e32 v3, v89, v85
	v_exp_f32_e32 v89, v3
	v_sub_f32_e32 v3, v97, v85
	v_exp_f32_e32 v97, v3
	v_sub_f32_e32 v3, v98, v85
	v_exp_f32_e32 v98, v3
	v_sub_f32_e32 v3, v99, v85
	v_exp_f32_e32 v99, v3
	v_sub_f32_e32 v3, v100, v85
	v_add_u32_e32 v75, s1, v94
	v_exp_f32_e32 v100, v3
	v_sub_f32_e32 v3, v101, v85
	v_exp_f32_e32 v101, v3
	v_add_u32_e32 v3, v75, v71
	v_add_u32_e32 v74, v75, v69
	ds_read2st64_b64 v[102:105], v3 offset0:32 offset1:36
	ds_read2st64_b64 v[106:109], v74 offset0:32 offset1:36
	v_cvt_pk_bf16_f32 v52, v87, v88
	v_cvt_pk_bf16_f32 v53, v89, v97
	v_cvt_pk_bf16_f32 v54, v98, v99
	v_cvt_pk_bf16_f32 v55, v100, v101
	s_waitcnt lgkmcnt(0)
	v_mov_b32_e32 v112, v106
	v_mov_b32_e32 v113, v107
	v_mov_b32_e32 v106, v104
	v_mov_b32_e32 v107, v105
	v_cvt_pk_bf16_f32 v56, v76, v77
	v_cvt_pk_bf16_f32 v57, v78, v80
	v_cvt_pk_bf16_f32 v58, v81, v82
	v_cvt_pk_bf16_f32 v59, v83, v84
	v_mov_b32_e32 v110, v102
	v_mov_b32_e32 v111, v103
	v_mfma_f32_16x16x32_bf16 v[24:27], v[106:109], v[52:55], v[24:27]
	v_mfma_f32_16x16x32_bf16 v[20:23], v[106:109], v[56:59], v[20:23]
	ds_read2st64_b64 v[102:105], v3 offset0:40 offset1:44
	ds_read2st64_b64 v[106:109], v74 offset0:40 offset1:44
	v_mfma_f32_16x16x32_bf16 v[44:47], v[110:113], v[52:55], v[44:47]
	v_mfma_f32_16x16x32_bf16 v[32:35], v[110:113], v[56:59], v[32:35]
	s_waitcnt lgkmcnt(0)
; __device__ __forceinline__ float fexp2(float x) { return __builtin_amdgcn_exp2f(x); }
; template <int DKA, int DKB, int DV, bool BAND, bool SINK> ...
;     ...
;           for (int ks = 0; ks < KS; ++ks) a = mfma16(kf[ks], qf[qb][ks], a);
;           s[qb][kb2] = a;
;         }
;       }
; #pragma unroll
;       for (int qb = 0; qb < 2; ++qb) {
;         float mx = mrun[qb];
;         const int qp = qpos0 + wave * 32 + qb * 16 + fr;
; #pragma unroll
;         for (int kb2 = 0; kb2 < 2; ++kb2)
; #pragma unroll
;           for (int j = 0; j < 4; ++j) {
;             float v = s[qb][kb2][j] * scale2;
;             if (BAND && k0 < 2048) {
;               int d = qp - (k0 + (kk * 2 + kb2) * 16 + fq * 4 + j);
;               if (d > 128 || d < -128) v = -1e30f;
;             }
;             s[qb][kb2][j] = v;
;             mx = fmaxf(mx, v);
;           }
;         mx = fmaxf(mx, __shfl_xor(mx, 16));
;         mx = fmaxf(mx, __shfl_xor(mx, 32));
;         const float alpha = fexp2(mrun[qb] - mx);
;         mrun[qb] = mx;
;         float ls = 0.f;
; #pragma unroll
;         for (int kb2 = 0; kb2 < 2; ++kb2)
; #pragma unroll
;           for (int j = 0; j < 4; ++j) {
;             float pv = fexp2(s[qb][kb2][j] - mx);
;             s[qb][kb2][j] = pv;
;             ls += pv;
;           }
;         lrun[qb] = lrun[qb] * alpha + ls;
;         if (__any(alpha != 1.f)) {
; #pragma unroll
;           for (int eb = 0; eb < EB; ++eb) {
;             o[qb][eb][0] *= alpha; o[qb][eb][1] *= alpha; o[qb][eb][2] *= alpha; o[qb][eb][3] *= alpha;
;           }
;         }
;       }
	v_mov_b32_e32 v110, v102
	v_mov_b32_e32 v111, v103
	v_mov_b32_e32 v112, v106
	v_mov_b32_e32 v113, v107
	v_mov_b32_e32 v106, v104
	v_mov_b32_e32 v107, v105
	v_mfma_f32_16x16x32_bf16 v[36:39], v[110:113], v[52:55], v[36:39]
	v_mfma_f32_16x16x32_bf16 v[28:31], v[110:113], v[56:59], v[28:31]
	v_mfma_f32_16x16x32_bf16 v[40:43], v[106:109], v[52:55], v[40:43]
	v_mfma_f32_16x16x32_bf16 v[48:51], v[106:109], v[56:59], v[48:51]
	ds_read_b128 v[52:55], v66 offset:4096
	ds_read_b128 v[56:59], v64 offset:4096
	s_waitcnt lgkmcnt(0)
	v_mfma_f32_16x16x32_bf16 v[102:105], v[52:55], v[8:11], 0
	v_mfma_f32_16x16x32_bf16 v[52:55], v[52:55], v[12:15], 0
	v_mfma_f32_16x16x32_bf16 v[102:105], v[56:59], v[4:7], v[102:105]
	v_mfma_f32_16x16x32_bf16 v[52:55], v[56:59], v[16:19], v[52:55]
	ds_read_b128 v[56:59], v66 offset:6144
	ds_read_b128 v[106:109], v64 offset:6144
	s_waitcnt lgkmcnt(0)
	v_mfma_f32_16x16x32_bf16 v[110:113], v[56:59], v[8:11], 0
	v_mfma_f32_16x16x32_bf16 v[56:59], v[56:59], v[12:15], 0
	v_mfma_f32_16x16x32_bf16 v[110:113], v[106:109], v[4:7], v[110:113]
	v_mfma_f32_16x16x32_bf16 v[56:59], v[106:109], v[16:19], v[56:59]
	v_mul_f32_e32 v109, 0x3e38aa3b, v102
	v_mul_f32_e32 v108, 0x3e38aa3b, v103
	v_max3_f32 v3, v85, v109, v108
	v_mul_f32_e32 v107, 0x3e38aa3b, v104
	v_mul_f32_e32 v106, 0x3e38aa3b, v105
	v_max3_f32 v3, v3, v107, v106
	s_nop 0
	v_mul_f32_e32 v105, 0x3e38aa3b, v110
	v_mul_f32_e32 v104, 0x3e38aa3b, v111
	v_max3_f32 v3, v3, v105, v104
	v_mul_f32_e32 v103, 0x3e38aa3b, v112
	v_mul_f32_e32 v102, 0x3e38aa3b, v113
	v_max3_f32 v3, v3, v103, v102
	v_mov_b32_e32 v64, v3
	s_waitcnt lgkmcnt(0)
	s_nop 1
	v_permlane16_swap_b32_e32 v3, v64
	v_max_f32_e32 v3, v3, v64
	v_mov_b32_e32 v64, v3
	s_waitcnt lgkmcnt(0)
	v_mov_b32_e32 v74, v3
	s_nop 1
	v_permlane32_swap_b32_e32 v74, v64
	v_max_f32_e32 v74, v74, v64
	v_sub_f32_e32 v3, v85, v74
	v_exp_f32_e32 v64, v3
	s_nop 0
	v_cmp_neq_f32_e32 vcc, 1.0, v64
	s_cbranch_vccz .LBB0_523
	v_pk_mul_f32 v[46:47], v[46:47], v[64:65] op_sel_hi:[1,0]
	v_pk_mul_f32 v[44:45], v[44:45], v[64:65] op_sel_hi:[1,0]
	v_pk_mul_f32 v[26:27], v[26:27], v[64:65] op_sel_hi:[1,0]
	v_pk_mul_f32 v[24:25], v[24:25], v[64:65] op_sel_hi:[1,0]
	v_pk_mul_f32 v[38:39], v[38:39], v[64:65] op_sel_hi:[1,0]
	v_pk_mul_f32 v[36:37], v[36:37], v[64:65] op_sel_hi:[1,0]
	v_pk_mul_f32 v[42:43], v[42:43], v[64:65] op_sel_hi:[1,0]
	v_pk_mul_f32 v[40:41], v[40:41], v[64:65] op_sel_hi:[1,0]
.LBB0_523:
	v_mul_f32_e32 v3, 0x3e38aa3b, v52
	v_mul_f32_e32 v66, 0x3e38aa3b, v53
	v_max3_f32 v3, v86, v3, v66
	v_mul_f32_e32 v66, 0x3e38aa3b, v54
	v_mul_f32_e32 v85, 0x3e38aa3b, v55
	v_max3_f32 v3, v3, v66, v85
	v_mul_f32_e32 v66, 0x3e38aa3b, v56
	v_mul_f32_e32 v85, 0x3e38aa3b, v57
	v_max3_f32 v3, v3, v66, v85
	v_mul_f32_e32 v66, 0x3e38aa3b, v58
	v_mul_f32_e32 v85, 0x3e38aa3b, v59
	v_max3_f32 v3, v3, v66, v85
	v_mov_b32_e32 v66, v3
	s_waitcnt lgkmcnt(0)
	s_nop 1
	v_permlane16_swap_b32_e32 v3, v66
	v_max_f32_e32 v3, v3, v66
	v_mov_b32_e32 v66, v3
	s_waitcnt lgkmcnt(0)
	s_nop 1
	v_permlane32_swap_b32_e32 v3, v66
	v_max_f32_e32 v3, v3, v66
	v_sub_f32_e32 v66, v86, v3
	v_exp_f32_e32 v66, v66
	s_nop 0
	v_cmp_neq_f32_e32 vcc, 1.0, v66
	s_cbranch_vccz .LBB0_516
	v_pk_mul_f32 v[34:35], v[34:35], v[66:67] op_sel_hi:[1,0]
	v_pk_mul_f32 v[32:33], v[32:33], v[66:67] op_sel_hi:[1,0]
	v_pk_mul_f32 v[22:23], v[22:23], v[66:67] op_sel_hi:[1,0]
	v_pk_mul_f32 v[20:21], v[20:21], v[66:67] op_sel_hi:[1,0]
	v_pk_mul_f32 v[30:31], v[30:31], v[66:67] op_sel_hi:[1,0]
	v_pk_mul_f32 v[28:29], v[28:29], v[66:67] op_sel_hi:[1,0]
	v_pk_mul_f32 v[50:51], v[50:51], v[66:67] op_sel_hi:[1,0]
	v_pk_mul_f32 v[48:49], v[48:49], v[66:67] op_sel_hi:[1,0]
	s_branch .LBB0_516
.LBB0_525:
	s_waitcnt vmcnt(0)
	v_add_u32_e32 v2, v70, v73
	v_add_u32_e32 v73, v70, v72
	s_waitcnt lgkmcnt(0)
	s_barrier
	ds_read_b128 v[56:59], v2 offset:10240
	ds_read_b128 v[60:63], v73 offset:10240
	ds_read_b128 v[52:55], v2 offset:8192
	ds_read_b128 v[80:83], v73 offset:8192
	s_waitcnt lgkmcnt(0)
	v_mfma_f32_16x16x32_bf16 v[84:87], v[80:83], v[8:11], 0
	v_mfma_f32_16x16x32_bf16 v[80:83], v[80:83], v[12:15], 0
	v_mfma_f32_16x16x32_bf16 v[84:87], v[52:55], v[4:7], v[84:87]
	v_mfma_f32_16x16x32_bf16 v[52:55], v[52:55], v[16:19], v[80:83]
	v_mfma_f32_16x16x32_bf16 v[80:83], v[60:63], v[8:11], 0
	v_mfma_f32_16x16x32_bf16 v[60:63], v[60:63], v[12:15], 0
	v_mfma_f32_16x16x32_bf16 v[98:101], v[56:59], v[4:7], v[80:83]
	v_mfma_f32_16x16x32_bf16 v[56:59], v[56:59], v[16:19], v[60:63]
	s_nop 5
	v_mul_f32_e32 v61, 0x3e38aa3b, v84
	v_mul_f32_e32 v60, 0x3e38aa3b, v85
	v_max3_f32 v0, v74, v61, v60
	v_mul_f32_e32 v63, 0x3e38aa3b, v86
	v_mul_f32_e32 v62, 0x3e38aa3b, v87
	v_max3_f32 v0, v0, v63, v62
	v_mul_f32_e32 v82, 0x3e38aa3b, v98
	v_mul_f32_e32 v84, 0x3e38aa3b, v99
	v_max3_f32 v0, v0, v82, v84
	v_mul_f32_e32 v86, 0x3e38aa3b, v100
	v_mul_f32_e32 v88, 0x3e38aa3b, v101
	v_max3_f32 v0, v0, v86, v88
	v_mov_b32_e32 v64, v0
	s_waitcnt lgkmcnt(0)
	s_nop 1
	v_permlane16_swap_b32_e32 v0, v64
	v_max_f32_e32 v0, v0, v64
	v_mov_b32_e32 v64, v0
	s_waitcnt lgkmcnt(0)
	v_mov_b32_e32 v85, v0
	s_nop 1
	v_permlane32_swap_b32_e32 v85, v64
	v_max_f32_e32 v85, v85, v64
	v_sub_f32_e32 v0, v74, v85
	v_exp_f32_e32 v64, v0
	s_nop 0
	v_cmp_neq_f32_e32 vcc, 1.0, v64
	s_cbranch_vccz .LBB0_527
	v_pk_mul_f32 v[46:47], v[46:47], v[64:65] op_sel_hi:[1,0]
	v_pk_mul_f32 v[44:45], v[44:45], v[64:65] op_sel_hi:[1,0]
	v_pk_mul_f32 v[26:27], v[26:27], v[64:65] op_sel_hi:[1,0]
	v_pk_mul_f32 v[24:25], v[24:25], v[64:65] op_sel_hi:[1,0]
	v_pk_mul_f32 v[38:39], v[38:39], v[64:65] op_sel_hi:[1,0]
	v_pk_mul_f32 v[36:37], v[36:37], v[64:65] op_sel_hi:[1,0]
	v_pk_mul_f32 v[42:43], v[42:43], v[64:65] op_sel_hi:[1,0]
	v_pk_mul_f32 v[40:41], v[40:41], v[64:65] op_sel_hi:[1,0]
; __device__ __forceinline__ float fexp2(float x) { return __builtin_amdgcn_exp2f(x); }
; template <int DKA, int DKB, int DV, bool BAND, bool SINK> ...
;     ...
;           for (int ks = 0; ks < KS; ++ks) a = mfma16(kf[ks], qf[qb][ks], a);
;           s[qb][kb2] = a;
;         }
;       }
; #pragma unroll
;       for (int qb = 0; qb < 2; ++qb) {
;         float mx = mrun[qb];
;         const int qp = qpos0 + wave * 32 + qb * 16 + fr;
; #pragma unroll
;         for (int kb2 = 0; kb2 < 2; ++kb2)
; #pragma unroll
;           for (int j = 0; j < 4; ++j) {
;             float v = s[qb][kb2][j] * scale2;
;             if (BAND && k0 < 2048) {
;               int d = qp - (k0 + (kk * 2 + kb2) * 16 + fq * 4 + j);
;               if (d > 128 || d < -128) v = -1e30f;
;             }
;             s[qb][kb2][j] = v;
;             mx = fmaxf(mx, v);
;           }
;         mx = fmaxf(mx, __shfl_xor(mx, 16));
;         mx = fmaxf(mx, __shfl_xor(mx, 32));
;         const float alpha = fexp2(mrun[qb] - mx);
;         mrun[qb] = mx;
;         float ls = 0.f;
; #pragma unroll
;         for (int kb2 = 0; kb2 < 2; ++kb2)
; #pragma unroll
;           for (int j = 0; j < 4; ++j) {
;             float pv = fexp2(s[qb][kb2][j] - mx);
;             s[qb][kb2][j] = pv;
;             ls += pv;
;           }
;         lrun[qb] = lrun[qb] * alpha + ls;
;         if (__any(alpha != 1.f)) {
; #pragma unroll
;           for (int eb = 0; eb < EB; ++eb) {
;             o[qb][eb][0] *= alpha; o[qb][eb][1] *= alpha; o[qb][eb][2] *= alpha; o[qb][eb][3] *= alpha;
;           }
;         }
;       }
;       bf16x8 pf[2];
; #pragma unroll
;       for (int qb = 0; qb < 2; ++qb)
;         pf[qb] = mk8(pack2(s[qb][0][0], s[qb][0][1]), pack2(s[qb][0][2], s[qb][0][3]),
;                      pack2(s[qb][1][0], s[qb][1][1]), pack2(s[qb][1][2], s[qb][1][3]));
; #pragma unroll
;       for (int eb = 0; eb < EB; ++eb) {
;         const char* vrow = vbuf + (eb * 16 + fr) * 128 + (fq & 1) * 8;
;         uint2 v0 = *(const uint2*)(vrow + (((kk * 4 + (fq >> 1)) ^ swz8) * 16));
;         uint2 v1 = *(const uint2*)(vrow + (((kk * 4 + 2 + (fq >> 1)) ^ swz8) * 16));
;         bf16x8 vf = mk8(v0.x, v0.y, v1.x, v1.y);
; #pragma unroll
;         for (int qb = 0; qb < 2; ++qb) o[qb][eb] = mfma16(vf, pf[qb], o[qb][eb]);
;       }
.LBB0_527:
	v_mul_f32_e32 v70, 0x3e38aa3b, v52
	v_mul_f32_e32 v66, 0x3e38aa3b, v53
	v_max3_f32 v0, v3, v70, v66
	v_mul_f32_e32 v68, 0x3e38aa3b, v54
	v_mul_f32_e32 v55, 0x3e38aa3b, v55
	v_max3_f32 v0, v0, v68, v55
	v_mul_f32_e32 v56, 0x3e38aa3b, v56
	v_mul_f32_e32 v53, 0x3e38aa3b, v57
	v_max3_f32 v0, v0, v56, v53
	v_mul_f32_e32 v54, 0x3e38aa3b, v58
	v_mul_f32_e32 v52, 0x3e38aa3b, v59
	v_max3_f32 v0, v0, v54, v52
	v_mov_b32_e32 v57, v0
	s_waitcnt lgkmcnt(0)
	s_nop 1
	v_permlane16_swap_b32_e32 v0, v57
	v_max_f32_e32 v0, v0, v57
	v_mov_b32_e32 v57, v0
	s_waitcnt lgkmcnt(0)
	v_mov_b32_e32 v87, v0
	s_nop 1
	v_permlane32_swap_b32_e32 v87, v57
	v_max_f32_e32 v87, v87, v57
	v_sub_f32_e32 v0, v3, v87
	v_exp_f32_e32 v0, v0
	s_nop 0
	v_cmp_neq_f32_e32 vcc, 1.0, v0
	s_cbranch_vccz .LBB0_529
	v_pk_mul_f32 v[34:35], v[34:35], v[0:1] op_sel_hi:[1,0]
	v_pk_mul_f32 v[32:33], v[32:33], v[0:1] op_sel_hi:[1,0]
	v_pk_mul_f32 v[22:23], v[22:23], v[0:1] op_sel_hi:[1,0]
	v_pk_mul_f32 v[20:21], v[20:21], v[0:1] op_sel_hi:[1,0]
	v_pk_mul_f32 v[30:31], v[30:31], v[0:1] op_sel_hi:[1,0]
	v_pk_mul_f32 v[28:29], v[28:29], v[0:1] op_sel_hi:[1,0]
	v_pk_mul_f32 v[50:51], v[50:51], v[0:1] op_sel_hi:[1,0]
	v_pk_mul_f32 v[48:49], v[48:49], v[0:1] op_sel_hi:[1,0]
.LBB0_529:
	v_sub_f32_e32 v3, v70, v87
	v_exp_f32_e32 v75, v3
	v_sub_f32_e32 v3, v66, v87
	v_exp_f32_e32 v77, v3
	v_sub_f32_e32 v3, v68, v87
	v_exp_f32_e32 v66, v3
	v_sub_f32_e32 v3, v55, v87
	v_exp_f32_e32 v68, v3
	v_sub_f32_e32 v3, v56, v87
	v_exp_f32_e32 v70, v3
	v_sub_f32_e32 v3, v53, v87
	v_exp_f32_e32 v72, v3
	v_sub_f32_e32 v3, v54, v87
	v_exp_f32_e32 v74, v3
	v_sub_f32_e32 v3, v52, v87
	v_exp_f32_e32 v76, v3
	v_sub_f32_e32 v3, v61, v85
	v_exp_f32_e32 v81, v3
	v_sub_f32_e32 v3, v60, v85
	v_exp_f32_e32 v83, v3
	v_sub_f32_e32 v3, v63, v85
	v_exp_f32_e32 v78, v3
	v_sub_f32_e32 v3, v62, v85
	v_exp_f32_e32 v80, v3
	v_sub_f32_e32 v3, v82, v85
	v_exp_f32_e32 v82, v3
	v_sub_f32_e32 v3, v84, v85
	v_exp_f32_e32 v84, v3
	v_sub_f32_e32 v3, v86, v85
	v_exp_f32_e32 v86, v3
	v_sub_f32_e32 v3, v88, v85
	v_exp_f32_e32 v88, v3
	v_add_u32_e32 v3, v94, v71
	v_add_u32_e32 v69, v94, v69
	ds_read2st64_b64 v[54:57], v3 offset0:48 offset1:52
	ds_read2st64_b64 v[60:63], v69 offset0:48 offset1:52
	v_cvt_pk_bf16_f32 v98, v81, v83
	v_cvt_pk_bf16_f32 v99, v78, v80
	v_cvt_pk_bf16_f32 v100, v82, v84
	s_waitcnt lgkmcnt(0)
	v_mov_b32_e32 v52, v54
	v_mov_b32_e32 v53, v55
	v_mov_b32_e32 v54, v60
	v_mov_b32_e32 v55, v61
	v_cvt_pk_bf16_f32 v101, v86, v88
	v_cvt_pk_bf16_f32 v102, v75, v77
	v_cvt_pk_bf16_f32 v103, v66, v68
	v_cvt_pk_bf16_f32 v104, v70, v72
	v_cvt_pk_bf16_f32 v105, v74, v76
	v_mfma_f32_16x16x32_bf16 v[44:47], v[52:55], v[98:101], v[44:47]
	v_mov_b32_e32 v60, v56
	v_mov_b32_e32 v61, v57
	v_mfma_f32_16x16x32_bf16 v[52:55], v[52:55], v[102:105], v[32:35]
	s_nop 2
	ds_read2st64_b64 v[32:35], v3 offset0:56 offset1:60
	ds_read2st64_b64 v[106:109], v69 offset0:56 offset1:60
	v_mfma_f32_16x16x32_bf16 v[56:59], v[60:63], v[98:101], v[24:27]
	s_waitcnt lgkmcnt(0)
	s_nop 1
	v_mov_b32_e32 v24, v32
	v_mov_b32_e32 v25, v33
	v_mov_b32_e32 v26, v106
	v_mov_b32_e32 v27, v107
	v_mov_b32_e32 v106, v34
	v_mov_b32_e32 v107, v35
	v_mfma_f32_16x16x32_bf16 v[60:63], v[60:63], v[102:105], v[20:23]
	v_mfma_f32_16x16x32_bf16 v[20:23], v[24:27], v[98:101], v[36:39]
	v_mfma_f32_16x16x32_bf16 v[24:27], v[24:27], v[102:105], v[28:31]
	v_mfma_f32_16x16x32_bf16 v[28:31], v[106:109], v[98:101], v[40:43]
	s_nop 0
	ds_read_b128 v[36:39], v73 offset:12288
	s_nop 0
	ds_read_b128 v[40:43], v2 offset:12288
	v_mfma_f32_16x16x32_bf16 v[32:35], v[106:109], v[102:105], v[48:51]
	s_waitcnt lgkmcnt(0)
	v_mfma_f32_16x16x32_bf16 v[48:51], v[36:39], v[8:11], 0
	v_mfma_f32_16x16x32_bf16 v[36:39], v[36:39], v[12:15], 0
	v_mfma_f32_16x16x32_bf16 v[48:51], v[40:43], v[4:7], v[48:51]
	v_mfma_f32_16x16x32_bf16 v[36:39], v[40:43], v[16:19], v[36:39]
	ds_read_b128 v[40:43], v73 offset:14336
	ds_read_b128 v[98:101], v2 offset:14336
	s_waitcnt lgkmcnt(0)
	v_mfma_f32_16x16x32_bf16 v[8:11], v[40:43], v[8:11], 0
	v_mfma_f32_16x16x32_bf16 v[102:105], v[98:101], v[4:7], v[8:11]
	v_mfma_f32_16x16x32_bf16 v[2:5], v[40:43], v[12:15], 0
	s_nop 0
	v_mul_f32_e32 v14, 0x3e38aa3b, v48
	v_mul_f32_e32 v12, 0x3e38aa3b, v49
	v_max3_f32 v6, v85, v14, v12
	v_mul_f32_e32 v13, 0x3e38aa3b, v50
	s_nop 0
	v_mul_f32_e32 v10, 0x3e38aa3b, v51
	v_max3_f32 v6, v6, v13, v10
	v_mul_f32_e32 v11, 0x3e38aa3b, v102
	v_mul_f32_e32 v8, 0x3e38aa3b, v103
	v_max3_f32 v6, v6, v11, v8
	v_mul_f32_e32 v9, 0x3e38aa3b, v104
	v_mul_f32_e32 v7, 0x3e38aa3b, v105
	v_max3_f32 v6, v6, v9, v7
	v_mov_b32_e32 v15, v6
	v_mfma_f32_16x16x32_bf16 v[2:5], v[98:101], v[16:19], v[2:5]
	s_waitcnt lgkmcnt(0)
	s_nop 1
	v_permlane16_swap_b32_e32 v6, v15
	v_max_f32_e32 v6, v6, v15
	v_mov_b32_e32 v15, v6
	s_waitcnt lgkmcnt(0)
	s_nop 1
	v_permlane32_swap_b32_e32 v6, v15
	v_max_f32_e32 v15, v6, v15
	v_sub_f32_e32 v6, v85, v15
	v_exp_f32_e32 v6, v6
	s_nop 0
	v_cmp_neq_f32_e32 vcc, 1.0, v6
	s_cbranch_vccz .LBB0_531
	v_pk_mul_f32 v[46:47], v[46:47], v[6:7] op_sel_hi:[1,0]
	v_pk_mul_f32 v[44:45], v[44:45], v[6:7] op_sel_hi:[1,0]
	v_pk_mul_f32 v[58:59], v[58:59], v[6:7] op_sel_hi:[1,0]
	v_pk_mul_f32 v[56:57], v[56:57], v[6:7] op_sel_hi:[1,0]
	v_pk_mul_f32 v[22:23], v[22:23], v[6:7] op_sel_hi:[1,0]
	v_pk_mul_f32 v[20:21], v[20:21], v[6:7] op_sel_hi:[1,0]
	v_pk_mul_f32 v[30:31], v[30:31], v[6:7] op_sel_hi:[1,0]
	v_pk_mul_f32 v[28:29], v[28:29], v[6:7] op_sel_hi:[1,0]
.LBB0_531:
	v_mul_f32_e32 v40, 0x3e38aa3b, v36
	v_mul_f32_e32 v19, 0x3e38aa3b, v37
	v_max3_f32 v16, v87, v40, v19
	v_mul_f32_e32 v36, 0x3e38aa3b, v38
	v_mul_f32_e32 v17, 0x3e38aa3b, v39
	v_max3_f32 v37, v16, v36, v17
	v_mul_f32_e32 v18, 0x3e38aa3b, v2
	v_mul_f32_e32 v16, 0x3e38aa3b, v3
	v_max3_f32 v2, v37, v18, v16
	v_mul_f32_e32 v4, 0x3e38aa3b, v4
	v_mul_f32_e32 v3, 0x3e38aa3b, v5
	v_max3_f32 v2, v2, v4, v3
	v_mov_b32_e32 v5, v2
	s_waitcnt lgkmcnt(0)
	s_nop 1
	v_permlane16_swap_b32_e32 v2, v5
	v_max_f32_e32 v2, v2, v5
	v_mov_b32_e32 v5, v2
	s_waitcnt lgkmcnt(0)
	s_nop 1
	v_permlane32_swap_b32_e32 v2, v5
	v_max_f32_e32 v5, v2, v5
	v_sub_f32_e32 v2, v87, v5
	v_exp_f32_e32 v2, v2
	s_nop 0
	v_cmp_neq_f32_e32 vcc, 1.0, v2
	s_cbranch_vccz .LBB0_514
	v_pk_mul_f32 v[54:55], v[54:55], v[2:3] op_sel_hi:[1,0]
	v_pk_mul_f32 v[52:53], v[52:53], v[2:3] op_sel_hi:[1,0]
	v_pk_mul_f32 v[62:63], v[62:63], v[2:3] op_sel_hi:[1,0]
	v_pk_mul_f32 v[60:61], v[60:61], v[2:3] op_sel_hi:[1,0]
	v_pk_mul_f32 v[26:27], v[26:27], v[2:3] op_sel_hi:[1,0]
	v_pk_mul_f32 v[24:25], v[24:25], v[2:3] op_sel_hi:[1,0]
	v_pk_mul_f32 v[34:35], v[34:35], v[2:3] op_sel_hi:[1,0]
	v_pk_mul_f32 v[32:33], v[32:33], v[2:3] op_sel_hi:[1,0]
	s_branch .LBB0_514

; __device__ __forceinline__ float fexp2(float x) { return __builtin_amdgcn_exp2f(x); }
; template <int DKA, int DKB, int DV, bool BAND, bool SINK> ...
;     ...
;       for (int kb2 = 0; kb2 < 2; ++kb2) {
;         const int kb = kk * 2 + kb2;
;         bf16x8 kf[KS];
; #pragma unroll
;         for (int ks = 0; ks < KS; ++ks) {
;           if (ks < KSA) {
;             if (DKA == 128) kf[ks] = *(const bf16x8*)(kst + (kb * 16 + fr) * 256 + (((ks * 4 + fq) ^ fr) * 16));
;             else kf[ks] = *(const bf16x8*)(kst + (kb * 16 + fr) * 128 + (((ks * 4 + fq) ^ swz8) * 16));
;           } else {
;             kf[ks] = *(const bf16x8*)(kst + KASZ + (kb * 16 + fr) * 128 + ((((ks - KSA) * 4 + fq) ^ swz8) * 16));
;           }
;         }
; #pragma unroll
;         for (int qb = 0; qb < 2; ++qb) {
;           f32x4 a = (f32x4){0.f, 0.f, 0.f, 0.f};
; #pragma unroll
;           for (int ks = 0; ks < KS; ++ks) a = mfma16(kf[ks], qf[qb][ks], a);
;           s[qb][kb2] = a;
;         }
;       }
; #pragma unroll
;       for (int qb = 0; qb < 2; ++qb) {
;         float mx = mrun[qb];
;         const int qp = qpos0 + wave * 32 + qb * 16 + fr;
; #pragma unroll
;         for (int kb2 = 0; kb2 < 2; ++kb2)
; #pragma unroll
;           for (int j = 0; j < 4; ++j) {
;             float v = s[qb][kb2][j] * scale2;
;             if (BAND && k0 < 2048) {
;               int d = qp - (k0 + (kk * 2 + kb2) * 16 + fq * 4 + j);
;               if (d > 128 || d < -128) v = -1e30f;
;             }
;             s[qb][kb2][j] = v;
;             mx = fmaxf(mx, v);
;           }
;         mx = fmaxf(mx, __shfl_xor(mx, 16));
;         mx = fmaxf(mx, __shfl_xor(mx, 32));
;         const float alpha = fexp2(mrun[qb] - mx);
;         mrun[qb] = mx;
;         float ls = 0.f;
; #pragma unroll
;         for (int kb2 = 0; kb2 < 2; ++kb2)
; #pragma unroll
;           for (int j = 0; j < 4; ++j) {
;             float pv = fexp2(s[qb][kb2][j] - mx);
;             s[qb][kb2][j] = pv;
;             ls += pv;
;           }
;         lrun[qb] = lrun[qb] * alpha + ls;
;         if (__any(alpha != 1.f)) {
; #pragma unroll
;           for (int eb = 0; eb < EB; ++eb) {
;             o[qb][eb][0] *= alpha; o[qb][eb][1] *= alpha; o[qb][eb][2] *= alpha; o[qb][eb][3] *= alpha;
;           }
;         }
;       }
.LBB0_559:
	s_add_i32 s8, s1, 4
	s_cmp_lt_i32 s8, s46
	s_cselect_b32 s8, 0, s46
	s_cselect_b32 s9, s65, 0x800
	s_add_i32 s11, s87, 0xffffe000
	s_and_b32 s57, s11, 0x2000
	v_cmp_lt_i32_e32 vcc, v200, v198
	v_or_b32_e32 v54, s57, v71
	v_add_u32_e32 v85, v54, v73
	v_cndmask_b32_e32 v50, v197, v200, vcc
	v_cmp_lt_i32_e32 vcc, v199, v198
	v_lshlrev_b32_e32 v82, 2, v50
	v_add_u32_e32 v68, v54, v74
	v_cndmask_b32_e32 v50, v197, v199, vcc
	v_lshlrev_b32_e32 v83, 2, v50
	ds_read_b128 v[50:53], v85
	ds_read_b128 v[54:57], v68
	s_waitcnt lgkmcnt(0)
	v_mfma_f32_16x16x32_bf16 v[86:89], v[50:53], v[2:5], 0
	s_lshl_b32 s8, s8, 6
	s_sub_i32 s10, s9, s8
	s_add_i32 s10, s34, s10
	v_mfma_f32_16x16x32_bf16 v[50:53], v[50:53], v[10:13], 0
	s_sub_i32 s10, s10, 64
	s_cmpk_lt_i32 s10, 0x800
	s_cselect_b64 s[66:67], -1, 0
	v_mfma_f32_16x16x32_bf16 v[86:89], v[54:57], v[6:9], v[86:89]
	s_sub_i32 s8, s8, s9
	v_mfma_f32_16x16x32_bf16 v[50:53], v[54:57], v[14:17], v[50:53]
	ds_read_b128 v[54:57], v85 offset:2048
	ds_read_b128 v[90:93], v68 offset:2048
	s_nop 3
	v_mul_f32_e32 v64, 0x3e38aa3b, v86
	s_waitcnt lgkmcnt(0)
	v_mfma_f32_16x16x32_bf16 v[94:97], v[54:57], v[2:5], 0
	v_mfma_f32_16x16x32_bf16 v[102:105], v[90:93], v[6:9], v[94:97]
	s_nop 6
	v_add_u32_e32 v94, s8, v79
	v_add_u32_e32 v66, 51, v94
	v_cmp_gt_u32_e32 vcc, s56, v66
	v_add_u32_e32 v66, 50, v94
	s_and_b64 s[16:17], s[66:67], vcc
	v_cmp_gt_u32_e32 vcc, s56, v66
	v_add_u32_e32 v84, 49, v94
	s_and_b64 s[18:19], s[66:67], vcc
	v_cmp_gt_u32_e32 vcc, s56, v84
	v_add_u32_e32 v84, 48, v94
	v_mul_f32_e32 v66, 0x3e38aa3b, v88
	s_and_b64 s[20:21], s[66:67], vcc
	v_cmp_gt_u32_e32 vcc, s56, v84
	v_add_u32_e32 v84, 35, v94
	v_cndmask_b32_e64 v99, v66, v207, s[20:21]
	v_mul_f32_e32 v66, 0x3e38aa3b, v89
	s_and_b64 s[22:23], s[66:67], vcc
	v_cmp_gt_u32_e32 vcc, s56, v84
	v_add_u32_e32 v84, 34, v94
	v_cndmask_b32_e64 v97, v64, v207, s[16:17]
	v_mul_f32_e32 v64, 0x3e38aa3b, v87
	v_cndmask_b32_e64 v100, v66, v207, s[22:23]
	v_mul_f32_e32 v66, 0x3e38aa3b, v102
	s_and_b64 s[8:9], s[66:67], vcc
	v_cmp_gt_u32_e32 vcc, s56, v84
	v_add_u32_e32 v84, 33, v94
	v_cndmask_b32_e64 v98, v64, v207, s[18:19]
	v_cndmask_b32_e64 v101, v66, v207, s[8:9]
	v_mul_f32_e32 v66, 0x3e38aa3b, v103
	s_and_b64 s[10:11], s[66:67], vcc
	v_cmp_gt_u32_e32 vcc, s56, v84
	v_add_u32_e32 v84, 32, v94
	v_max3_f32 v64, v80, v97, v98
	v_cndmask_b32_e64 v102, v66, v207, s[10:11]
	v_mul_f32_e32 v66, 0x3e38aa3b, v104
	s_and_b64 s[12:13], s[66:67], vcc
	v_cmp_gt_u32_e32 vcc, s56, v84
	v_max3_f32 v64, v64, v99, v100
	v_cndmask_b32_e64 v103, v66, v207, s[12:13]
	v_mul_f32_e32 v66, 0x3e38aa3b, v105
	s_and_b64 s[14:15], s[66:67], vcc
	v_max3_f32 v64, v64, v101, v102
	v_cndmask_b32_e64 v104, v66, v207, s[14:15]
	v_max3_f32 v64, v64, v103, v104
	v_mov_b32_e32 v66, v64
	v_mfma_f32_16x16x32_bf16 v[54:57], v[54:57], v[10:13], 0
	s_waitcnt lgkmcnt(0)
	s_nop 1
	v_permlane16_swap_b32_e32 v64, v66
	v_max_f32_e32 v64, v64, v66
	v_mov_b32_e32 v66, v64
	v_mfma_f32_16x16x32_bf16 v[54:57], v[90:93], v[14:17], v[54:57]
	s_waitcnt lgkmcnt(0)
	v_mov_b32_e32 v95, v64
	s_nop 1
	v_permlane32_swap_b32_e32 v95, v66
	v_max_f32_e32 v95, v95, v66
	v_sub_f32_e32 v64, v80, v95
	v_exp_f32_e32 v64, v64
	s_nop 0
	v_cmp_neq_f32_e32 vcc, 1.0, v64
	s_cbranch_vccz .LBB0_561
	v_pk_mul_f32 v[44:45], v[44:45], v[64:65] op_sel_hi:[1,0]
	v_pk_mul_f32 v[42:43], v[42:43], v[64:65] op_sel_hi:[1,0]
	v_pk_mul_f32 v[36:37], v[36:37], v[64:65] op_sel_hi:[1,0]
	v_pk_mul_f32 v[34:35], v[34:35], v[64:65] op_sel_hi:[1,0]
	v_pk_mul_f32 v[40:41], v[40:41], v[64:65] op_sel_hi:[1,0]
	v_pk_mul_f32 v[38:39], v[38:39], v[64:65] op_sel_hi:[1,0]
	v_pk_mul_f32 v[48:49], v[48:49], v[64:65] op_sel_hi:[1,0]
	v_pk_mul_f32 v[46:47], v[46:47], v[64:65] op_sel_hi:[1,0]
.LBB0_561:
	v_add_u32_e32 v66, 0x43, v94
	v_cmp_gt_u32_e32 vcc, s56, v66
	v_mul_f32_e32 v50, 0x3e38aa3b, v50
	s_and_b64 vcc, s[66:67], vcc
	v_add_u32_e32 v66, 0x42, v94
	v_cndmask_b32_e32 v50, v50, v207, vcc
	v_cmp_gt_u32_e32 vcc, s56, v66
	v_mul_f32_e32 v51, 0x3e38aa3b, v51
	s_and_b64 vcc, s[66:67], vcc
	v_add_u32_e32 v80, 0x41, v94
	v_cndmask_b32_e32 v51, v51, v207, vcc
	v_cmp_gt_u32_e32 vcc, s56, v80
	v_mul_f32_e32 v52, 0x3e38aa3b, v52
	s_and_b64 vcc, s[66:67], vcc
	v_add_u32_e32 v80, 64, v94
	v_cndmask_b32_e32 v52, v52, v207, vcc
	v_cmp_gt_u32_e32 vcc, s56, v80
	v_mul_f32_e32 v53, 0x3e38aa3b, v53
	s_and_b64 vcc, s[66:67], vcc
	v_max3_f32 v66, v81, v50, v51
	v_cndmask_b32_e32 v53, v53, v207, vcc
	v_mul_f32_e32 v54, 0x3e38aa3b, v54
	v_mul_f32_e32 v55, 0x3e38aa3b, v55
	v_max3_f32 v66, v66, v52, v53
	v_cndmask_b32_e64 v54, v54, v207, s[16:17]
	v_cndmask_b32_e64 v55, v55, v207, s[18:19]
	v_mul_f32_e32 v56, 0x3e38aa3b, v56
	v_mul_f32_e32 v57, 0x3e38aa3b, v57
	v_max3_f32 v66, v66, v54, v55
	v_cndmask_b32_e64 v56, v56, v207, s[20:21]
	v_cndmask_b32_e64 v57, v57, v207, s[22:23]
	v_max3_f32 v66, v66, v56, v57
	v_mov_b32_e32 v80, v66
	s_waitcnt lgkmcnt(0)
	s_nop 1
	v_permlane16_swap_b32_e32 v66, v80
	v_max_f32_e32 v66, v66, v80
	v_mov_b32_e32 v80, v66
	s_waitcnt lgkmcnt(0)
	v_mov_b32_e32 v96, v66
	s_nop 1
	v_permlane32_swap_b32_e32 v96, v80
	v_max_f32_e32 v96, v96, v80
	v_sub_f32_e32 v66, v81, v96
	v_exp_f32_e32 v66, v66
	s_nop 0
	v_cmp_neq_f32_e32 vcc, 1.0, v66
	s_cbranch_vccz .LBB0_563
	v_pk_mul_f32 v[24:25], v[24:25], v[66:67] op_sel_hi:[1,0]
	v_pk_mul_f32 v[22:23], v[22:23], v[66:67] op_sel_hi:[1,0]
	v_pk_mul_f32 v[20:21], v[20:21], v[66:67] op_sel_hi:[1,0]
	v_pk_mul_f32 v[18:19], v[18:19], v[66:67] op_sel_hi:[1,0]
	v_pk_mul_f32 v[28:29], v[28:29], v[66:67] op_sel_hi:[1,0]
	v_pk_mul_f32 v[26:27], v[26:27], v[66:67] op_sel_hi:[1,0]
	v_pk_mul_f32 v[32:33], v[32:33], v[66:67] op_sel_hi:[1,0]
	v_pk_mul_f32 v[30:31], v[30:31], v[66:67] op_sel_hi:[1,0]
; __device__ __forceinline__ float fexp2(float x) { return __builtin_amdgcn_exp2f(x); }
; template <int DKA, int DKB, int DV, bool BAND, bool SINK> ...
;     ...
;           for (int ks = 0; ks < KS; ++ks) a = mfma16(kf[ks], qf[qb][ks], a);
;           s[qb][kb2] = a;
;         }
;       }
; #pragma unroll
;       for (int qb = 0; qb < 2; ++qb) {
;         float mx = mrun[qb];
;         const int qp = qpos0 + wave * 32 + qb * 16 + fr;
; #pragma unroll
;         for (int kb2 = 0; kb2 < 2; ++kb2)
; #pragma unroll
;           for (int j = 0; j < 4; ++j) {
;             float v = s[qb][kb2][j] * scale2;
;             if (BAND && k0 < 2048) {
;               int d = qp - (k0 + (kk * 2 + kb2) * 16 + fq * 4 + j);
;               if (d > 128 || d < -128) v = -1e30f;
;             }
;             s[qb][kb2][j] = v;
;             mx = fmaxf(mx, v);
;           }
;         mx = fmaxf(mx, __shfl_xor(mx, 16));
;         mx = fmaxf(mx, __shfl_xor(mx, 32));
;         const float alpha = fexp2(mrun[qb] - mx);
;         mrun[qb] = mx;
;         float ls = 0.f;
; #pragma unroll
;         for (int kb2 = 0; kb2 < 2; ++kb2)
; #pragma unroll
;           for (int j = 0; j < 4; ++j) {
;             float pv = fexp2(s[qb][kb2][j] - mx);
;             s[qb][kb2][j] = pv;
;             ls += pv;
;           }
;         lrun[qb] = lrun[qb] * alpha + ls;
;         if (__any(alpha != 1.f)) {
; #pragma unroll
;           for (int eb = 0; eb < EB; ++eb) {
;             o[qb][eb][0] *= alpha; o[qb][eb][1] *= alpha; o[qb][eb][2] *= alpha; o[qb][eb][3] *= alpha;
;           }
;         }
;       }
;       bf16x8 pf[2];
; #pragma unroll
;       for (int qb = 0; qb < 2; ++qb)
;         pf[qb] = mk8(pack2(s[qb][0][0], s[qb][0][1]), pack2(s[qb][0][2], s[qb][0][3]),
;                      pack2(s[qb][1][0], s[qb][1][1]), pack2(s[qb][1][2], s[qb][1][3]));
; #pragma unroll
;       for (int eb = 0; eb < EB; ++eb) {
;         const char* vrow = vbuf + (eb * 16 + fr) * 128 + (fq & 1) * 8;
;         uint2 v0 = *(const uint2*)(vrow + (((kk * 4 + (fq >> 1)) ^ swz8) * 16));
;         uint2 v1 = *(const uint2*)(vrow + (((kk * 4 + 2 + (fq >> 1)) ^ swz8) * 16));
;         bf16x8 vf = mk8(v0.x, v0.y, v1.x, v1.y);
; #pragma unroll
;         for (int qb = 0; qb < 2; ++qb) o[qb][eb] = mfma16(vf, pf[qb], o[qb][eb]);
;       }
.LBB0_563:
	v_sub_f32_e32 v50, v50, v96
	v_exp_f32_e32 v86, v50
	v_sub_f32_e32 v50, v51, v96
	v_exp_f32_e32 v87, v50
	v_sub_f32_e32 v50, v52, v96
	v_exp_f32_e32 v88, v50
	v_sub_f32_e32 v50, v53, v96
	v_exp_f32_e32 v89, v50
	v_sub_f32_e32 v50, v54, v96
	v_exp_f32_e32 v90, v50
	v_sub_f32_e32 v50, v55, v96
	v_exp_f32_e32 v91, v50
	v_sub_f32_e32 v50, v56, v96
	v_exp_f32_e32 v92, v50
	v_sub_f32_e32 v50, v57, v96
	v_exp_f32_e32 v93, v50
	v_sub_f32_e32 v50, v97, v95
	v_add_u32_e32 v84, s57, v72
	v_exp_f32_e32 v97, v50
	v_sub_f32_e32 v50, v98, v95
	v_exp_f32_e32 v98, v50
	v_sub_f32_e32 v50, v99, v95
	v_add_u32_e32 v80, v84, v75
	v_add_u32_e32 v81, v84, v76
	v_exp_f32_e32 v99, v50
	v_sub_f32_e32 v50, v100, v95
	ds_read2st64_b64 v[106:109], v80 offset0:32 offset1:36
	ds_read2st64_b64 v[110:113], v81 offset0:32 offset1:36
	v_exp_f32_e32 v100, v50
	v_sub_f32_e32 v50, v101, v95
	v_exp_f32_e32 v101, v50
	v_sub_f32_e32 v50, v102, v95
	v_exp_f32_e32 v102, v50
	v_sub_f32_e32 v50, v103, v95
	v_exp_f32_e32 v103, v50
	v_sub_f32_e32 v50, v104, v95
	v_exp_f32_e32 v104, v50
	s_waitcnt lgkmcnt(0)
	v_mov_b32_e32 v116, v110
	v_mov_b32_e32 v117, v111
	v_mov_b32_e32 v110, v108
	v_mov_b32_e32 v111, v109
	v_cvt_pk_bf16_f32 v50, v97, v98
	v_cvt_pk_bf16_f32 v51, v99, v100
	v_cvt_pk_bf16_f32 v52, v101, v102
	v_cvt_pk_bf16_f32 v53, v103, v104
	v_cvt_pk_bf16_f32 v54, v86, v87
	v_cvt_pk_bf16_f32 v55, v88, v89
	v_cvt_pk_bf16_f32 v56, v90, v91
	v_cvt_pk_bf16_f32 v57, v92, v93
	v_mov_b32_e32 v114, v106
	v_mov_b32_e32 v115, v107
	v_mfma_f32_16x16x32_bf16 v[34:37], v[110:113], v[50:53], v[34:37]
	v_mfma_f32_16x16x32_bf16 v[18:21], v[110:113], v[54:57], v[18:21]
	ds_read2st64_b64 v[106:109], v80 offset0:40 offset1:44
	ds_read2st64_b64 v[110:113], v81 offset0:40 offset1:44
	v_add_u32_e32 v80, 19, v94
	v_cmp_gt_u32_e32 vcc, s56, v80
	v_mfma_f32_16x16x32_bf16 v[42:45], v[114:117], v[50:53], v[42:45]
	v_add_u32_e32 v80, 18, v94
	s_and_b64 s[16:17], s[66:67], vcc
	v_cmp_gt_u32_e32 vcc, s56, v80
	v_mfma_f32_16x16x32_bf16 v[22:25], v[114:117], v[54:57], v[22:25]
	s_waitcnt lgkmcnt(0)
	v_mov_b32_e32 v114, v106
	v_mov_b32_e32 v115, v107
	v_mov_b32_e32 v116, v110
	v_mov_b32_e32 v117, v111
	v_mov_b32_e32 v110, v108
	v_mov_b32_e32 v111, v109
	v_mfma_f32_16x16x32_bf16 v[38:41], v[114:117], v[50:53], v[38:41]
	v_add_u32_e32 v81, 17, v94
	s_and_b64 s[18:19], s[66:67], vcc
	v_cmp_gt_u32_e32 vcc, s56, v81
	v_mfma_f32_16x16x32_bf16 v[26:29], v[114:117], v[54:57], v[26:29]
	v_add_u32_e32 v81, 16, v94
	s_and_b64 s[20:21], s[66:67], vcc
	v_cmp_gt_u32_e32 vcc, s56, v81
	v_mfma_f32_16x16x32_bf16 v[46:49], v[110:113], v[50:53], v[46:49]
	v_add_u32_e32 v81, 3, v94
	s_and_b64 s[22:23], s[66:67], vcc
	v_cmp_gt_u32_e32 vcc, s56, v81
	v_mfma_f32_16x16x32_bf16 v[30:33], v[110:113], v[54:57], v[30:33]
	ds_read_b128 v[50:53], v85 offset:4096
	ds_read_b128 v[54:57], v68 offset:4096
	s_and_b64 vcc, s[66:67], vcc
	v_add_u32_e32 v81, 2, v94
	s_waitcnt lgkmcnt(0)
	v_mfma_f32_16x16x32_bf16 v[106:109], v[50:53], v[2:5], 0
	v_mfma_f32_16x16x32_bf16 v[50:53], v[50:53], v[10:13], 0
	v_mfma_f32_16x16x32_bf16 v[112:115], v[54:57], v[6:9], v[106:109]
	v_mfma_f32_16x16x32_bf16 v[50:53], v[54:57], v[14:17], v[50:53]
	ds_read_b128 v[54:57], v85 offset:6144
	s_nop 3
	ds_read_b128 v[106:109], v68 offset:6144
	s_nop 0
	v_mul_f32_e32 v80, 0x3e38aa3b, v114
	v_mul_f32_e32 v68, 0x3e38aa3b, v112
	s_waitcnt lgkmcnt(0)
	v_mfma_f32_16x16x32_bf16 v[116:119], v[54:57], v[2:5], 0
	v_cndmask_b32_e64 v111, v68, v207, s[16:17]
	v_mul_f32_e32 v68, 0x3e38aa3b, v113
	v_cndmask_b32_e64 v110, v68, v207, s[18:19]
	v_mfma_f32_16x16x32_bf16 v[54:57], v[54:57], v[10:13], 0
	v_max3_f32 v68, v95, v111, v110
	v_mfma_f32_16x16x32_bf16 v[116:119], v[106:109], v[6:9], v[116:119]
	v_mfma_f32_16x16x32_bf16 v[54:57], v[106:109], v[14:17], v[54:57]
	v_cndmask_b32_e64 v109, v80, v207, s[20:21]
	v_mul_f32_e32 v80, 0x3e38aa3b, v115
	v_cndmask_b32_e64 v108, v80, v207, s[22:23]
	s_nop 3
	v_mul_f32_e32 v80, 0x3e38aa3b, v116
	v_cndmask_b32_e32 v107, v80, v207, vcc
	v_cmp_gt_u32_e32 vcc, s56, v81
	v_mul_f32_e32 v80, 0x3e38aa3b, v117
	s_and_b64 vcc, s[66:67], vcc
	v_add_u32_e32 v81, 1, v94
	v_cndmask_b32_e32 v106, v80, v207, vcc
	v_cmp_gt_u32_e32 vcc, s56, v81
	v_mul_f32_e32 v80, 0x3e38aa3b, v118
	s_and_b64 vcc, s[66:67], vcc
	v_cndmask_b32_e32 v105, v80, v207, vcc
	v_cmp_gt_u32_e32 vcc, s56, v94
	v_max3_f32 v68, v68, v109, v108
	v_mul_f32_e32 v80, 0x3e38aa3b, v119
	s_and_b64 vcc, s[66:67], vcc
	v_max3_f32 v68, v68, v107, v106
	v_cndmask_b32_e32 v85, v80, v207, vcc
	v_max3_f32 v68, v68, v105, v85
	v_mov_b32_e32 v80, v68
	s_waitcnt lgkmcnt(0)
	s_nop 1
	v_permlane16_swap_b32_e32 v68, v80
	v_max_f32_e32 v68, v68, v80
	v_mov_b32_e32 v80, v68
	s_waitcnt lgkmcnt(0)
	s_nop 1
	v_permlane32_swap_b32_e32 v68, v80
	v_max_f32_e32 v80, v68, v80
	v_sub_f32_e32 v68, v95, v80
	v_exp_f32_e32 v68, v68
	s_nop 0
	v_cmp_neq_f32_e32 vcc, 1.0, v68
	s_cbranch_vccz .LBB0_565
	v_pk_mul_f32 v[44:45], v[44:45], v[68:69] op_sel_hi:[1,0]
	v_pk_mul_f32 v[42:43], v[42:43], v[68:69] op_sel_hi:[1,0]
	v_pk_mul_f32 v[36:37], v[36:37], v[68:69] op_sel_hi:[1,0]
	v_pk_mul_f32 v[34:35], v[34:35], v[68:69] op_sel_hi:[1,0]
	v_pk_mul_f32 v[40:41], v[40:41], v[68:69] op_sel_hi:[1,0]
	v_pk_mul_f32 v[38:39], v[38:39], v[68:69] op_sel_hi:[1,0]
	v_pk_mul_f32 v[48:49], v[48:49], v[68:69] op_sel_hi:[1,0]
	v_pk_mul_f32 v[46:47], v[46:47], v[68:69] op_sel_hi:[1,0]
.LBB0_565:
	v_mul_f32_e32 v50, 0x3e38aa3b, v50
	v_cndmask_b32_e64 v113, v50, v207, s[8:9]
	v_mul_f32_e32 v50, 0x3e38aa3b, v51
	v_mul_f32_e32 v51, 0x3e38aa3b, v52
	v_cndmask_b32_e64 v95, v51, v207, s[12:13]
	v_mul_f32_e32 v51, 0x3e38aa3b, v53
	v_cndmask_b32_e64 v94, v51, v207, s[14:15]
	v_mul_f32_e32 v51, 0x3e38aa3b, v54
	v_cndmask_b32_e64 v112, v50, v207, s[10:11]
	v_cndmask_b32_e64 v54, v51, v207, s[16:17]
	v_mul_f32_e32 v51, 0x3e38aa3b, v55
	v_max3_f32 v50, v96, v113, v112
	v_cndmask_b32_e64 v53, v51, v207, s[18:19]
	v_mul_f32_e32 v51, 0x3e38aa3b, v56
	v_max3_f32 v50, v50, v95, v94
	v_cndmask_b32_e64 v52, v51, v207, s[20:21]
	v_mul_f32_e32 v51, 0x3e38aa3b, v57
	v_max3_f32 v50, v50, v54, v53
	v_cndmask_b32_e64 v51, v51, v207, s[22:23]
	v_max3_f32 v50, v50, v52, v51
	v_mov_b32_e32 v55, v50
	s_waitcnt lgkmcnt(0)
	s_nop 1
	v_permlane16_swap_b32_e32 v50, v55
	v_max_f32_e32 v50, v50, v55
	v_mov_b32_e32 v55, v50
	s_waitcnt lgkmcnt(0)
	v_mov_b32_e32 v81, v50
	s_nop 1
	v_permlane32_swap_b32_e32 v81, v55
	v_max_f32_e32 v81, v81, v55
	v_sub_f32_e32 v50, v96, v81
	v_exp_f32_e32 v50, v50
	s_nop 0
	v_cmp_neq_f32_e32 vcc, 1.0, v50
	s_cbranch_vccz .LBB0_556
	v_pk_mul_f32 v[24:25], v[24:25], v[50:51] op_sel_hi:[1,0]
	v_pk_mul_f32 v[22:23], v[22:23], v[50:51] op_sel_hi:[1,0]
	v_pk_mul_f32 v[20:21], v[20:21], v[50:51] op_sel_hi:[1,0]
	v_pk_mul_f32 v[18:19], v[18:19], v[50:51] op_sel_hi:[1,0]
	v_pk_mul_f32 v[28:29], v[28:29], v[50:51] op_sel_hi:[1,0]
	v_pk_mul_f32 v[26:27], v[26:27], v[50:51] op_sel_hi:[1,0]
	v_pk_mul_f32 v[32:33], v[32:33], v[50:51] op_sel_hi:[1,0]
	v_pk_mul_f32 v[30:31], v[30:31], v[50:51] op_sel_hi:[1,0]
	s_branch .LBB0_556

; __device__ __forceinline__ float fexp2(float x) { return __builtin_amdgcn_exp2f(x); }
; template <int DKA, int DKB, int DV, bool BAND, bool SINK> ...
;     ...
;       for (int kb2 = 0; kb2 < 2; ++kb2) {
;         const int kb = kk * 2 + kb2;
;         bf16x8 kf[KS];
; #pragma unroll
;         for (int ks = 0; ks < KS; ++ks) {
;           if (ks < KSA) {
;             if (DKA == 128) kf[ks] = *(const bf16x8*)(kst + (kb * 16 + fr) * 256 + (((ks * 4 + fq) ^ fr) * 16));
;             else kf[ks] = *(const bf16x8*)(kst + (kb * 16 + fr) * 128 + (((ks * 4 + fq) ^ swz8) * 16));
;           } else {
;             kf[ks] = *(const bf16x8*)(kst + KASZ + (kb * 16 + fr) * 128 + ((((ks - KSA) * 4 + fq) ^ swz8) * 16));
;           }
;         }
; #pragma unroll
;         for (int qb = 0; qb < 2; ++qb) {
;           f32x4 a = (f32x4){0.f, 0.f, 0.f, 0.f};
; #pragma unroll
;           for (int ks = 0; ks < KS; ++ks) a = mfma16(kf[ks], qf[qb][ks], a);
;           s[qb][kb2] = a;
;         }
;       }
; #pragma unroll
;       for (int qb = 0; qb < 2; ++qb) {
;         float mx = mrun[qb];
;         const int qp = qpos0 + wave * 32 + qb * 16 + fr;
; #pragma unroll
;         for (int kb2 = 0; kb2 < 2; ++kb2)
; #pragma unroll
;           for (int j = 0; j < 4; ++j) {
;             float v = s[qb][kb2][j] * scale2;
;             if (BAND && k0 < 2048) {
;               int d = qp - (k0 + (kk * 2 + kb2) * 16 + fq * 4 + j);
;               if (d > 128 || d < -128) v = -1e30f;
;             }
;             s[qb][kb2][j] = v;
;             mx = fmaxf(mx, v);
;           }
;         mx = fmaxf(mx, __shfl_xor(mx, 16));
;         mx = fmaxf(mx, __shfl_xor(mx, 32));
;         const float alpha = fexp2(mrun[qb] - mx);
;         mrun[qb] = mx;
;         float ls = 0.f;
; #pragma unroll
;         for (int kb2 = 0; kb2 < 2; ++kb2)
; #pragma unroll
;           for (int j = 0; j < 4; ++j) {
;             float pv = fexp2(s[qb][kb2][j] - mx);
;             s[qb][kb2][j] = pv;
;             ls += pv;
;           }
;         lrun[qb] = lrun[qb] * alpha + ls;
;         if (__any(alpha != 1.f)) {
; #pragma unroll
;           for (int eb = 0; eb < EB; ++eb) {
;             o[qb][eb][0] *= alpha; o[qb][eb][1] *= alpha; o[qb][eb][2] *= alpha; o[qb][eb][3] *= alpha;
;           }
;         }
;       }
.LBB0_1542:
	s_and_b32 s0, s45, 1
	s_mul_i32 s1, s0, 0x6000
	v_cmp_lt_i32_e32 vcc, v200, v198
	v_or_b32_e32 v119, s1, v156
	v_add_u32_e32 v174, v119, v158
	v_cndmask_b32_e32 v114, v197, v200, vcc
	v_cmp_lt_i32_e32 vcc, v199, v198
	v_lshlrev_b32_e32 v141, 2, v114
	v_add_u32_e32 v173, v119, v159
	v_cndmask_b32_e32 v114, v197, v199, vcc
	v_lshlrev_b32_e32 v139, 2, v114
	ds_read_b128 v[114:117], v174
	ds_read_b128 v[122:125], v173
	v_add_u32_e32 v172, v119, v160
	v_or_b32_e32 v118, s1, v155
	ds_read_b128 v[176:179], v172
	v_add_u32_e32 v171, v119, v161
	v_add_u32_e32 v145, v118, v162
	v_add_u32_e32 v143, v118, v163
	s_waitcnt lgkmcnt(0)
	v_mfma_f32_16x16x32_bf16 v[118:121], v[114:117], v[2:5], 0
	ds_read_b128 v[180:183], v171
	ds_read_b128 v[184:187], v145 offset:16384
	ds_read_b128 v[188:191], v143 offset:16384
	v_mfma_f32_16x16x32_bf16 v[114:117], v[114:117], v[26:29], 0
	v_mfma_f32_16x16x32_bf16 v[118:121], v[122:125], v[6:9], v[118:121]
	v_mfma_f32_16x16x32_bf16 v[114:117], v[122:125], v[30:33], v[114:117]
	v_mfma_f32_16x16x32_bf16 v[118:121], v[176:179], v[10:13], v[118:121]
	v_mfma_f32_16x16x32_bf16 v[114:117], v[176:179], v[34:37], v[114:117]
	s_waitcnt lgkmcnt(0)
	v_mfma_f32_16x16x32_bf16 v[118:121], v[180:183], v[14:17], v[118:121]
	v_mfma_f32_16x16x32_bf16 v[114:117], v[180:183], v[38:41], v[114:117]
	v_mfma_f32_16x16x32_bf16 v[118:121], v[184:187], v[18:21], v[118:121]
	v_mfma_f32_16x16x32_bf16 v[114:117], v[184:187], v[42:45], v[114:117]
	v_mfma_f32_16x16x32_bf16 v[118:121], v[188:191], v[22:25], v[118:121]
	v_mfma_f32_16x16x32_bf16 v[114:117], v[188:191], v[46:49], v[114:117]
	ds_read_b128 v[122:125], v174 offset:4096
	ds_read_b128 v[176:179], v173 offset:4096
	ds_read_b128 v[180:183], v172 offset:4096
	ds_read_b128 v[184:187], v171 offset:4096
	ds_read_b128 v[188:191], v145 offset:18432
	ds_read_b128 v[192:195], v143 offset:18432
	s_nop 0
	v_mul_f32_e32 v175, 0x3dd53b94, v118
	v_mul_f32_e32 v118, 0x3dd53b94, v119
	s_waitcnt lgkmcnt(0)
	v_mfma_f32_16x16x32_bf16 v[210:213], v[122:125], v[2:5], 0
	v_max3_f32 v134, v170, v175, v118
	v_mul_f32_e32 v120, 0x3dd53b94, v120
	v_mul_f32_e32 v119, 0x3dd53b94, v121
	v_mfma_f32_16x16x32_bf16 v[210:213], v[176:179], v[6:9], v[210:213]
	v_max3_f32 v134, v134, v120, v119
	v_mfma_f32_16x16x32_bf16 v[210:213], v[180:183], v[10:13], v[210:213]
	v_mfma_f32_16x16x32_bf16 v[210:213], v[184:187], v[14:17], v[210:213]
	v_mfma_f32_16x16x32_bf16 v[210:213], v[188:191], v[18:21], v[210:213]
	v_mfma_f32_16x16x32_bf16 v[122:125], v[122:125], v[26:29], 0
	v_mfma_f32_16x16x32_bf16 v[210:213], v[192:195], v[22:25], v[210:213]
	v_mfma_f32_16x16x32_bf16 v[122:125], v[176:179], v[30:33], v[122:125]
	v_mfma_f32_16x16x32_bf16 v[122:125], v[180:183], v[34:37], v[122:125]
	s_nop 5
	v_mul_f32_e32 v178, 0x3dd53b94, v210
	v_mul_f32_e32 v121, 0x3dd53b94, v211
	v_max3_f32 v134, v134, v178, v121
	v_mul_f32_e32 v180, 0x3dd53b94, v212
	v_mul_f32_e32 v181, 0x3dd53b94, v213
	v_max3_f32 v134, v134, v180, v181
	v_mov_b32_e32 v135, v134
	v_mfma_f32_16x16x32_bf16 v[122:125], v[184:187], v[38:41], v[122:125]
	s_waitcnt lgkmcnt(0)
	s_nop 1
	v_permlane16_swap_b32_e32 v134, v135
	v_max_f32_e32 v134, v134, v135
	v_mov_b32_e32 v135, v134
	v_mfma_f32_16x16x32_bf16 v[122:125], v[188:191], v[42:45], v[122:125]
	s_waitcnt lgkmcnt(0)
	v_mov_b32_e32 v182, v134
	s_nop 1
	v_permlane32_swap_b32_e32 v182, v135
	v_max_f32_e32 v182, v182, v135
	v_sub_f32_e32 v134, v170, v182
	v_exp_f32_e32 v146, v134
	v_mfma_f32_16x16x32_bf16 v[122:125], v[192:195], v[46:49], v[122:125]
	v_cmp_neq_f32_e32 vcc, 1.0, v146
	s_cbranch_vccz .LBB0_1544
	v_pk_mul_f32 v[88:89], v[88:89], v[146:147] op_sel_hi:[1,0]
	v_pk_mul_f32 v[86:87], v[86:87], v[146:147] op_sel_hi:[1,0]
	v_pk_mul_f32 v[84:85], v[84:85], v[146:147] op_sel_hi:[1,0]
	v_pk_mul_f32 v[82:83], v[82:83], v[146:147] op_sel_hi:[1,0]
	v_pk_mul_f32 v[96:97], v[96:97], v[146:147] op_sel_hi:[1,0]
	v_pk_mul_f32 v[94:95], v[94:95], v[146:147] op_sel_hi:[1,0]
	v_pk_mul_f32 v[92:93], v[92:93], v[146:147] op_sel_hi:[1,0]
	v_pk_mul_f32 v[90:91], v[90:91], v[146:147] op_sel_hi:[1,0]
	v_pk_mul_f32 v[104:105], v[104:105], v[146:147] op_sel_hi:[1,0]
	v_pk_mul_f32 v[102:103], v[102:103], v[146:147] op_sel_hi:[1,0]
	v_pk_mul_f32 v[100:101], v[100:101], v[146:147] op_sel_hi:[1,0]
	v_pk_mul_f32 v[98:99], v[98:99], v[146:147] op_sel_hi:[1,0]
	v_pk_mul_f32 v[108:109], v[108:109], v[146:147] op_sel_hi:[1,0]
	v_pk_mul_f32 v[106:107], v[106:107], v[146:147] op_sel_hi:[1,0]
	v_pk_mul_f32 v[112:113], v[112:113], v[146:147] op_sel_hi:[1,0]
	v_pk_mul_f32 v[110:111], v[110:111], v[146:147] op_sel_hi:[1,0]
.LBB0_1544:
	v_mul_f32_e32 v179, 0x3dd53b94, v114
	v_mul_f32_e32 v176, 0x3dd53b94, v115
	v_max3_f32 v114, v169, v179, v176
	v_mul_f32_e32 v177, 0x3dd53b94, v116
	v_mul_f32_e32 v117, 0x3dd53b94, v117
	v_max3_f32 v114, v114, v177, v117
	v_mul_f32_e32 v170, 0x3dd53b94, v122
	v_mul_f32_e32 v115, 0x3dd53b94, v123
	v_max3_f32 v122, v114, v170, v115
	v_mul_f32_e32 v116, 0x3dd53b94, v124
	v_mul_f32_e32 v114, 0x3dd53b94, v125
	v_max3_f32 v122, v122, v116, v114
	v_mov_b32_e32 v123, v122
	s_waitcnt lgkmcnt(0)
	s_nop 1
	v_permlane16_swap_b32_e32 v122, v123
	v_max_f32_e32 v122, v122, v123
	v_mov_b32_e32 v123, v122
	s_waitcnt lgkmcnt(0)
	v_mov_b32_e32 v183, v122
	s_nop 1
	v_permlane32_swap_b32_e32 v183, v123
	v_max_f32_e32 v183, v183, v123
	v_sub_f32_e32 v122, v169, v183
	v_exp_f32_e32 v122, v122
	s_nop 0
	v_cmp_neq_f32_e32 vcc, 1.0, v122
	s_cbranch_vccz .LBB0_1546
	v_pk_mul_f32 v[56:57], v[56:57], v[122:123] op_sel_hi:[1,0]
	v_pk_mul_f32 v[54:55], v[54:55], v[122:123] op_sel_hi:[1,0]
	v_pk_mul_f32 v[52:53], v[52:53], v[122:123] op_sel_hi:[1,0]
	v_pk_mul_f32 v[50:51], v[50:51], v[122:123] op_sel_hi:[1,0]
	v_pk_mul_f32 v[64:65], v[64:65], v[122:123] op_sel_hi:[1,0]
	v_pk_mul_f32 v[62:63], v[62:63], v[122:123] op_sel_hi:[1,0]
	v_pk_mul_f32 v[60:61], v[60:61], v[122:123] op_sel_hi:[1,0]
	v_pk_mul_f32 v[58:59], v[58:59], v[122:123] op_sel_hi:[1,0]
	v_pk_mul_f32 v[72:73], v[72:73], v[122:123] op_sel_hi:[1,0]
	v_pk_mul_f32 v[70:71], v[70:71], v[122:123] op_sel_hi:[1,0]
	v_pk_mul_f32 v[68:69], v[68:69], v[122:123] op_sel_hi:[1,0]
	v_pk_mul_f32 v[66:67], v[66:67], v[122:123] op_sel_hi:[1,0]
	v_pk_mul_f32 v[80:81], v[80:81], v[122:123] op_sel_hi:[1,0]
	v_pk_mul_f32 v[78:79], v[78:79], v[122:123] op_sel_hi:[1,0]
	v_pk_mul_f32 v[76:77], v[76:77], v[122:123] op_sel_hi:[1,0]
	v_pk_mul_f32 v[74:75], v[74:75], v[122:123] op_sel_hi:[1,0]
; __device__ __forceinline__ float fexp2(float x) { return __builtin_amdgcn_exp2f(x); }
; template <int DKA, int DKB, int DV, bool BAND, bool SINK> ...
;     ...
;           for (int ks = 0; ks < KS; ++ks) a = mfma16(kf[ks], qf[qb][ks], a);
;           s[qb][kb2] = a;
;         }
;       }
; #pragma unroll
;       for (int qb = 0; qb < 2; ++qb) {
;         float mx = mrun[qb];
;         const int qp = qpos0 + wave * 32 + qb * 16 + fr;
; #pragma unroll
;         for (int kb2 = 0; kb2 < 2; ++kb2)
; #pragma unroll
;           for (int j = 0; j < 4; ++j) {
;             float v = s[qb][kb2][j] * scale2;
;             if (BAND && k0 < 2048) {
;               int d = qp - (k0 + (kk * 2 + kb2) * 16 + fq * 4 + j);
;               if (d > 128 || d < -128) v = -1e30f;
;             }
;             s[qb][kb2][j] = v;
;             mx = fmaxf(mx, v);
;           }
;         mx = fmaxf(mx, __shfl_xor(mx, 16));
;         mx = fmaxf(mx, __shfl_xor(mx, 32));
;         const float alpha = fexp2(mrun[qb] - mx);
;         mrun[qb] = mx;
;         float ls = 0.f;
; #pragma unroll
;         for (int kb2 = 0; kb2 < 2; ++kb2)
; #pragma unroll
;           for (int j = 0; j < 4; ++j) {
;             float pv = fexp2(s[qb][kb2][j] - mx);
;             s[qb][kb2][j] = pv;
;             ls += pv;
;           }
;         lrun[qb] = lrun[qb] * alpha + ls;
;         if (__any(alpha != 1.f)) {
; #pragma unroll
;           for (int eb = 0; eb < EB; ++eb) {
;             o[qb][eb][0] *= alpha; o[qb][eb][1] *= alpha; o[qb][eb][2] *= alpha; o[qb][eb][3] *= alpha;
;           }
;         }
;       }
;       bf16x8 pf[2];
; #pragma unroll
;       for (int qb = 0; qb < 2; ++qb)
;         pf[qb] = mk8(pack2(s[qb][0][0], s[qb][0][1]), pack2(s[qb][0][2], s[qb][0][3]),
;                      pack2(s[qb][1][0], s[qb][1][1]), pack2(s[qb][1][2], s[qb][1][3]));
; #pragma unroll
;       for (int eb = 0; eb < EB; ++eb) {
;         const char* vrow = vbuf + (eb * 16 + fr) * 128 + (fq & 1) * 8;
;         uint2 v0 = *(const uint2*)(vrow + (((kk * 4 + (fq >> 1)) ^ swz8) * 16));
;         uint2 v1 = *(const uint2*)(vrow + (((kk * 4 + 2 + (fq >> 1)) ^ swz8) * 16));
;         bf16x8 vf = mk8(v0.x, v0.y, v1.x, v1.y);
; #pragma unroll
;         for (int qb = 0; qb < 2; ++qb) o[qb][eb] = mfma16(vf, pf[qb], o[qb][eb]);
;       }
.LBB0_1546:
	v_sub_f32_e32 v123, v179, v183
	v_exp_f32_e32 v184, v123
	v_sub_f32_e32 v123, v176, v183
	v_sub_f32_e32 v114, v114, v183
	v_exp_f32_e32 v185, v123
	v_sub_f32_e32 v123, v177, v183
	v_exp_f32_e32 v191, v114
	v_sub_f32_e32 v114, v175, v182
	v_exp_f32_e32 v186, v123
	v_lshl_or_b32 v123, s0, 14, v157
	v_exp_f32_e32 v125, v114
	v_sub_f32_e32 v114, v118, v182
	v_exp_f32_e32 v175, v114
	v_sub_f32_e32 v114, v120, v182
	v_add_u32_e32 v124, v123, v164
	v_add_u32_e32 v134, v123, v165
	v_exp_f32_e32 v176, v114
	v_sub_f32_e32 v114, v119, v182
	ds_read2st64_b64 v[192:195], v124 offset0:96 offset1:100
	ds_read2st64_b64 v[210:213], v134 offset0:96 offset1:100
	v_exp_f32_e32 v177, v114
	v_sub_f32_e32 v114, v178, v182
	v_exp_f32_e32 v178, v114
	v_sub_f32_e32 v114, v121, v182
	v_sub_f32_e32 v117, v117, v183
	v_sub_f32_e32 v115, v115, v183
	v_exp_f32_e32 v179, v114
	v_sub_f32_e32 v114, v180, v182
	v_exp_f32_e32 v187, v117
	v_sub_f32_e32 v117, v170, v183
	v_exp_f32_e32 v189, v115
	v_sub_f32_e32 v115, v116, v183
	v_exp_f32_e32 v180, v114
	v_sub_f32_e32 v114, v181, v182
	v_exp_f32_e32 v188, v117
	v_exp_f32_e32 v190, v115
	v_exp_f32_e32 v181, v114
	s_waitcnt lgkmcnt(0)
	v_mov_b32_e32 v216, v210
	v_mov_b32_e32 v217, v211
	v_mov_b32_e32 v210, v194
	v_mov_b32_e32 v211, v195
	v_cvt_pk_bf16_f32 v114, v125, v175
	v_cvt_pk_bf16_f32 v115, v176, v177
	v_cvt_pk_bf16_f32 v116, v178, v179
	v_cvt_pk_bf16_f32 v117, v180, v181
	v_cvt_pk_bf16_f32 v118, v184, v185
	v_cvt_pk_bf16_f32 v119, v186, v187
	v_cvt_pk_bf16_f32 v120, v188, v189
	v_cvt_pk_bf16_f32 v121, v190, v191
	v_mov_b32_e32 v214, v192
	v_mov_b32_e32 v215, v193
	v_mfma_f32_16x16x32_bf16 v[82:85], v[210:213], v[114:117], v[82:85]
	v_mfma_f32_16x16x32_bf16 v[50:53], v[210:213], v[118:121], v[50:53]
	ds_read2st64_b64 v[192:195], v124 offset0:104 offset1:108
	ds_read2st64_b64 v[210:213], v134 offset0:104 offset1:108
	v_mfma_f32_16x16x32_bf16 v[86:89], v[214:217], v[114:117], v[86:89]
	v_mfma_f32_16x16x32_bf16 v[54:57], v[214:217], v[118:121], v[54:57]
	s_waitcnt lgkmcnt(0)
	v_mov_b32_e32 v216, v210
	v_mov_b32_e32 v217, v211
	v_mov_b32_e32 v210, v194
	v_mov_b32_e32 v211, v195
	v_mov_b32_e32 v214, v192
	v_mov_b32_e32 v215, v193
	v_mfma_f32_16x16x32_bf16 v[90:93], v[210:213], v[114:117], v[90:93]
	v_mfma_f32_16x16x32_bf16 v[58:61], v[210:213], v[118:121], v[58:61]
	ds_read2st64_b64 v[192:195], v124 offset0:112 offset1:116
	ds_read2st64_b64 v[210:213], v134 offset0:112 offset1:116
	v_mfma_f32_16x16x32_bf16 v[94:97], v[214:217], v[114:117], v[94:97]
	v_mfma_f32_16x16x32_bf16 v[62:65], v[214:217], v[118:121], v[62:65]
	s_waitcnt lgkmcnt(0)
	v_mov_b32_e32 v216, v210
	v_mov_b32_e32 v217, v211
	v_mov_b32_e32 v210, v194
	v_mov_b32_e32 v211, v195
	v_mov_b32_e32 v214, v192
	v_mov_b32_e32 v215, v193
	v_mfma_f32_16x16x32_bf16 v[98:101], v[210:213], v[114:117], v[98:101]
	v_mfma_f32_16x16x32_bf16 v[66:69], v[210:213], v[118:121], v[66:69]
	ds_read2st64_b64 v[192:195], v124 offset0:120 offset1:124
	ds_read2st64_b64 v[210:213], v134 offset0:120 offset1:124
	v_mfma_f32_16x16x32_bf16 v[102:105], v[214:217], v[114:117], v[102:105]
	v_mfma_f32_16x16x32_bf16 v[70:73], v[214:217], v[118:121], v[70:73]
	s_waitcnt lgkmcnt(0)
	v_mov_b32_e32 v214, v192
	v_mov_b32_e32 v215, v193
	v_mov_b32_e32 v216, v210
	v_mov_b32_e32 v217, v211
	v_mov_b32_e32 v210, v194
	v_mov_b32_e32 v211, v195
	v_mfma_f32_16x16x32_bf16 v[106:109], v[214:217], v[114:117], v[106:109]
	v_mfma_f32_16x16x32_bf16 v[78:81], v[214:217], v[118:121], v[78:81]
	v_mfma_f32_16x16x32_bf16 v[110:113], v[210:213], v[114:117], v[110:113]
	v_mfma_f32_16x16x32_bf16 v[74:77], v[210:213], v[118:121], v[74:77]
	ds_read_b128 v[114:117], v174 offset:8192
	ds_read_b128 v[118:121], v173 offset:8192
	ds_read_b128 v[192:195], v172 offset:8192
	ds_read_b128 v[210:213], v171 offset:8192
	ds_read_b128 v[214:217], v145 offset:20480
	ds_read_b128 v[218:221], v143 offset:20480
	s_waitcnt lgkmcnt(0)
	v_mfma_f32_16x16x32_bf16 v[222:225], v[114:117], v[2:5], 0
	v_mfma_f32_16x16x32_bf16 v[114:117], v[114:117], v[26:29], 0
	v_mfma_f32_16x16x32_bf16 v[222:225], v[118:121], v[6:9], v[222:225]
	v_mfma_f32_16x16x32_bf16 v[114:117], v[118:121], v[30:33], v[114:117]
	v_mfma_f32_16x16x32_bf16 v[222:225], v[192:195], v[10:13], v[222:225]
	v_mfma_f32_16x16x32_bf16 v[114:117], v[192:195], v[34:37], v[114:117]
	v_mfma_f32_16x16x32_bf16 v[222:225], v[210:213], v[14:17], v[222:225]
	v_mfma_f32_16x16x32_bf16 v[114:117], v[210:213], v[38:41], v[114:117]
	v_mfma_f32_16x16x32_bf16 v[222:225], v[214:217], v[18:21], v[222:225]
	v_mfma_f32_16x16x32_bf16 v[114:117], v[214:217], v[42:45], v[114:117]
	v_mfma_f32_16x16x32_bf16 v[222:225], v[218:221], v[22:25], v[222:225]
	v_mfma_f32_16x16x32_bf16 v[114:117], v[218:221], v[46:49], v[114:117]
	ds_read_b128 v[118:121], v174 offset:12288
	ds_read_b128 v[192:195], v173 offset:12288
	ds_read_b128 v[210:213], v172 offset:12288
	ds_read_b128 v[170:173], v171 offset:12288
	ds_read_b128 v[214:217], v145 offset:22528
	ds_read_b128 v[218:221], v143 offset:22528
	s_nop 0
	v_mul_f32_e32 v174, 0x3dd53b94, v224
	s_waitcnt lgkmcnt(0)
	v_mfma_f32_16x16x32_bf16 v[226:229], v[118:121], v[2:5], 0
	v_mfma_f32_16x16x32_bf16 v[226:229], v[192:195], v[6:9], v[226:229]
	v_mfma_f32_16x16x32_bf16 v[226:229], v[210:213], v[10:13], v[226:229]
	v_mfma_f32_16x16x32_bf16 v[118:121], v[118:121], v[26:29], 0
	v_mfma_f32_16x16x32_bf16 v[226:229], v[170:173], v[14:17], v[226:229]
	v_mfma_f32_16x16x32_bf16 v[118:121], v[192:195], v[30:33], v[118:121]
	v_mul_f32_e32 v193, 0x3dd53b94, v222
	v_mul_f32_e32 v192, 0x3dd53b94, v223
	v_max3_f32 v124, v182, v193, v192
	v_mfma_f32_16x16x32_bf16 v[226:229], v[214:217], v[18:21], v[226:229]
	v_mfma_f32_16x16x32_bf16 v[118:121], v[210:213], v[34:37], v[118:121]
	v_mfma_f32_16x16x32_bf16 v[226:229], v[218:221], v[22:25], v[226:229]
	v_mfma_f32_16x16x32_bf16 v[118:121], v[170:173], v[38:41], v[118:121]
	v_mul_f32_e32 v173, 0x3dd53b94, v225
	v_max3_f32 v124, v124, v174, v173
	s_nop 4
	v_mul_f32_e32 v172, 0x3dd53b94, v226
	v_mul_f32_e32 v171, 0x3dd53b94, v227
	v_max3_f32 v124, v124, v172, v171
	v_mul_f32_e32 v145, 0x3dd53b94, v228
	v_mul_f32_e32 v143, 0x3dd53b94, v229
	v_max3_f32 v124, v124, v145, v143
	v_mov_b32_e32 v134, v124
	v_mfma_f32_16x16x32_bf16 v[118:121], v[214:217], v[42:45], v[118:121]
	s_waitcnt lgkmcnt(0)
	s_nop 1
	v_permlane16_swap_b32_e32 v124, v134
	v_max_f32_e32 v124, v124, v134
	v_mov_b32_e32 v134, v124
	v_mfma_f32_16x16x32_bf16 v[118:121], v[218:221], v[46:49], v[118:121]
	s_waitcnt lgkmcnt(0)
	v_mov_b32_e32 v170, v124
	s_nop 1
	v_permlane32_swap_b32_e32 v170, v134
	v_max_f32_e32 v170, v170, v134
	v_sub_f32_e32 v124, v182, v170
	v_exp_f32_e32 v124, v124
	s_nop 0
	v_cmp_neq_f32_e32 vcc, 1.0, v124
	s_cbranch_vccz .LBB0_1548
; __device__ __forceinline__ float fexp2(float x) { return __builtin_amdgcn_exp2f(x); }
; template <int DKA, int DKB, int DV, bool BAND, bool SINK> ...
;     ...
; #pragma unroll
;       for (int qb = 0; qb < 2; ++qb) {
;         float mx = mrun[qb];
;         const int qp = qpos0 + wave * 32 + qb * 16 + fr;
; #pragma unroll
;         for (int kb2 = 0; kb2 < 2; ++kb2)
; #pragma unroll
;           for (int j = 0; j < 4; ++j) {
;             float v = s[qb][kb2][j] * scale2;
;             if (BAND && k0 < 2048) {
;               int d = qp - (k0 + (kk * 2 + kb2) * 16 + fq * 4 + j);
;               if (d > 128 || d < -128) v = -1e30f;
;             }
;             s[qb][kb2][j] = v;
;             mx = fmaxf(mx, v);
;           }
;         mx = fmaxf(mx, __shfl_xor(mx, 16));
;         mx = fmaxf(mx, __shfl_xor(mx, 32));
;         const float alpha = fexp2(mrun[qb] - mx);
;         mrun[qb] = mx;
;         float ls = 0.f;
; #pragma unroll
;         for (int kb2 = 0; kb2 < 2; ++kb2)
; #pragma unroll
;           for (int j = 0; j < 4; ++j) {
;             float pv = fexp2(s[qb][kb2][j] - mx);
;             s[qb][kb2][j] = pv;
;             ls += pv;
;           }
;         lrun[qb] = lrun[qb] * alpha + ls;
;         if (__any(alpha != 1.f)) {
; #pragma unroll
;           for (int eb = 0; eb < EB; ++eb) {
;             o[qb][eb][0] *= alpha; o[qb][eb][1] *= alpha; o[qb][eb][2] *= alpha; o[qb][eb][3] *= alpha;
;           }
;         }
;       }
	v_pk_mul_f32 v[88:89], v[88:89], v[124:125] op_sel_hi:[1,0]
	v_pk_mul_f32 v[86:87], v[86:87], v[124:125] op_sel_hi:[1,0]
	v_pk_mul_f32 v[84:85], v[84:85], v[124:125] op_sel_hi:[1,0]
	v_pk_mul_f32 v[82:83], v[82:83], v[124:125] op_sel_hi:[1,0]
	v_pk_mul_f32 v[96:97], v[96:97], v[124:125] op_sel_hi:[1,0]
	v_pk_mul_f32 v[94:95], v[94:95], v[124:125] op_sel_hi:[1,0]
	v_pk_mul_f32 v[92:93], v[92:93], v[124:125] op_sel_hi:[1,0]
	v_pk_mul_f32 v[90:91], v[90:91], v[124:125] op_sel_hi:[1,0]
	v_pk_mul_f32 v[104:105], v[104:105], v[124:125] op_sel_hi:[1,0]
	v_pk_mul_f32 v[102:103], v[102:103], v[124:125] op_sel_hi:[1,0]
	v_pk_mul_f32 v[100:101], v[100:101], v[124:125] op_sel_hi:[1,0]
	v_pk_mul_f32 v[98:99], v[98:99], v[124:125] op_sel_hi:[1,0]
	v_pk_mul_f32 v[108:109], v[108:109], v[124:125] op_sel_hi:[1,0]
	v_pk_mul_f32 v[106:107], v[106:107], v[124:125] op_sel_hi:[1,0]
	v_pk_mul_f32 v[112:113], v[112:113], v[124:125] op_sel_hi:[1,0]
	v_pk_mul_f32 v[110:111], v[110:111], v[124:125] op_sel_hi:[1,0]
.LBB0_1548:
	v_mul_f32_e32 v210, 0x3dd53b94, v114
	v_mul_f32_e32 v195, 0x3dd53b94, v115
	v_max3_f32 v114, v183, v210, v195
	v_mul_f32_e32 v194, 0x3dd53b94, v116
	v_mul_f32_e32 v182, 0x3dd53b94, v117
	v_max3_f32 v114, v114, v194, v182
	v_mul_f32_e32 v118, 0x3dd53b94, v118
	v_mul_f32_e32 v117, 0x3dd53b94, v119
	v_max3_f32 v114, v114, v118, v117
	v_mul_f32_e32 v116, 0x3dd53b94, v120
	v_mul_f32_e32 v115, 0x3dd53b94, v121
	v_max3_f32 v114, v114, v116, v115
	v_mov_b32_e32 v119, v114
	s_waitcnt lgkmcnt(0)
	s_nop 1
	v_permlane16_swap_b32_e32 v114, v119
	v_max_f32_e32 v114, v114, v119
	v_mov_b32_e32 v119, v114
	s_waitcnt lgkmcnt(0)
	v_mov_b32_e32 v169, v114
	s_nop 1
	v_permlane32_swap_b32_e32 v169, v119
	v_max_f32_e32 v169, v169, v119
	v_sub_f32_e32 v114, v183, v169
	v_exp_f32_e32 v114, v114
	s_nop 0
	v_cmp_neq_f32_e32 vcc, 1.0, v114
	s_cbranch_vccz .LBB0_1550
	v_pk_mul_f32 v[56:57], v[56:57], v[114:115] op_sel_hi:[1,0]
	v_pk_mul_f32 v[54:55], v[54:55], v[114:115] op_sel_hi:[1,0]
	v_pk_mul_f32 v[52:53], v[52:53], v[114:115] op_sel_hi:[1,0]
	v_pk_mul_f32 v[50:51], v[50:51], v[114:115] op_sel_hi:[1,0]
	v_pk_mul_f32 v[64:65], v[64:65], v[114:115] op_sel_hi:[1,0]
	v_pk_mul_f32 v[62:63], v[62:63], v[114:115] op_sel_hi:[1,0]
	v_pk_mul_f32 v[60:61], v[60:61], v[114:115] op_sel_hi:[1,0]
	v_pk_mul_f32 v[58:59], v[58:59], v[114:115] op_sel_hi:[1,0]
	v_pk_mul_f32 v[72:73], v[72:73], v[114:115] op_sel_hi:[1,0]
	v_pk_mul_f32 v[70:71], v[70:71], v[114:115] op_sel_hi:[1,0]
	v_pk_mul_f32 v[68:69], v[68:69], v[114:115] op_sel_hi:[1,0]
	v_pk_mul_f32 v[66:67], v[66:67], v[114:115] op_sel_hi:[1,0]
	v_pk_mul_f32 v[80:81], v[80:81], v[114:115] op_sel_hi:[1,0]
	v_pk_mul_f32 v[78:79], v[78:79], v[114:115] op_sel_hi:[1,0]
	v_pk_mul_f32 v[76:77], v[76:77], v[114:115] op_sel_hi:[1,0]
	v_pk_mul_f32 v[74:75], v[74:75], v[114:115] op_sel_hi:[1,0]

; __device__ __forceinline__ float lo_bf(unsigned u) { return __uint_as_float(u << 16); }
; __device__ __forceinline__ float hi_bf(unsigned u) { return __uint_as_float(u & 0xffff0000u); }
; __device__ __forceinline__ void cmlp_item(const Params& p, int j, int rt, int g, const u16* __restrict__ ZB, u16* sVT) {
;     ...
;   __syncthreads();
;   {
;     const int q = tid >> 1, half = tid & 1;
;     const u16* src = ZB + (size_t)(m0 + q) * 1024 + 512 + g * 128 + half * 64;
;     uint4 raw[8];
; #pragma unroll
;     for (int i = 0; i < 8; ++i) raw[i] = *(const uint4*)(src + i * 8);
;     float ss = 0.f;
; #pragma unroll
;     for (int i = 0; i < 8; ++i) {
;       unsigned w[4] = {raw[i].x, raw[i].y, raw[i].z, raw[i].w};
; #pragma unroll
;       for (int k = 0; k < 4; ++k) { float a = lo_bf(w[k]), b = hi_bf(w[k]); ss += a * a + b * b; }
;     }
;     ss += __shfl_xor(ss, 1);
;     const float rstd = rsqrtf(ss * (1.f / 128.f) + EPSV);
.LBB0_1553:
	v_mov_b32_e32 v38, v206
	s_and_b32 s9, s1, 0xffffff80
	v_bfe_u32 v0, v38, 1, 7
	v_or_b32_e32 v2, s9, v0
	v_ashrrev_i32_e32 v3, 31, v2
	s_and_b32 s10, s0, 3
	v_lshlrev_b64 v[2:3], 11, v[2:3]
	v_lshlrev_b32_e32 v0, 6, v38
	v_lshl_add_u64 v[2:3], s[92:93], 0, v[2:3]
	s_lshl_b32 s34, s10, 8
	v_and_b32_e32 v39, 64, v0
	v_lshl_add_u64 v[2:3], v[2:3], 0, s[34:35]
	v_lshlrev_b32_e32 v0, 1, v39
	v_lshl_add_u64 v[30:31], v[2:3], 0, v[0:1]
	s_waitcnt vmcnt(0)
	s_barrier
	global_load_dwordx4 v[2:5], v[30:31], off offset:1072
	global_load_dwordx4 v[6:9], v[30:31], off offset:1056
	global_load_dwordx4 v[10:13], v[30:31], off offset:1040
	global_load_dwordx4 v[14:17], v[30:31], off offset:1024
	global_load_dwordx4 v[18:21], v[30:31], off offset:1104
	global_load_dwordx4 v[22:25], v[30:31], off offset:1088
	global_load_dwordx4 v[26:29], v[30:31], off offset:1136
	s_nop 0
	global_load_dwordx4 v[30:33], v[30:31], off offset:1120
	s_lshl_b32 s6, s10, 9
	s_add_u32 s6, s14, s6
	s_addc_u32 s7, s15, 0
	v_lshlrev_b32_e32 v87, 2, v39
	s_or_b32 s10, s10, s16
	v_and_b32_e32 v67, 15, v38
	v_bfe_u32 v66, v38, 6, 2
	s_waitcnt vmcnt(7)
	v_and_b32_e32 v64, 0xffff0000, v2
	s_waitcnt vmcnt(6)
	v_and_b32_e32 v56, 0xffff0000, v6
	s_waitcnt vmcnt(5)
	v_and_b32_e32 v48, 0xffff0000, v10
	s_waitcnt vmcnt(4)
	v_and_b32_e32 v40, 0xffff0000, v14
	v_and_b32_e32 v42, 0xffff0000, v15
	v_lshlrev_b32_e32 v0, 16, v14
	v_mul_f32_e32 v14, v40, v40
	v_lshlrev_b32_e32 v41, 16, v15
	v_mul_f32_e32 v15, v42, v42
	v_fmac_f32_e32 v14, v0, v0
	v_fmac_f32_e32 v15, v41, v41
	v_and_b32_e32 v44, 0xffff0000, v16
	v_add_f32_e32 v14, v14, v15
	v_lshlrev_b32_e32 v43, 16, v16
	v_mul_f32_e32 v15, v44, v44
	v_fmac_f32_e32 v15, v43, v43
	v_and_b32_e32 v46, 0xffff0000, v17
	v_add_f32_e32 v14, v14, v15
	v_lshlrev_b32_e32 v45, 16, v17
	v_mul_f32_e32 v15, v46, v46
	v_fmac_f32_e32 v15, v45, v45
	v_lshlrev_b32_e32 v47, 16, v10
	v_mul_f32_e32 v10, v48, v48
	v_and_b32_e32 v50, 0xffff0000, v11
	v_add_f32_e32 v14, v14, v15
	v_fmac_f32_e32 v10, v47, v47
	v_lshlrev_b32_e32 v49, 16, v11
	v_mul_f32_e32 v11, v50, v50
	v_add_f32_e32 v10, v14, v10
	v_fmac_f32_e32 v11, v49, v49
	v_and_b32_e32 v52, 0xffff0000, v12
	v_add_f32_e32 v10, v10, v11
	v_lshlrev_b32_e32 v51, 16, v12
	v_mul_f32_e32 v11, v52, v52
	v_fmac_f32_e32 v11, v51, v51
	v_and_b32_e32 v54, 0xffff0000, v13
	v_add_f32_e32 v10, v10, v11
	v_lshlrev_b32_e32 v53, 16, v13
	v_mul_f32_e32 v11, v54, v54
	v_fmac_f32_e32 v11, v53, v53
	v_lshlrev_b32_e32 v55, 16, v6
	v_mul_f32_e32 v6, v56, v56
	v_and_b32_e32 v58, 0xffff0000, v7
	v_add_f32_e32 v10, v10, v11
	v_fmac_f32_e32 v6, v55, v55
	v_lshlrev_b32_e32 v57, 16, v7
	v_mul_f32_e32 v7, v58, v58
	v_add_f32_e32 v6, v10, v6
	v_fmac_f32_e32 v7, v57, v57
	v_and_b32_e32 v60, 0xffff0000, v8
	v_add_f32_e32 v6, v6, v7
	v_lshlrev_b32_e32 v59, 16, v8
	v_mul_f32_e32 v7, v60, v60
	v_fmac_f32_e32 v7, v59, v59
	v_and_b32_e32 v62, 0xffff0000, v9
	v_add_f32_e32 v6, v6, v7
	v_lshlrev_b32_e32 v61, 16, v9
	v_mul_f32_e32 v7, v62, v62
	v_fmac_f32_e32 v7, v61, v61
	v_lshlrev_b32_e32 v63, 16, v2
	v_mul_f32_e32 v2, v64, v64
	v_and_b32_e32 v68, 0xffff0000, v3
	v_add_f32_e32 v6, v6, v7
	v_fmac_f32_e32 v2, v63, v63
	v_lshlrev_b32_e32 v65, 16, v3
	v_mul_f32_e32 v3, v68, v68
	v_add_f32_e32 v2, v6, v2
	v_fmac_f32_e32 v3, v65, v65
	v_and_b32_e32 v70, 0xffff0000, v4
	v_add_f32_e32 v2, v2, v3
	v_lshlrev_b32_e32 v69, 16, v4
	v_mul_f32_e32 v3, v70, v70
	v_fmac_f32_e32 v3, v69, v69
	v_and_b32_e32 v73, 0xffff0000, v5
	v_add_f32_e32 v2, v2, v3
	v_lshlrev_b32_e32 v72, 16, v5
	v_mul_f32_e32 v3, v73, v73
	v_fmac_f32_e32 v3, v72, v72
	s_waitcnt vmcnt(2)
	v_and_b32_e32 v75, 0xffff0000, v22
	v_add_f32_e32 v2, v2, v3
	v_lshlrev_b32_e32 v74, 16, v22
	v_mul_f32_e32 v3, v75, v75
	v_fmac_f32_e32 v3, v74, v74
	v_and_b32_e32 v77, 0xffff0000, v23
	v_add_f32_e32 v2, v2, v3
	v_lshlrev_b32_e32 v76, 16, v23
	v_mul_f32_e32 v3, v77, v77
	v_fmac_f32_e32 v3, v76, v76
	v_and_b32_e32 v79, 0xffff0000, v24
	v_add_f32_e32 v2, v2, v3
	v_lshlrev_b32_e32 v78, 16, v24
	v_mul_f32_e32 v3, v79, v79
	v_fmac_f32_e32 v3, v78, v78
	v_and_b32_e32 v81, 0xffff0000, v25
	v_add_f32_e32 v2, v2, v3
	v_lshlrev_b32_e32 v80, 16, v25
	v_mul_f32_e32 v3, v81, v81
	v_fmac_f32_e32 v3, v80, v80
	v_and_b32_e32 v83, 0xffff0000, v18
	v_add_f32_e32 v2, v2, v3
	v_lshlrev_b32_e32 v82, 16, v18
	v_mul_f32_e32 v3, v83, v83
	v_fmac_f32_e32 v3, v82, v82
	v_and_b32_e32 v85, 0xffff0000, v19
	v_add_f32_e32 v2, v2, v3
	v_lshlrev_b32_e32 v84, 16, v19
	v_mul_f32_e32 v3, v85, v85
	v_fmac_f32_e32 v3, v84, v84
	v_and_b32_e32 v19, 0xffff0000, v21
	v_and_b32_e32 v18, 0xffff0000, v20
	v_add_f32_e32 v4, v2, v3
	v_lshlrev_b32_e32 v37, 16, v21
	v_lshlrev_b32_e32 v36, 16, v20
	v_pk_mul_f32 v[2:3], v[18:19], v[18:19]
	s_waitcnt vmcnt(0)
	v_and_b32_e32 v15, 0xffff0000, v31
	v_pk_fma_f32 v[2:3], v[36:37], v[36:37], v[2:3]
	v_and_b32_e32 v14, 0xffff0000, v30
	v_add_f32_e32 v2, v4, v2
	v_add_f32_e32 v4, v2, v3
	v_lshlrev_b32_e32 v17, 16, v31
	v_lshlrev_b32_e32 v16, 16, v30
	v_pk_mul_f32 v[2:3], v[14:15], v[14:15]
	v_and_b32_e32 v11, 0xffff0000, v33
	v_pk_fma_f32 v[2:3], v[16:17], v[16:17], v[2:3]
	v_and_b32_e32 v10, 0xffff0000, v32
	v_add_f32_e32 v2, v4, v2
	v_add_f32_e32 v4, v2, v3
	v_lshlrev_b32_e32 v13, 16, v33
	v_lshlrev_b32_e32 v12, 16, v32
	v_pk_mul_f32 v[2:3], v[10:11], v[10:11]
	v_and_b32_e32 v7, 0xffff0000, v27
	v_pk_fma_f32 v[2:3], v[12:13], v[12:13], v[2:3]
	v_and_b32_e32 v6, 0xffff0000, v26
	v_add_f32_e32 v2, v4, v2
	v_add_f32_e32 v4, v2, v3
	v_lshlrev_b32_e32 v9, 16, v27
	v_lshlrev_b32_e32 v8, 16, v26
	v_pk_mul_f32 v[2:3], v[6:7], v[6:7]
	v_lshlrev_b32_e32 v5, 16, v29
	v_pk_fma_f32 v[2:3], v[8:9], v[8:9], v[2:3]
	s_nop 0
	v_add_f32_e32 v2, v4, v2
	v_add_f32_e32 v22, v2, v3
	v_and_b32_e32 v3, 0xffff0000, v29
	v_and_b32_e32 v2, 0xffff0000, v28
	v_lshlrev_b32_e32 v4, 16, v28
	v_pk_mul_f32 v[20:21], v[2:3], v[2:3]
	s_nop 0
	v_pk_fma_f32 v[20:21], v[4:5], v[4:5], v[20:21]
	s_nop 0
	v_add_f32_e32 v20, v22, v20
	v_add_f32_e32 v20, v20, v21
	ds_bpermute_b32 v21, v71, v20
	s_waitcnt lgkmcnt(0)
; __device__ __forceinline__ float lo_bf(unsigned u) { return __uint_as_float(u << 16); }
; __device__ __forceinline__ float hi_bf(unsigned u) { return __uint_as_float(u & 0xffff0000u); }
; __device__ __forceinline__ void cmlp_item(const Params& p, int j, int rt, int g, const u16* __restrict__ ZB, u16* sVT) {
;     ...
;     const float rstd = rsqrtf(ss * (1.f / 128.f) + EPSV);
;     const float* vn = p.cmlp_v_norm + j * 512 + g * 128 + half * 64;
; #pragma unroll
;     for (int i = 0; i < 8; ++i) {
;       unsigned w[4] = {raw[i].x, raw[i].y, raw[i].z, raw[i].w};
; #pragma unroll
;       for (int k = 0; k < 4; ++k) {
;         int d = i * 8 + k * 2;
;         sVT[(half * 64 + d) * 136 + q] = f2bf(lo_bf(w[k]) * rstd * vn[d]);
;         sVT[(half * 64 + d + 1) * 136 + q] = f2bf(hi_bf(w[k]) * rstd * vn[d + 1]);
;       }
;     }
	v_add_f32_e32 v20, v20, v21
	v_fmamk_f32 v20, v20, 0x3c000000, v252
	v_cmp_gt_f32_e32 vcc, s90, v20
	v_mul_f32_e32 v21, 0x4b800000, v20
	s_nop 0
	v_cndmask_b32_e32 v20, v20, v21, vcc
	v_rsq_f32_e32 v20, v20
	s_nop 0
	v_mul_f32_e32 v21, 0x45800000, v20
	v_cndmask_b32_e32 v86, v20, v21, vcc
	global_load_dwordx4 v[20:23], v87, s[6:7] offset:48
	global_load_dwordx4 v[24:27], v87, s[6:7] offset:32
	global_load_dwordx4 v[28:31], v87, s[6:7] offset:16
	global_load_dwordx4 v[32:35], v87, s[6:7]
	v_mul_f32_e32 v0, v86, v0
	s_waitcnt vmcnt(0)
	v_mul_f32_e32 v0, v32, v0
	v_mul_u32_u24_e32 v32, 0x88, v39
	v_lshlrev_b32_e32 v32, 1, v32
	v_and_b32_e32 v39, 0xfe, v38
	v_cvt_pk_bf16_f32 v0, v0, s0
	v_add3_u32 v88, s58, v32, v39
	ds_write_b16 v88, v0
	v_mul_f32_e32 v0, v86, v40
	v_mul_f32_e32 v0, v33, v0
	v_cvt_pk_bf16_f32 v0, v0, s0
	v_add3_u32 v39, s58, v39, v32
	ds_write_b16 v39, v0 offset:272
	v_mul_f32_e32 v0, v86, v41
	v_mul_f32_e32 v0, v34, v0
	v_cvt_pk_bf16_f32 v0, v0, s0
	ds_write_b16 v88, v0 offset:544
	v_mul_f32_e32 v0, v86, v42
	v_mul_f32_e32 v0, v35, v0
	v_cvt_pk_bf16_f32 v0, v0, s0
	ds_write_b16 v39, v0 offset:816
	v_mul_f32_e32 v0, v86, v43
	v_mul_f32_e32 v0, v28, v0
	v_cvt_pk_bf16_f32 v0, v0, s0
	ds_write_b16 v88, v0 offset:1088
	v_mul_f32_e32 v0, v86, v44
	v_mul_f32_e32 v0, v0, v29
	v_cvt_pk_bf16_f32 v0, v0, s0
	ds_write_b16 v39, v0 offset:1360
	v_mul_f32_e32 v0, v86, v45
	v_mul_f32_e32 v0, v0, v30
	v_cvt_pk_bf16_f32 v0, v0, s0
	ds_write_b16 v88, v0 offset:1632
	v_mul_f32_e32 v0, v86, v46
	v_mul_f32_e32 v0, v0, v31
	v_cvt_pk_bf16_f32 v0, v0, s0
	ds_write_b16 v39, v0 offset:1904
	v_mul_f32_e32 v0, v86, v47
	v_mul_f32_e32 v0, v0, v24
	v_cvt_pk_bf16_f32 v0, v0, s0
	ds_write_b16 v88, v0 offset:2176
	v_mul_f32_e32 v0, v86, v48
	v_mul_f32_e32 v0, v0, v25
	v_cvt_pk_bf16_f32 v0, v0, s0
	ds_write_b16 v39, v0 offset:2448
	v_mul_f32_e32 v0, v86, v49
	v_mul_f32_e32 v0, v0, v26
	v_cvt_pk_bf16_f32 v0, v0, s0
	ds_write_b16 v88, v0 offset:2720
	v_mul_f32_e32 v0, v86, v50
	v_mul_f32_e32 v0, v0, v27
	v_cvt_pk_bf16_f32 v0, v0, s0
	ds_write_b16 v39, v0 offset:2992
	v_mul_f32_e32 v0, v86, v51
	v_mul_f32_e32 v0, v0, v20
	v_cvt_pk_bf16_f32 v0, v0, s0
	ds_write_b16 v88, v0 offset:3264
	v_mul_f32_e32 v0, v86, v52
	v_mul_f32_e32 v0, v0, v21
	v_cvt_pk_bf16_f32 v0, v0, s0
	ds_write_b16 v39, v0 offset:3536
	v_mul_f32_e32 v0, v86, v53
	v_mul_f32_e32 v0, v0, v22
	v_cvt_pk_bf16_f32 v0, v0, s0
	ds_write_b16 v88, v0 offset:3808
	v_mul_f32_e32 v0, v86, v54
	v_mul_f32_e32 v0, v0, v23
	v_cvt_pk_bf16_f32 v0, v0, s0
	ds_write_b16 v39, v0 offset:4080
	global_load_dwordx4 v[20:23], v87, s[6:7] offset:112
	global_load_dwordx4 v[24:27], v87, s[6:7] offset:96
	global_load_dwordx4 v[28:31], v87, s[6:7] offset:80
	global_load_dwordx4 v[32:35], v87, s[6:7] offset:64
	v_mul_f32_e32 v0, v86, v55
	s_waitcnt vmcnt(0)
	v_mul_f32_e32 v0, v0, v32
	v_cvt_pk_bf16_f32 v0, v0, s0
	ds_write_b16 v88, v0 offset:4352
	v_mul_f32_e32 v0, v86, v56
	v_mul_f32_e32 v0, v0, v33
	v_cvt_pk_bf16_f32 v0, v0, s0
	ds_write_b16 v39, v0 offset:4624
	v_mul_f32_e32 v0, v86, v57
	v_mul_f32_e32 v0, v0, v34
	v_cvt_pk_bf16_f32 v0, v0, s0
	ds_write_b16 v88, v0 offset:4896
	v_mul_f32_e32 v0, v86, v58
	v_mul_f32_e32 v0, v0, v35
	v_cvt_pk_bf16_f32 v0, v0, s0
	ds_write_b16 v39, v0 offset:5168
	v_mul_f32_e32 v0, v86, v59
	v_mul_f32_e32 v0, v0, v28
	v_cvt_pk_bf16_f32 v0, v0, s0
	ds_write_b16 v88, v0 offset:5440
	v_mul_f32_e32 v0, v86, v60
	v_mul_f32_e32 v0, v0, v29
	v_cvt_pk_bf16_f32 v0, v0, s0
	ds_write_b16 v39, v0 offset:5712
	v_mul_f32_e32 v0, v86, v61
	v_mul_f32_e32 v0, v0, v30
	v_cvt_pk_bf16_f32 v0, v0, s0
	ds_write_b16 v88, v0 offset:5984
	v_mul_f32_e32 v0, v86, v62
	v_mul_f32_e32 v0, v0, v31
	v_cvt_pk_bf16_f32 v0, v0, s0
	ds_write_b16 v39, v0 offset:6256
	v_mul_f32_e32 v0, v86, v63
	v_mul_f32_e32 v0, v0, v24
	v_cvt_pk_bf16_f32 v0, v0, s0
	ds_write_b16 v88, v0 offset:6528
	v_mul_f32_e32 v0, v86, v64
	v_mul_f32_e32 v0, v0, v25
	v_cvt_pk_bf16_f32 v0, v0, s0
	ds_write_b16 v39, v0 offset:6800
	v_mul_f32_e32 v0, v86, v65
	v_mul_f32_e32 v0, v0, v26
	v_cvt_pk_bf16_f32 v0, v0, s0
	ds_write_b16 v88, v0 offset:7072
	v_mul_f32_e32 v0, v86, v68
	v_mul_f32_e32 v0, v0, v27
	v_cvt_pk_bf16_f32 v0, v0, s0
	ds_write_b16 v39, v0 offset:7344
	v_mul_f32_e32 v0, v86, v69
	v_mul_f32_e32 v0, v0, v20
	v_cvt_pk_bf16_f32 v0, v0, s0
	ds_write_b16 v88, v0 offset:7616
	v_mul_f32_e32 v0, v86, v70
	v_mul_f32_e32 v0, v0, v21
	v_cvt_pk_bf16_f32 v0, v0, s0
	ds_write_b16 v39, v0 offset:7888
	v_mul_f32_e32 v0, v86, v72
	v_mul_f32_e32 v0, v0, v22
	v_cvt_pk_bf16_f32 v0, v0, s0
	ds_write_b16 v88, v0 offset:8160
	v_mul_f32_e32 v0, v86, v73
	v_mul_f32_e32 v0, v0, v23
	v_cvt_pk_bf16_f32 v0, v0, s0
	ds_write_b16 v39, v0 offset:8432
	global_load_dwordx4 v[20:23], v87, s[6:7] offset:176
	global_load_dwordx4 v[24:27], v87, s[6:7] offset:160
	global_load_dwordx4 v[28:31], v87, s[6:7] offset:144
	global_load_dwordx4 v[32:35], v87, s[6:7] offset:128
	v_mul_f32_e32 v0, v86, v74
	s_waitcnt vmcnt(0)
; __device__ __forceinline__ float lo_bf(unsigned u) { return __uint_as_float(u << 16); }
; __device__ __forceinline__ float hi_bf(unsigned u) { return __uint_as_float(u & 0xffff0000u); }
; __device__ __forceinline__ void cmlp_item(const Params& p, int j, int rt, int g, const u16* __restrict__ ZB, u16* sVT) {
;     ...
; #pragma unroll
;     for (int i = 0; i < 8; ++i) {
;       unsigned w[4] = {raw[i].x, raw[i].y, raw[i].z, raw[i].w};
; #pragma unroll
;       for (int k = 0; k < 4; ++k) {
;         int d = i * 8 + k * 2;
;         sVT[(half * 64 + d) * 136 + q] = f2bf(lo_bf(w[k]) * rstd * vn[d]);
;         sVT[(half * 64 + d + 1) * 136 + q] = f2bf(hi_bf(w[k]) * rstd * vn[d + 1]);
;       }
;     }
;   }
;   __syncthreads();
	v_mul_f32_e32 v0, v0, v32
	v_cvt_pk_bf16_f32 v0, v0, s0
	ds_write_b16 v88, v0 offset:8704
	v_mul_f32_e32 v0, v86, v75
	v_mul_f32_e32 v0, v0, v33
	v_cvt_pk_bf16_f32 v0, v0, s0
	ds_write_b16 v39, v0 offset:8976
	v_mul_f32_e32 v0, v86, v76
	v_mul_f32_e32 v0, v0, v34
	v_cvt_pk_bf16_f32 v0, v0, s0
	ds_write_b16 v88, v0 offset:9248
	v_mul_f32_e32 v0, v86, v77
	v_mul_f32_e32 v0, v0, v35
	v_cvt_pk_bf16_f32 v0, v0, s0
	ds_write_b16 v39, v0 offset:9520
	v_mul_f32_e32 v0, v86, v78
	v_mul_f32_e32 v0, v0, v28
	v_cvt_pk_bf16_f32 v0, v0, s0
	ds_write_b16 v88, v0 offset:9792
	v_mul_f32_e32 v0, v86, v79
	v_mul_f32_e32 v0, v0, v29
	v_cvt_pk_bf16_f32 v0, v0, s0
	ds_write_b16 v39, v0 offset:10064
	v_mul_f32_e32 v0, v86, v80
	v_mul_f32_e32 v0, v0, v30
	v_cvt_pk_bf16_f32 v0, v0, s0
	ds_write_b16 v88, v0 offset:10336
	v_mul_f32_e32 v0, v86, v81
	v_mul_f32_e32 v0, v0, v31
	v_cvt_pk_bf16_f32 v0, v0, s0
	ds_write_b16 v39, v0 offset:10608
	v_mul_f32_e32 v0, v86, v82
	v_mul_f32_e32 v0, v0, v24
	v_cvt_pk_bf16_f32 v0, v0, s0
	ds_write_b16 v88, v0 offset:10880
	v_mul_f32_e32 v0, v86, v83
	v_mul_f32_e32 v0, v0, v25
	v_cvt_pk_bf16_f32 v0, v0, s0
	ds_write_b16 v39, v0 offset:11152
	v_mul_f32_e32 v0, v86, v84
	v_mul_f32_e32 v0, v0, v26
	v_cvt_pk_bf16_f32 v0, v0, s0
	ds_write_b16 v88, v0 offset:11424
	v_mul_f32_e32 v0, v86, v85
	v_mul_f32_e32 v0, v0, v27
	v_cvt_pk_bf16_f32 v0, v0, s0
	ds_write_b16 v39, v0 offset:11696
	v_mul_f32_e32 v0, v86, v36
	v_mul_f32_e32 v0, v0, v20
	v_cvt_pk_bf16_f32 v0, v0, s0
	ds_write_b16 v88, v0 offset:11968
	v_mul_f32_e32 v0, v86, v18
	v_mul_f32_e32 v0, v0, v21
	v_cvt_pk_bf16_f32 v0, v0, s0
	ds_write_b16 v39, v0 offset:12240
	v_mul_f32_e32 v0, v86, v37
	v_mul_f32_e32 v0, v0, v22
	v_cvt_pk_bf16_f32 v0, v0, s0
	ds_write_b16 v88, v0 offset:12512
	v_mul_f32_e32 v0, v86, v19
	v_mul_f32_e32 v0, v0, v23
	v_cvt_pk_bf16_f32 v0, v0, s0
	ds_write_b16 v39, v0 offset:12784
	global_load_dwordx4 v[18:21], v87, s[6:7] offset:240
	global_load_dwordx4 v[22:25], v87, s[6:7] offset:224
	global_load_dwordx4 v[26:29], v87, s[6:7] offset:208
	global_load_dwordx4 v[30:33], v87, s[6:7] offset:192
	v_mul_f32_e32 v0, v86, v16
	s_lshl_b32 s6, s10, 16
	s_add_u32 s6, s46, s6
	s_addc_u32 s7, s47, 0
	s_waitcnt vmcnt(0)
	v_mul_f32_e32 v0, v0, v30
	v_cvt_pk_bf16_f32 v0, v0, s0
	ds_write_b16 v88, v0 offset:13056
	v_mul_f32_e32 v0, v86, v14
	v_mul_f32_e32 v0, v0, v31
	v_cvt_pk_bf16_f32 v0, v0, s0
	ds_write_b16 v39, v0 offset:13328
	v_mul_f32_e32 v0, v86, v17
	v_mul_f32_e32 v0, v0, v32
	v_cvt_pk_bf16_f32 v0, v0, s0
	ds_write_b16 v88, v0 offset:13600
	v_mul_f32_e32 v0, v86, v15
	v_mul_f32_e32 v0, v0, v33
	v_cvt_pk_bf16_f32 v0, v0, s0
	ds_write_b16 v39, v0 offset:13872
	v_mul_f32_e32 v0, v86, v12
	v_mul_f32_e32 v0, v0, v26
	v_cvt_pk_bf16_f32 v0, v0, s0
	ds_write_b16 v88, v0 offset:14144
	v_mul_f32_e32 v0, v86, v10
	v_mul_f32_e32 v0, v0, v27
	v_cvt_pk_bf16_f32 v0, v0, s0
	ds_write_b16 v39, v0 offset:14416
	v_mul_f32_e32 v0, v86, v13
	v_mul_f32_e32 v0, v0, v28
	v_cvt_pk_bf16_f32 v0, v0, s0
	ds_write_b16 v88, v0 offset:14688
	v_mul_f32_e32 v0, v86, v11
	v_mul_f32_e32 v0, v0, v29
	v_cvt_pk_bf16_f32 v0, v0, s0
	ds_write_b16 v39, v0 offset:14960
	v_mul_f32_e32 v0, v86, v8
	v_mul_f32_e32 v0, v0, v22
	v_cvt_pk_bf16_f32 v0, v0, s0
	ds_write_b16 v88, v0 offset:15232
	v_mul_f32_e32 v0, v86, v6
	v_mul_f32_e32 v0, v0, v23
	v_cvt_pk_bf16_f32 v0, v0, s0
	ds_write_b16 v39, v0 offset:15504
	v_mul_f32_e32 v0, v86, v9
	v_mul_f32_e32 v0, v0, v24
	v_cvt_pk_bf16_f32 v0, v0, s0
	ds_write_b16 v88, v0 offset:15776
	v_mul_f32_e32 v0, v86, v7
	v_mul_f32_e32 v0, v0, v25
	v_cvt_pk_bf16_f32 v0, v0, s0
	ds_write_b16 v39, v0 offset:16048
	v_mul_f32_e32 v0, v86, v4
	v_mul_f32_e32 v0, v0, v18
	v_cvt_pk_bf16_f32 v0, v0, s0
	ds_write_b16 v88, v0 offset:16320
	v_mul_f32_e32 v0, v86, v2
	v_mul_f32_e32 v0, v0, v19
	v_cvt_pk_bf16_f32 v0, v0, s0
	ds_write_b16 v39, v0 offset:16592
	v_mul_f32_e32 v0, v86, v5
	v_mul_f32_e32 v0, v0, v20
	v_cvt_pk_bf16_f32 v0, v0, s0
	v_bfe_u32 v4, v38, 4, 2
	ds_write_b16 v88, v0 offset:16864
	v_mul_f32_e32 v0, v86, v3
	v_lshlrev_b32_e32 v2, 5, v4
	v_mov_b32_e32 v3, v1
	v_lshl_add_u64 v[8:9], s[6:7], 0, v[2:3]
	v_lshlrev_b32_e32 v2, 9, v67
	v_mul_f32_e32 v0, v0, v21
	v_lshl_or_b32 v16, v66, 14, v2
	v_mov_b32_e32 v17, v1
	v_cvt_pk_bf16_f32 v0, v0, s0
	v_lshl_add_u64 v[10:11], v[8:9], 0, v[16:17]
	ds_write_b16 v39, v0 offset:17136
	s_waitcnt lgkmcnt(0)
	s_barrier
; __device__ __forceinline__ void cmlp_item(const Params& p, int j, int rt, int g, const u16* __restrict__ ZB, u16* sVT) {
;     ...
;   const float* wsb = p.cmlp_ws + (size_t)(j * 4 + g) * 128 * 128;
; #pragma unroll
;   for (int ks = 0; ks < 4; ++ks) {
;     bf16x8 wf[2];
; #pragma unroll
;     for (int pb = 0; pb < 2; ++pb) {
;       const float* wp = wsb + (size_t)(wave * 32 + pb * 16 + fr) * 128 + ks * 32 + fq * 8;
;       float4 a = *(const float4*)wp, b = *(const float4*)(wp + 4);
;       wf[pb] = mk8(pack2(a.x, a.y), pack2(a.z, a.w), pack2(b.x, b.y), pack2(b.z, b.w));
;     }
; #pragma unroll
;     for (int db = 0; db < 8; ++db) {
;       bf16x8 vf = *(const bf16x8*)(sVT + (db * 16 + fr) * 136 + ks * 32 + fq * 8);
; #pragma unroll
;       for (int pb = 0; pb < 2; ++pb) acc[pb][db] = mfma16(vf, wf[pb], acc[pb][db]);
;     }
;   }
	v_lshlrev_b32_e32 v0, 3, v4
	v_lshlrev_b32_e32 v18, 4, v4
	global_load_dwordx4 v[4:7], v[10:11], off offset:16
	global_load_dwordx4 v[12:15], v[10:11], off
	s_add_u32 s6, s92, s34
	s_addc_u32 s7, s93, 0
	s_add_i32 s8, s8, s87
	s_add_i32 s1, s1, s11
	s_add_i32 s0, s0, s86
	s_cmpk_gt_i32 s8, 0x47f
	s_waitcnt vmcnt(1)
	v_cvt_pk_bf16_f32 v4, v4, v5
	v_cvt_pk_bf16_f32 v5, v6, v7
	v_or_b32_e32 v6, 0x2000, v16
	v_mov_b32_e32 v7, v1
	s_waitcnt vmcnt(0)
	v_cvt_pk_bf16_f32 v2, v12, v13
	v_lshl_add_u64 v[12:13], v[8:9], 0, v[6:7]
	v_cvt_pk_bf16_f32 v3, v14, v15
	global_load_dwordx4 v[14:17], v[12:13], off offset:16
	global_load_dwordx4 v[6:9], v[12:13], off
	s_waitcnt vmcnt(0)
	v_cvt_pk_bf16_f32 v6, v6, v7
	v_cvt_pk_bf16_f32 v7, v8, v9
	v_cvt_pk_bf16_f32 v8, v14, v15
	v_mul_u32_u24_e32 v14, 0x88, v67
	v_lshlrev_b32_e32 v14, 1, v14
	v_add3_u32 v34, s58, v18, v14
	v_cvt_pk_bf16_f32 v9, v16, v17
	ds_read_b128 v[14:17], v34
	ds_read_b128 v[22:25], v34 offset:4352
	ds_read_b128 v[30:33], v34 offset:8704
	ds_read_b128 v[40:43], v34 offset:13056
	ds_read_b128 v[48:51], v34 offset:17408
	ds_read_b128 v[56:59], v34 offset:21760
	ds_read_b128 v[72:75], v34 offset:26112
	ds_read_b128 v[80:83], v34 offset:30464
	s_waitcnt lgkmcnt(7)
	v_mfma_f32_16x16x32_bf16 v[18:21], v[14:17], v[2:5], 0
	v_mfma_f32_16x16x32_bf16 v[14:17], v[14:17], v[6:9], 0
	s_waitcnt lgkmcnt(6)
	v_mfma_f32_16x16x32_bf16 v[26:29], v[22:25], v[2:5], 0
	v_mfma_f32_16x16x32_bf16 v[22:25], v[22:25], v[6:9], 0
	s_waitcnt lgkmcnt(5)
	v_mfma_f32_16x16x32_bf16 v[36:39], v[30:33], v[2:5], 0
	v_mfma_f32_16x16x32_bf16 v[30:33], v[30:33], v[6:9], 0
	s_waitcnt lgkmcnt(4)
	v_mfma_f32_16x16x32_bf16 v[44:47], v[40:43], v[2:5], 0
	v_mfma_f32_16x16x32_bf16 v[40:43], v[40:43], v[6:9], 0
	s_waitcnt lgkmcnt(3)
	v_mfma_f32_16x16x32_bf16 v[52:55], v[48:51], v[2:5], 0
	v_mfma_f32_16x16x32_bf16 v[48:51], v[48:51], v[6:9], 0
	s_waitcnt lgkmcnt(2)
	v_mfma_f32_16x16x32_bf16 v[60:63], v[56:59], v[2:5], 0
	v_mfma_f32_16x16x32_bf16 v[56:59], v[56:59], v[6:9], 0
	s_waitcnt lgkmcnt(1)
	v_mfma_f32_16x16x32_bf16 v[76:79], v[72:75], v[2:5], 0
	v_mfma_f32_16x16x32_bf16 v[72:75], v[72:75], v[6:9], 0
	s_waitcnt lgkmcnt(0)
	v_mfma_f32_16x16x32_bf16 v[2:5], v[80:83], v[2:5], 0
	v_mfma_f32_16x16x32_bf16 v[6:9], v[80:83], v[6:9], 0
	global_load_dwordx4 v[80:83], v[10:11], off offset:144
	global_load_dwordx4 v[84:87], v[10:11], off offset:128
	s_waitcnt vmcnt(0)
	v_cvt_pk_bf16_f32 v84, v84, v85
	v_cvt_pk_bf16_f32 v85, v86, v87
	v_cvt_pk_bf16_f32 v86, v80, v81
	v_cvt_pk_bf16_f32 v87, v82, v83
	global_load_dwordx4 v[80:83], v[12:13], off offset:144
	global_load_dwordx4 v[88:91], v[12:13], off offset:128
	s_waitcnt vmcnt(0)
	v_cvt_pk_bf16_f32 v88, v88, v89
	v_cvt_pk_bf16_f32 v89, v90, v91
	v_cvt_pk_bf16_f32 v90, v80, v81
	v_cvt_pk_bf16_f32 v91, v82, v83
	ds_read_b128 v[80:83], v34 offset:64
	s_waitcnt lgkmcnt(0)
	v_mfma_f32_16x16x32_bf16 v[18:21], v[80:83], v[84:87], v[18:21]
	v_mfma_f32_16x16x32_bf16 v[14:17], v[80:83], v[88:91], v[14:17]
	ds_read_b128 v[80:83], v34 offset:4416
	s_waitcnt lgkmcnt(0)
	v_mfma_f32_16x16x32_bf16 v[26:29], v[80:83], v[84:87], v[26:29]
	v_mfma_f32_16x16x32_bf16 v[22:25], v[80:83], v[88:91], v[22:25]
	ds_read_b128 v[80:83], v34 offset:8768
	s_waitcnt lgkmcnt(0)
	v_mfma_f32_16x16x32_bf16 v[36:39], v[80:83], v[84:87], v[36:39]
	v_mfma_f32_16x16x32_bf16 v[30:33], v[80:83], v[88:91], v[30:33]
	ds_read_b128 v[80:83], v34 offset:13120
	s_waitcnt lgkmcnt(0)
	v_mfma_f32_16x16x32_bf16 v[44:47], v[80:83], v[84:87], v[44:47]
	v_mfma_f32_16x16x32_bf16 v[40:43], v[80:83], v[88:91], v[40:43]
	ds_read_b128 v[80:83], v34 offset:17472
	s_waitcnt lgkmcnt(0)
	v_mfma_f32_16x16x32_bf16 v[52:55], v[80:83], v[84:87], v[52:55]
	v_mfma_f32_16x16x32_bf16 v[48:51], v[80:83], v[88:91], v[48:51]
	ds_read_b128 v[80:83], v34 offset:21824
	s_waitcnt lgkmcnt(0)
	v_mfma_f32_16x16x32_bf16 v[60:63], v[80:83], v[84:87], v[60:63]
	v_mfma_f32_16x16x32_bf16 v[56:59], v[80:83], v[88:91], v[56:59]
	ds_read_b128 v[80:83], v34 offset:26176
	s_waitcnt lgkmcnt(0)
	v_mfma_f32_16x16x32_bf16 v[76:79], v[80:83], v[84:87], v[76:79]
	v_mfma_f32_16x16x32_bf16 v[72:75], v[80:83], v[88:91], v[72:75]
	ds_read_b128 v[80:83], v34 offset:30528
	s_waitcnt lgkmcnt(0)
	v_mfma_f32_16x16x32_bf16 v[2:5], v[80:83], v[84:87], v[2:5]
	v_mfma_f32_16x16x32_bf16 v[6:9], v[80:83], v[88:91], v[6:9]
	global_load_dwordx4 v[80:83], v[10:11], off offset:272
	global_load_dwordx4 v[84:87], v[10:11], off offset:256
	s_waitcnt vmcnt(0)
	v_cvt_pk_bf16_f32 v84, v84, v85
	v_cvt_pk_bf16_f32 v85, v86, v87
	v_cvt_pk_bf16_f32 v86, v80, v81
	v_cvt_pk_bf16_f32 v87, v82, v83
	global_load_dwordx4 v[80:83], v[12:13], off offset:272
	global_load_dwordx4 v[88:91], v[12:13], off offset:256
	s_waitcnt vmcnt(0)
	v_cvt_pk_bf16_f32 v88, v88, v89
	v_cvt_pk_bf16_f32 v89, v90, v91
	v_cvt_pk_bf16_f32 v90, v80, v81
	v_cvt_pk_bf16_f32 v91, v82, v83
	ds_read_b128 v[80:83], v34 offset:128
	s_waitcnt lgkmcnt(0)
	v_mfma_f32_16x16x32_bf16 v[18:21], v[80:83], v[84:87], v[18:21]
	v_mfma_f32_16x16x32_bf16 v[14:17], v[80:83], v[88:91], v[14:17]
	ds_read_b128 v[80:83], v34 offset:4480
	s_waitcnt lgkmcnt(0)
	v_mfma_f32_16x16x32_bf16 v[26:29], v[80:83], v[84:87], v[26:29]
	v_mfma_f32_16x16x32_bf16 v[22:25], v[80:83], v[88:91], v[22:25]
	ds_read_b128 v[80:83], v34 offset:8832
	s_waitcnt lgkmcnt(0)
	v_mfma_f32_16x16x32_bf16 v[36:39], v[80:83], v[84:87], v[36:39]
	v_mfma_f32_16x16x32_bf16 v[80:83], v[80:83], v[88:91], v[30:33]
	s_nop 2
	ds_read_b128 v[30:33], v34 offset:13184
	s_waitcnt lgkmcnt(0)
	v_mfma_f32_16x16x32_bf16 v[44:47], v[30:33], v[84:87], v[44:47]
	v_mfma_f32_16x16x32_bf16 v[40:43], v[30:33], v[88:91], v[40:43]
	ds_read_b128 v[30:33], v34 offset:17536
	s_waitcnt lgkmcnt(0)
; __device__ __forceinline__ float lo_bf(unsigned u) { return __uint_as_float(u << 16); }
; __device__ __forceinline__ float hi_bf(unsigned u) { return __uint_as_float(u & 0xffff0000u); }
; __device__ __forceinline__ void cmlp_item(const Params& p, int j, int rt, int g, const u16* __restrict__ ZB, u16* sVT) {
;     ...
; #pragma unroll
;     for (int db = 0; db < 8; ++db) {
;       bf16x8 vf = *(const bf16x8*)(sVT + (db * 16 + fr) * 136 + ks * 32 + fq * 8);
; #pragma unroll
;       for (int pb = 0; pb < 2; ++pb) acc[pb][db] = mfma16(vf, wf[pb], acc[pb][db]);
;     }
;   }
; #pragma unroll
;   for (int pb = 0; pb < 2; ++pb) {
;     const int pp = wave * 32 + pb * 16 + fr;
;     const float bias = p.cmlp_bs[(j * 4 + g) * 128 + pp];
; #pragma unroll
;     for (int db = 0; db < 8; ++db) {
;       const int d = db * 16 + fq * 4;
;       uint2 uu = *(const uint2*)(ZB + (size_t)(m0 + pp) * 1024 + g * 128 + d);
;       f32x4 r;
;       r[0] = lo_bf(uu.x) * (acc[pb][db][0] + bias);
;       r[1] = hi_bf(uu.x) * (acc[pb][db][1] + bias);
;       r[2] = lo_bf(uu.y) * (acc[pb][db][2] + bias);
;       r[3] = hi_bf(uu.y) * (acc[pb][db][3] + bias);
;       store4bf(p.XN + (size_t)(m0 + pp) * 1024 + 512 + g * 128 + d, r);
;     }
	v_mfma_f32_16x16x32_bf16 v[92:95], v[30:33], v[84:87], v[52:55]
	v_mfma_f32_16x16x32_bf16 v[96:99], v[30:33], v[88:91], v[48:51]
	ds_read_b128 v[30:33], v34 offset:21888
	s_waitcnt lgkmcnt(0)
	v_mfma_f32_16x16x32_bf16 v[100:103], v[30:33], v[84:87], v[60:63]
	v_mfma_f32_16x16x32_bf16 v[104:107], v[30:33], v[88:91], v[56:59]
	ds_read_b128 v[30:33], v34 offset:26240
	s_waitcnt lgkmcnt(0)
	v_mfma_f32_16x16x32_bf16 v[76:79], v[30:33], v[84:87], v[76:79]
	v_mfma_f32_16x16x32_bf16 v[72:75], v[30:33], v[88:91], v[72:75]
	ds_read_b128 v[30:33], v34 offset:30592
	s_waitcnt lgkmcnt(0)
	v_mfma_f32_16x16x32_bf16 v[2:5], v[30:33], v[84:87], v[2:5]
	v_mfma_f32_16x16x32_bf16 v[84:87], v[30:33], v[88:91], v[6:9]
	s_nop 2
	global_load_dwordx4 v[6:9], v[10:11], off offset:400
	global_load_dwordx4 v[30:33], v[10:11], off offset:384
	s_waitcnt vmcnt(1)
	v_cvt_pk_bf16_f32 v90, v6, v7
	v_cvt_pk_bf16_f32 v91, v8, v9
	global_load_dwordx4 v[6:9], v[12:13], off offset:400
	s_nop 0
	global_load_dwordx4 v[10:13], v[12:13], off offset:384
	s_waitcnt vmcnt(2)
	v_cvt_pk_bf16_f32 v88, v30, v31
	v_cvt_pk_bf16_f32 v89, v32, v33
	s_waitcnt vmcnt(1)
	v_cvt_pk_bf16_f32 v110, v6, v7
	v_cvt_pk_bf16_f32 v111, v8, v9
	ds_read_b128 v[6:9], v34 offset:192
	s_waitcnt vmcnt(0)
	v_cvt_pk_bf16_f32 v108, v10, v11
	v_cvt_pk_bf16_f32 v109, v12, v13
	s_waitcnt lgkmcnt(0)
	v_mfma_f32_16x16x32_bf16 v[62:65], v[6:9], v[88:91], v[18:21]
	v_mfma_f32_16x16x32_bf16 v[30:33], v[6:9], v[108:111], v[14:17]
	ds_read_b128 v[6:9], v34 offset:4544
	s_waitcnt lgkmcnt(0)
	v_mfma_f32_16x16x32_bf16 v[58:61], v[6:9], v[88:91], v[26:29]
	v_mfma_f32_16x16x32_bf16 v[26:29], v[6:9], v[108:111], v[22:25]
	ds_read_b128 v[6:9], v34 offset:8896
	s_waitcnt lgkmcnt(0)
	v_mfma_f32_16x16x32_bf16 v[54:57], v[6:9], v[88:91], v[36:39]
	v_mfma_f32_16x16x32_bf16 v[22:25], v[6:9], v[108:111], v[80:83]
	ds_read_b128 v[6:9], v34 offset:13248
	s_waitcnt lgkmcnt(0)
	v_mfma_f32_16x16x32_bf16 v[50:53], v[6:9], v[88:91], v[44:47]
	v_mfma_f32_16x16x32_bf16 v[18:21], v[6:9], v[108:111], v[40:43]
	ds_read_b128 v[6:9], v34 offset:17600
	s_waitcnt lgkmcnt(0)
	v_mfma_f32_16x16x32_bf16 v[46:49], v[6:9], v[88:91], v[92:95]
	v_mfma_f32_16x16x32_bf16 v[14:17], v[6:9], v[108:111], v[96:99]
	ds_read_b128 v[6:9], v34 offset:21952
	s_waitcnt lgkmcnt(0)
	v_mfma_f32_16x16x32_bf16 v[42:45], v[6:9], v[88:91], v[100:103]
	v_mfma_f32_16x16x32_bf16 v[10:13], v[6:9], v[108:111], v[104:107]
	ds_read_b128 v[6:9], v34 offset:26304
	s_waitcnt lgkmcnt(0)
	v_mfma_f32_16x16x32_bf16 v[38:41], v[6:9], v[88:91], v[76:79]
	v_mfma_f32_16x16x32_bf16 v[6:9], v[6:9], v[108:111], v[72:75]
	s_nop 2
	ds_read_b128 v[72:75], v34 offset:30656
	s_waitcnt lgkmcnt(0)
	v_mfma_f32_16x16x32_bf16 v[34:37], v[72:75], v[88:91], v[2:5]
	v_mfma_f32_16x16x32_bf16 v[2:5], v[72:75], v[108:111], v[84:87]
	v_lshl_or_b32 v72, v66, 5, v67
	v_lshl_or_b32 v66, s10, 7, v72
	v_mov_b32_e32 v67, v1
	v_lshl_add_u64 v[68:69], v[66:67], 2, s[48:49]
	v_or_b32_e32 v66, s9, v72
	v_ashrrev_i32_e32 v67, 31, v66
	v_lshlrev_b64 v[76:77], 11, v[66:67]
	v_lshl_add_u64 v[72:73], s[6:7], 0, v[76:77]
	v_lshl_add_u64 v[72:73], v[72:73], 0, v[0:1]
	global_load_dword v70, v[68:69], off
	global_load_dwordx2 v[78:79], v[72:73], off
	global_load_dword v112, v[68:69], off offset:64
	global_load_dwordx2 v[114:115], v[72:73], off offset:32
	global_load_dwordx2 v[116:117], v[72:73], off offset:64
	global_load_dwordx2 v[118:119], v[72:73], off offset:96
	global_load_dwordx2 v[120:121], v[72:73], off offset:128
	global_load_dwordx2 v[122:123], v[72:73], off offset:160
	global_load_dwordx2 v[124:125], v[72:73], off offset:192
	global_load_dwordx2 v[126:127], v[72:73], off offset:224
	v_or_b32_e32 v144, 16, v66
	v_ashrrev_i32_e32 v145, 31, v144
	v_lshlrev_b64 v[144:145], 11, v[144:145]
	v_lshl_add_u64 v[144:145], s[6:7], 0, v[144:145]
	v_lshl_add_u64 v[144:145], v[144:145], 0, v[0:1]
	global_load_dwordx2 v[128:129], v[144:145], off
	global_load_dwordx2 v[130:131], v[144:145], off offset:32
	global_load_dwordx2 v[132:133], v[144:145], off offset:64
	global_load_dwordx2 v[134:135], v[144:145], off offset:96
	global_load_dwordx2 v[136:137], v[144:145], off offset:128
	global_load_dwordx2 v[138:139], v[144:145], off offset:160
	global_load_dwordx2 v[140:141], v[144:145], off offset:192
	global_load_dwordx2 v[142:143], v[144:145], off offset:224
	s_waitcnt vmcnt(0)
; __device__ __forceinline__ float lo_bf(unsigned u) { return __uint_as_float(u << 16); }
; __device__ __forceinline__ float hi_bf(unsigned u) { return __uint_as_float(u & 0xffff0000u); }
; __device__ __forceinline__ void cmlp_item(const Params& p, int j, int rt, int g, const u16* __restrict__ ZB, u16* sVT) {
;     ...
; #pragma unroll
;   for (int pb = 0; pb < 2; ++pb) {
;     const int pp = wave * 32 + pb * 16 + fr;
;     const float bias = p.cmlp_bs[(j * 4 + g) * 128 + pp];
; #pragma unroll
;     for (int db = 0; db < 8; ++db) {
;       const int d = db * 16 + fq * 4;
;       uint2 uu = *(const uint2*)(ZB + (size_t)(m0 + pp) * 1024 + g * 128 + d);
;       f32x4 r;
;       r[0] = lo_bf(uu.x) * (acc[pb][db][0] + bias);
;       r[1] = hi_bf(uu.x) * (acc[pb][db][1] + bias);
;       r[2] = lo_bf(uu.y) * (acc[pb][db][2] + bias);
;       r[3] = hi_bf(uu.y) * (acc[pb][db][3] + bias);
;       store4bf(p.XN + (size_t)(m0 + pp) * 1024 + 512 + g * 128 + d, r);
;     }
	v_pk_add_f32 v[62:63], v[62:63], v[70:71] op_sel_hi:[1,0]
	v_lshlrev_b32_e32 v74, 16, v78
	v_and_b32_e32 v75, 0xffff0000, v78
	v_pk_mul_f32 v[74:75], v[62:63], v[74:75]
	v_lshlrev_b32_e32 v62, 16, v79
	v_and_b32_e32 v63, 0xffff0000, v79
	v_pk_add_f32 v[64:65], v[64:65], v[70:71] op_sel_hi:[1,0]
	v_cvt_pk_bf16_f32 v74, v74, v75
	v_pk_mul_f32 v[64:65], v[64:65], v[62:63]
	v_lshl_add_u64 v[62:63], s[42:43], 0, v[76:77]
	v_lshl_add_u64 v[62:63], v[62:63], 0, s[34:35]
	v_lshl_add_u64 v[62:63], v[62:63], 0, v[0:1]
	v_cvt_pk_bf16_f32 v75, v64, v65
	global_store_dwordx2 v[62:63], v[74:75], off offset:1024
	v_mov_b32_e32 v64, v114
	v_mov_b32_e32 v65, v115
	v_pk_add_f32 v[58:59], v[58:59], v[70:71] op_sel_hi:[1,0]
	v_pk_add_f32 v[60:61], v[60:61], v[70:71] op_sel_hi:[1,0]
	v_pk_add_f32 v[54:55], v[54:55], v[70:71] op_sel_hi:[1,0]
	v_pk_add_f32 v[56:57], v[56:57], v[70:71] op_sel_hi:[1,0]
	v_pk_add_f32 v[50:51], v[50:51], v[70:71] op_sel_hi:[1,0]
	v_pk_add_f32 v[52:53], v[52:53], v[70:71] op_sel_hi:[1,0]
	v_pk_add_f32 v[46:47], v[46:47], v[70:71] op_sel_hi:[1,0]
	v_pk_add_f32 v[48:49], v[48:49], v[70:71] op_sel_hi:[1,0]
	v_pk_add_f32 v[42:43], v[42:43], v[70:71] op_sel_hi:[1,0]
	v_pk_add_f32 v[44:45], v[44:45], v[70:71] op_sel_hi:[1,0]
	v_pk_add_f32 v[38:39], v[38:39], v[70:71] op_sel_hi:[1,0]
	v_pk_add_f32 v[40:41], v[40:41], v[70:71] op_sel_hi:[1,0]
	v_pk_add_f32 v[34:35], v[34:35], v[70:71] op_sel_hi:[1,0]
	v_pk_add_f32 v[36:37], v[36:37], v[70:71] op_sel_hi:[1,0]
	v_lshlrev_b32_e32 v74, 16, v64
	v_and_b32_e32 v75, 0xffff0000, v64
	v_lshlrev_b32_e32 v64, 16, v65
	v_and_b32_e32 v65, 0xffff0000, v65
	v_pk_mul_f32 v[58:59], v[58:59], v[74:75]
	v_pk_mul_f32 v[60:61], v[60:61], v[64:65]
	v_cvt_pk_bf16_f32 v58, v58, v59
	v_cvt_pk_bf16_f32 v59, v60, v61
	global_store_dwordx2 v[62:63], v[58:59], off offset:1056
	v_mov_b32_e32 v58, v116
	v_mov_b32_e32 v59, v117
	v_lshlrev_b32_e32 v60, 16, v58
	v_and_b32_e32 v61, 0xffff0000, v58
	v_lshlrev_b32_e32 v58, 16, v59
	v_and_b32_e32 v59, 0xffff0000, v59
	v_pk_mul_f32 v[54:55], v[54:55], v[60:61]
	v_pk_mul_f32 v[56:57], v[56:57], v[58:59]
	v_cvt_pk_bf16_f32 v54, v54, v55
	v_cvt_pk_bf16_f32 v55, v56, v57
	global_store_dwordx2 v[62:63], v[54:55], off offset:1088
	v_mov_b32_e32 v54, v118
	v_mov_b32_e32 v55, v119
	v_lshlrev_b32_e32 v56, 16, v54
	v_and_b32_e32 v57, 0xffff0000, v54
	v_lshlrev_b32_e32 v54, 16, v55
	v_and_b32_e32 v55, 0xffff0000, v55
	v_pk_mul_f32 v[50:51], v[50:51], v[56:57]
	v_pk_mul_f32 v[52:53], v[52:53], v[54:55]
	v_cvt_pk_bf16_f32 v50, v50, v51
	v_cvt_pk_bf16_f32 v51, v52, v53
	global_store_dwordx2 v[62:63], v[50:51], off offset:1120
	v_mov_b32_e32 v50, v120
	v_mov_b32_e32 v51, v121
	v_lshlrev_b32_e32 v52, 16, v50
	v_and_b32_e32 v53, 0xffff0000, v50
	v_lshlrev_b32_e32 v50, 16, v51
	v_and_b32_e32 v51, 0xffff0000, v51
	v_pk_mul_f32 v[46:47], v[46:47], v[52:53]
	v_pk_mul_f32 v[48:49], v[48:49], v[50:51]
	v_cvt_pk_bf16_f32 v46, v46, v47
	v_cvt_pk_bf16_f32 v47, v48, v49
	global_store_dwordx2 v[62:63], v[46:47], off offset:1152
	v_mov_b32_e32 v46, v122
	v_mov_b32_e32 v47, v123
	v_lshlrev_b32_e32 v48, 16, v46
	v_and_b32_e32 v49, 0xffff0000, v46
	v_lshlrev_b32_e32 v46, 16, v47
	v_and_b32_e32 v47, 0xffff0000, v47
	v_pk_mul_f32 v[42:43], v[42:43], v[48:49]
	v_pk_mul_f32 v[44:45], v[44:45], v[46:47]
	v_cvt_pk_bf16_f32 v42, v42, v43
	v_cvt_pk_bf16_f32 v43, v44, v45
	global_store_dwordx2 v[62:63], v[42:43], off offset:1184
	v_mov_b32_e32 v42, v124
	v_mov_b32_e32 v43, v125
	v_lshlrev_b32_e32 v44, 16, v42
	v_and_b32_e32 v45, 0xffff0000, v42
	v_lshlrev_b32_e32 v42, 16, v43
	v_and_b32_e32 v43, 0xffff0000, v43
	v_pk_mul_f32 v[38:39], v[38:39], v[44:45]
	v_pk_mul_f32 v[40:41], v[40:41], v[42:43]
	v_cvt_pk_bf16_f32 v38, v38, v39
	v_cvt_pk_bf16_f32 v39, v40, v41
	global_store_dwordx2 v[62:63], v[38:39], off offset:1216
	v_mov_b32_e32 v38, v126
	v_mov_b32_e32 v39, v127
	v_lshlrev_b32_e32 v40, 16, v38
	v_and_b32_e32 v41, 0xffff0000, v38
	v_lshlrev_b32_e32 v38, 16, v39
	v_and_b32_e32 v39, 0xffff0000, v39
	v_pk_mul_f32 v[34:35], v[34:35], v[40:41]
	v_pk_mul_f32 v[36:37], v[36:37], v[38:39]
	v_cvt_pk_bf16_f32 v34, v34, v35
	v_cvt_pk_bf16_f32 v35, v36, v37
	v_or_b32_e32 v36, 16, v66
	v_ashrrev_i32_e32 v37, 31, v36
	v_lshlrev_b64 v[38:39], 11, v[36:37]
	v_lshl_add_u64 v[36:37], s[6:7], 0, v[38:39]
	global_store_dwordx2 v[62:63], v[34:35], off offset:1248
; __device__ __forceinline__ float lo_bf(unsigned u) { return __uint_as_float(u << 16); }
; __device__ __forceinline__ float hi_bf(unsigned u) { return __uint_as_float(u & 0xffff0000u); }
; __device__ __forceinline__ void cmlp_item(const Params& p, int j, int rt, int g, const u16* __restrict__ ZB, u16* sVT) {
;     ...
; #pragma unroll
;   for (int pb = 0; pb < 2; ++pb) {
;     const int pp = wave * 32 + pb * 16 + fr;
;     const float bias = p.cmlp_bs[(j * 4 + g) * 128 + pp];
; #pragma unroll
;     for (int db = 0; db < 8; ++db) {
;       const int d = db * 16 + fq * 4;
;       uint2 uu = *(const uint2*)(ZB + (size_t)(m0 + pp) * 1024 + g * 128 + d);
;       f32x4 r;
;       r[0] = lo_bf(uu.x) * (acc[pb][db][0] + bias);
;       r[1] = hi_bf(uu.x) * (acc[pb][db][1] + bias);
;       r[2] = lo_bf(uu.y) * (acc[pb][db][2] + bias);
;       r[3] = hi_bf(uu.y) * (acc[pb][db][3] + bias);
;       store4bf(p.XN + (size_t)(m0 + pp) * 1024 + 512 + g * 128 + d, r);
;     }
	v_lshl_add_u64 v[36:37], v[36:37], 0, v[0:1]
	v_mov_b32_e32 v34, v112
	v_mov_b32_e32 v40, v128
	v_mov_b32_e32 v41, v129
	v_pk_add_f32 v[30:31], v[30:31], v[34:35] op_sel_hi:[1,0]
	v_lshlrev_b32_e32 v42, 16, v40
	v_and_b32_e32 v43, 0xffff0000, v40
	v_pk_mul_f32 v[42:43], v[30:31], v[42:43]
	v_lshlrev_b32_e32 v30, 16, v41
	v_and_b32_e32 v31, 0xffff0000, v41
	v_pk_add_f32 v[32:33], v[32:33], v[34:35] op_sel_hi:[1,0]
	v_pk_add_f32 v[26:27], v[26:27], v[34:35] op_sel_hi:[1,0]
	v_pk_mul_f32 v[32:33], v[32:33], v[30:31]
	v_lshl_add_u64 v[30:31], s[42:43], 0, v[38:39]
	v_lshl_add_u64 v[30:31], v[30:31], 0, s[34:35]
	v_lshl_add_u64 v[30:31], v[30:31], 0, v[0:1]
	v_cvt_pk_bf16_f32 v38, v42, v43
	v_cvt_pk_bf16_f32 v39, v32, v33
	global_store_dwordx2 v[30:31], v[38:39], off offset:1024
	v_mov_b32_e32 v32, v130
	v_mov_b32_e32 v33, v131
	v_pk_add_f32 v[28:29], v[28:29], v[34:35] op_sel_hi:[1,0]
	v_pk_add_f32 v[22:23], v[22:23], v[34:35] op_sel_hi:[1,0]
	v_pk_add_f32 v[24:25], v[24:25], v[34:35] op_sel_hi:[1,0]
	v_pk_add_f32 v[18:19], v[18:19], v[34:35] op_sel_hi:[1,0]
	v_pk_add_f32 v[20:21], v[20:21], v[34:35] op_sel_hi:[1,0]
	v_pk_add_f32 v[14:15], v[14:15], v[34:35] op_sel_hi:[1,0]
	v_pk_add_f32 v[16:17], v[16:17], v[34:35] op_sel_hi:[1,0]
	v_pk_add_f32 v[10:11], v[10:11], v[34:35] op_sel_hi:[1,0]
	v_pk_add_f32 v[12:13], v[12:13], v[34:35] op_sel_hi:[1,0]
	v_pk_add_f32 v[6:7], v[6:7], v[34:35] op_sel_hi:[1,0]
	v_pk_add_f32 v[8:9], v[8:9], v[34:35] op_sel_hi:[1,0]
	v_pk_add_f32 v[2:3], v[2:3], v[34:35] op_sel_hi:[1,0]
	v_pk_add_f32 v[4:5], v[4:5], v[34:35] op_sel_hi:[1,0]
	v_lshlrev_b32_e32 v38, 16, v32
	v_and_b32_e32 v39, 0xffff0000, v32
	v_lshlrev_b32_e32 v32, 16, v33
	v_and_b32_e32 v33, 0xffff0000, v33
	v_pk_mul_f32 v[26:27], v[26:27], v[38:39]
	v_pk_mul_f32 v[28:29], v[28:29], v[32:33]
	v_cvt_pk_bf16_f32 v26, v26, v27
	v_cvt_pk_bf16_f32 v27, v28, v29
	global_store_dwordx2 v[30:31], v[26:27], off offset:1056
	v_mov_b32_e32 v26, v132
	v_mov_b32_e32 v27, v133
	v_lshlrev_b32_e32 v28, 16, v26
	v_and_b32_e32 v29, 0xffff0000, v26
	v_lshlrev_b32_e32 v26, 16, v27
	v_and_b32_e32 v27, 0xffff0000, v27
	v_pk_mul_f32 v[22:23], v[22:23], v[28:29]
	v_pk_mul_f32 v[24:25], v[24:25], v[26:27]
	v_cvt_pk_bf16_f32 v22, v22, v23
	v_cvt_pk_bf16_f32 v23, v24, v25
	global_store_dwordx2 v[30:31], v[22:23], off offset:1088
	v_mov_b32_e32 v22, v134
	v_mov_b32_e32 v23, v135
	v_lshlrev_b32_e32 v24, 16, v22
	v_and_b32_e32 v25, 0xffff0000, v22
	v_lshlrev_b32_e32 v22, 16, v23
	v_and_b32_e32 v23, 0xffff0000, v23
	v_pk_mul_f32 v[18:19], v[18:19], v[24:25]
	v_pk_mul_f32 v[20:21], v[20:21], v[22:23]
	v_cvt_pk_bf16_f32 v18, v18, v19
	v_cvt_pk_bf16_f32 v19, v20, v21
	global_store_dwordx2 v[30:31], v[18:19], off offset:1120
	v_mov_b32_e32 v18, v136
	v_mov_b32_e32 v19, v137
	v_lshlrev_b32_e32 v20, 16, v18
	v_and_b32_e32 v21, 0xffff0000, v18
	v_lshlrev_b32_e32 v18, 16, v19
	v_and_b32_e32 v19, 0xffff0000, v19
	v_pk_mul_f32 v[14:15], v[14:15], v[20:21]
	v_pk_mul_f32 v[16:17], v[16:17], v[18:19]
	v_cvt_pk_bf16_f32 v14, v14, v15
	v_cvt_pk_bf16_f32 v15, v16, v17
	global_store_dwordx2 v[30:31], v[14:15], off offset:1152
	v_mov_b32_e32 v14, v138
	v_mov_b32_e32 v15, v139
	v_lshlrev_b32_e32 v16, 16, v14
	v_and_b32_e32 v17, 0xffff0000, v14
	v_lshlrev_b32_e32 v14, 16, v15
	v_and_b32_e32 v15, 0xffff0000, v15
	v_pk_mul_f32 v[10:11], v[10:11], v[16:17]
	v_pk_mul_f32 v[12:13], v[12:13], v[14:15]
	v_cvt_pk_bf16_f32 v10, v10, v11
	v_cvt_pk_bf16_f32 v11, v12, v13
	global_store_dwordx2 v[30:31], v[10:11], off offset:1184
	v_mov_b32_e32 v10, v140
	v_mov_b32_e32 v11, v141
	v_lshlrev_b32_e32 v12, 16, v10
	v_and_b32_e32 v13, 0xffff0000, v10
	v_lshlrev_b32_e32 v10, 16, v11
	v_and_b32_e32 v11, 0xffff0000, v11
	v_pk_mul_f32 v[6:7], v[6:7], v[12:13]
	v_pk_mul_f32 v[8:9], v[8:9], v[10:11]
	v_cvt_pk_bf16_f32 v6, v6, v7
	v_cvt_pk_bf16_f32 v7, v8, v9
	global_store_dwordx2 v[30:31], v[6:7], off offset:1216
	v_mov_b32_e32 v6, v142
	v_mov_b32_e32 v7, v143
	v_lshlrev_b32_e32 v8, 16, v6
	v_and_b32_e32 v9, 0xffff0000, v6
	v_lshlrev_b32_e32 v6, 16, v7
	v_and_b32_e32 v7, 0xffff0000, v7
	v_pk_mul_f32 v[2:3], v[2:3], v[8:9]
	v_pk_mul_f32 v[4:5], v[4:5], v[6:7]
	v_cvt_pk_bf16_f32 v2, v2, v3
	v_cvt_pk_bf16_f32 v3, v4, v5
	global_store_dwordx2 v[30:31], v[2:3], off offset:1248
	s_cbranch_scc0 .LBB0_1553
	v_readlane_b32 s44, v255, 21
	s_branch .LBB0_1524

; __device__ __forceinline__ float siluf(float x) { return x * __builtin_amdgcn_rcpf(1.f + __expf(-x)); }
; #define TILE_LOOP(MT, NT) for (int i_ = blockIdx.x >> 3, mx_ = (MT) >> 3, n4_ = 4 * (NT); i_ < mx_ * (NT); i_ += gridDim.x >> 3)
;   __device__ __forceinline__ void operator()(int m, int n, f32x4 v) const {
;     float h0 = siluf(v[0]) * v[1], h1 = siluf(v[2]) * v[3];
;     *(unsigned*)(H + (size_t)m * FFNH + (n >> 1)) = pack2(h0, h1);
;   }
; __global__ void __launch_bounds__(512, 2) fwd_megakernel(Params p) {
;     ...
;       EpiFfnIn epi{H};
;       TILE_LOOP(mt_res, 22)
;         gemm_tile(p.XN, 1024, p.w_ffn_in[L], 1024, TILE_MT(mt_res, 22) * 256, TILE_NT(22) * 256, smem, epi);
.LBB0_1745:
	s_andn2_b64 vcc, exec, s[6:7]
	s_cbranch_vccnz .LBB0_1744
	s_load_dwordx2 s[10:11], s[8:9], 0xb8
	v_readlane_b32 s21, v255, 15
	s_branch .LBB0_1748
.LBB0_1747:
	s_or_b64 exec, exec, s[0:1]
	v_or_b32_e32 v0, s34, v145
	v_add_u32_e32 v132, v0, v146
	v_lshlrev_b32_e32 v0, 5, v143
	v_lshlrev_b32_e32 v130, 2, v144
	v_or3_b32 v0, v0, v130, s22
	v_mul_f32_e32 v130, 0xbfb8aa3b, v126
	v_exp_f32_e32 v133, v130
	v_mul_f32_e32 v130, 0xbfb8aa3b, v128
	v_exp_f32_e32 v135, v130
	v_mov_b32_e32 v138, v126
	v_add_f32_e32 v133, 1.0, v133
	v_rcp_f32_e32 v134, v133
	v_add_f32_e32 v133, 1.0, v135
	v_rcp_f32_e32 v135, v133
	v_mov_b32_e32 v139, v128
	v_mov_b32_e32 v128, v127
	v_mov_b64_e32 v[130:131], s[70:71]
	v_pk_mul_f32 v[134:135], v[138:139], v[134:135]
	v_mad_i64_i32 v[136:137], s[0:1], v132, s27, v[130:131]
	v_pk_mul_f32 v[126:127], v[128:129], v[134:135]
	v_mov_b32_e32 v134, v122
	v_cvt_pk_bf16_f32 v133, v126, v127
	v_mul_f32_e32 v126, 0xbfb8aa3b, v122
	v_exp_f32_e32 v128, v126
	v_mul_f32_e32 v126, 0xbfb8aa3b, v124
	v_exp_f32_e32 v129, v126
	v_mov_b32_e32 v135, v124
	v_add_f32_e32 v128, 1.0, v128
	v_rcp_f32_e32 v128, v128
	v_add_f32_e32 v129, 1.0, v129
	v_rcp_f32_e32 v129, v129
	v_mov_b32_e32 v124, v123
	v_lshl_add_u64 v[126:127], v[136:137], 0, v[0:1]
	s_add_i32 s21, s21, s75
	v_pk_mul_f32 v[128:129], v[134:135], v[128:129]
	s_cmp_ge_u32 s21, s18
	v_pk_mul_f32 v[122:123], v[124:125], v[128:129]
	v_mov_b32_e32 v128, v118
	v_cvt_pk_bf16_f32 v122, v122, v123
	global_store_dword v[126:127], v122, off offset:16
	v_mul_f32_e32 v122, 0xbfb8aa3b, v118
	v_mul_f32_e32 v123, 0xbfb8aa3b, v120
	v_exp_f32_e32 v122, v122
	v_exp_f32_e32 v123, v123
	v_mov_b32_e32 v129, v120
	v_mov_b32_e32 v120, v119
	v_add_f32_e32 v122, 1.0, v122
	v_add_f32_e32 v123, 1.0, v123
	v_rcp_f32_e32 v122, v122
	v_rcp_f32_e32 v123, v123
	v_or_b32_e32 v124, 16, v132
	v_mad_i64_i32 v[124:125], s[0:1], v124, s27, v[130:131]
	v_pk_mul_f32 v[122:123], v[128:129], v[122:123]
	global_store_dword v[126:127], v133, off
	v_pk_mul_f32 v[118:119], v[120:121], v[122:123]
	v_mov_b32_e32 v123, v116
	v_cvt_pk_bf16_f32 v122, v118, v119
	v_mul_f32_e32 v118, 0xbfb8aa3b, v114
	v_exp_f32_e32 v120, v118
	v_mul_f32_e32 v118, 0xbfb8aa3b, v116
	v_exp_f32_e32 v121, v118
	v_lshl_add_u64 v[118:119], v[124:125], 0, v[0:1]
	v_add_f32_e32 v120, 1.0, v120
	v_rcp_f32_e32 v120, v120
	v_add_f32_e32 v121, 1.0, v121
	v_rcp_f32_e32 v121, v121
	global_store_dword v[118:119], v122, off
	v_mov_b32_e32 v122, v114
	v_mov_b32_e32 v116, v115
	v_pk_mul_f32 v[120:121], v[122:123], v[120:121]
	s_nop 0
	v_pk_mul_f32 v[114:115], v[116:117], v[120:121]
	v_mov_b32_e32 v120, v110
	v_cvt_pk_bf16_f32 v114, v114, v115
	global_store_dword v[118:119], v114, off offset:16
	v_mul_f32_e32 v114, 0xbfb8aa3b, v110
	v_mul_f32_e32 v115, 0xbfb8aa3b, v112
	v_exp_f32_e32 v114, v114
	v_exp_f32_e32 v115, v115
	v_mov_b32_e32 v121, v112
	v_mov_b32_e32 v112, v111
	v_add_f32_e32 v114, 1.0, v114
	v_add_f32_e32 v115, 1.0, v115
	v_rcp_f32_e32 v114, v114
	v_rcp_f32_e32 v115, v115
	v_or_b32_e32 v116, 32, v132
	v_mad_i64_i32 v[116:117], s[0:1], v116, s27, v[130:131]
	v_pk_mul_f32 v[114:115], v[120:121], v[114:115]
	s_nop 0
	v_pk_mul_f32 v[110:111], v[112:113], v[114:115]
	v_mov_b32_e32 v115, v108
	v_cvt_pk_bf16_f32 v114, v110, v111
	v_mul_f32_e32 v110, 0xbfb8aa3b, v106
	v_exp_f32_e32 v112, v110
	v_mul_f32_e32 v110, 0xbfb8aa3b, v108
	v_exp_f32_e32 v113, v110
	v_lshl_add_u64 v[110:111], v[116:117], 0, v[0:1]
	v_add_f32_e32 v112, 1.0, v112
	v_rcp_f32_e32 v112, v112
	v_add_f32_e32 v113, 1.0, v113
	v_rcp_f32_e32 v113, v113
	global_store_dword v[110:111], v114, off
	v_mov_b32_e32 v114, v106
	v_mov_b32_e32 v108, v107
	v_pk_mul_f32 v[112:113], v[114:115], v[112:113]
	s_nop 0
	v_pk_mul_f32 v[106:107], v[108:109], v[112:113]
	v_mov_b32_e32 v112, v102
	v_cvt_pk_bf16_f32 v106, v106, v107
	global_store_dword v[110:111], v106, off offset:16
	v_mul_f32_e32 v106, 0xbfb8aa3b, v102
	v_mul_f32_e32 v107, 0xbfb8aa3b, v104
	v_exp_f32_e32 v106, v106
	v_exp_f32_e32 v107, v107
	v_mov_b32_e32 v113, v104
	v_mov_b32_e32 v104, v103
	v_add_f32_e32 v106, 1.0, v106
	v_add_f32_e32 v107, 1.0, v107
	v_rcp_f32_e32 v106, v106
	v_rcp_f32_e32 v107, v107
	v_or_b32_e32 v108, 48, v132
	v_mad_i64_i32 v[108:109], s[0:1], v108, s27, v[130:131]
	v_pk_mul_f32 v[106:107], v[112:113], v[106:107]
	s_nop 0
	v_pk_mul_f32 v[102:103], v[104:105], v[106:107]
	v_mov_b32_e32 v107, v100
	v_cvt_pk_bf16_f32 v106, v102, v103
	v_mul_f32_e32 v102, 0xbfb8aa3b, v98
	v_exp_f32_e32 v104, v102
	v_mul_f32_e32 v102, 0xbfb8aa3b, v100
	v_exp_f32_e32 v105, v102
	v_lshl_add_u64 v[102:103], v[108:109], 0, v[0:1]
	v_add_f32_e32 v104, 1.0, v104
	v_rcp_f32_e32 v104, v104
	v_add_f32_e32 v105, 1.0, v105
	v_rcp_f32_e32 v105, v105
	global_store_dword v[102:103], v106, off
	v_mov_b32_e32 v106, v98
	v_mov_b32_e32 v100, v99
	v_pk_mul_f32 v[104:105], v[106:107], v[104:105]
	s_nop 0
	v_pk_mul_f32 v[98:99], v[100:101], v[104:105]
	v_mul_f32_e32 v100, 0xbfb8aa3b, v94
	v_mul_f32_e32 v101, 0xbfb8aa3b, v96
	v_exp_f32_e32 v100, v100
	v_exp_f32_e32 v101, v101
	v_cvt_pk_bf16_f32 v104, v98, v99
	global_store_dword v[102:103], v104, off offset:16
	v_add_f32_e32 v98, 1.0, v100
	v_add_f32_e32 v99, 1.0, v101
	v_rcp_f32_e32 v98, v98
	v_rcp_f32_e32 v99, v99
	v_mov_b32_e32 v100, v94
	v_mov_b32_e32 v101, v96
	v_mov_b32_e32 v96, v95
	v_pk_mul_f32 v[98:99], v[100:101], v[98:99]
	s_nop 0
	v_pk_mul_f32 v[94:95], v[96:97], v[98:99]
	v_mul_f32_e32 v96, 0xbfb8aa3b, v90
	v_mul_f32_e32 v97, 0xbfb8aa3b, v92
	v_exp_f32_e32 v96, v96
	v_exp_f32_e32 v97, v97
	v_cvt_pk_bf16_f32 v98, v94, v95
	global_store_dword v[126:127], v98, off offset:128
	v_add_f32_e32 v94, 1.0, v96
; __device__ __forceinline__ float siluf(float x) { return x * __builtin_amdgcn_rcpf(1.f + __expf(-x)); }
;   __device__ __forceinline__ void operator()(int m, int n, f32x4 v) const {
;     float h0 = siluf(v[0]) * v[1], h1 = siluf(v[2]) * v[3];
;     *(unsigned*)(H + (size_t)m * FFNH + (n >> 1)) = pack2(h0, h1);
;   }
	v_add_f32_e32 v95, 1.0, v97
	v_rcp_f32_e32 v94, v94
	v_rcp_f32_e32 v95, v95
	v_mov_b32_e32 v96, v90
	v_mov_b32_e32 v97, v92
	v_mov_b32_e32 v92, v91
	v_pk_mul_f32 v[94:95], v[96:97], v[94:95]
	s_nop 0
	v_pk_mul_f32 v[90:91], v[92:93], v[94:95]
	v_mul_f32_e32 v92, 0xbfb8aa3b, v86
	v_mul_f32_e32 v93, 0xbfb8aa3b, v88
	v_exp_f32_e32 v92, v92
	v_exp_f32_e32 v93, v93
	v_cvt_pk_bf16_f32 v94, v90, v91
	global_store_dword v[126:127], v94, off offset:144
	v_add_f32_e32 v90, 1.0, v92
	v_add_f32_e32 v91, 1.0, v93
	v_rcp_f32_e32 v90, v90
	v_rcp_f32_e32 v91, v91
	v_mov_b32_e32 v92, v86
	v_mov_b32_e32 v93, v88
	v_mov_b32_e32 v88, v87
	v_pk_mul_f32 v[90:91], v[92:93], v[90:91]
	s_nop 0
	v_pk_mul_f32 v[86:87], v[88:89], v[90:91]
	v_mul_f32_e32 v88, 0xbfb8aa3b, v82
	v_mul_f32_e32 v89, 0xbfb8aa3b, v84
	v_exp_f32_e32 v88, v88
	v_exp_f32_e32 v89, v89
	v_cvt_pk_bf16_f32 v90, v86, v87
	global_store_dword v[118:119], v90, off offset:128
	v_add_f32_e32 v86, 1.0, v88
	v_add_f32_e32 v87, 1.0, v89
	v_rcp_f32_e32 v86, v86
	v_rcp_f32_e32 v87, v87
	v_mov_b32_e32 v88, v82
	v_mov_b32_e32 v89, v84
	v_mov_b32_e32 v84, v83
	v_pk_mul_f32 v[86:87], v[88:89], v[86:87]
	s_nop 0
	v_pk_mul_f32 v[82:83], v[84:85], v[86:87]
	v_mul_f32_e32 v84, 0xbfb8aa3b, v78
	v_mul_f32_e32 v85, 0xbfb8aa3b, v80
	v_exp_f32_e32 v84, v84
	v_exp_f32_e32 v85, v85
	v_cvt_pk_bf16_f32 v86, v82, v83
	global_store_dword v[118:119], v86, off offset:144
	v_add_f32_e32 v82, 1.0, v84
	v_add_f32_e32 v83, 1.0, v85
	v_rcp_f32_e32 v82, v82
	v_rcp_f32_e32 v83, v83
	v_mov_b32_e32 v84, v78
	v_mov_b32_e32 v85, v80
	v_mov_b32_e32 v80, v79
	v_pk_mul_f32 v[82:83], v[84:85], v[82:83]
	s_nop 0
	v_pk_mul_f32 v[78:79], v[80:81], v[82:83]
	v_mul_f32_e32 v80, 0xbfb8aa3b, v74
	v_mul_f32_e32 v81, 0xbfb8aa3b, v76
	v_exp_f32_e32 v80, v80
	v_exp_f32_e32 v81, v81
	v_cvt_pk_bf16_f32 v82, v78, v79
	global_store_dword v[110:111], v82, off offset:128
	v_add_f32_e32 v78, 1.0, v80
	v_add_f32_e32 v79, 1.0, v81
	v_rcp_f32_e32 v78, v78
	v_rcp_f32_e32 v79, v79
	v_mov_b32_e32 v80, v74
	v_mov_b32_e32 v81, v76
	v_mov_b32_e32 v76, v75
	v_pk_mul_f32 v[78:79], v[80:81], v[78:79]
	s_nop 0
	v_pk_mul_f32 v[74:75], v[76:77], v[78:79]
	v_mul_f32_e32 v76, 0xbfb8aa3b, v70
	v_mul_f32_e32 v77, 0xbfb8aa3b, v72
	v_exp_f32_e32 v76, v76
	v_exp_f32_e32 v77, v77
	v_cvt_pk_bf16_f32 v78, v74, v75
	global_store_dword v[110:111], v78, off offset:144
	v_add_f32_e32 v74, 1.0, v76
	v_add_f32_e32 v75, 1.0, v77
	v_rcp_f32_e32 v74, v74
	v_rcp_f32_e32 v75, v75
	v_mov_b32_e32 v76, v70
	v_mov_b32_e32 v77, v72
	v_mov_b32_e32 v72, v71
	v_pk_mul_f32 v[74:75], v[76:77], v[74:75]
	s_nop 0
	v_pk_mul_f32 v[70:71], v[72:73], v[74:75]
	v_mul_f32_e32 v72, 0xbfb8aa3b, v66
	v_mul_f32_e32 v73, 0xbfb8aa3b, v68
	v_exp_f32_e32 v72, v72
	v_exp_f32_e32 v73, v73
	v_cvt_pk_bf16_f32 v74, v70, v71
	global_store_dword v[102:103], v74, off offset:128
	v_add_f32_e32 v70, 1.0, v72
	v_add_f32_e32 v71, 1.0, v73
	v_rcp_f32_e32 v70, v70
	v_rcp_f32_e32 v71, v71
	v_mov_b32_e32 v72, v66
	v_mov_b32_e32 v73, v68
	v_mov_b32_e32 v68, v67
	v_pk_mul_f32 v[70:71], v[72:73], v[70:71]
	s_nop 0
	v_pk_mul_f32 v[66:67], v[68:69], v[70:71]
	v_mov_b32_e32 v70, v62
	v_cvt_pk_bf16_f32 v66, v66, v67
	global_store_dword v[102:103], v66, off offset:144
	v_mul_f32_e32 v66, 0xbfb8aa3b, v62
	v_mul_f32_e32 v67, 0xbfb8aa3b, v64
	v_exp_f32_e32 v66, v66
	v_exp_f32_e32 v67, v67
	v_mov_b32_e32 v71, v64
	v_mov_b32_e32 v64, v63
	v_add_f32_e32 v66, 1.0, v66
	v_add_f32_e32 v67, 1.0, v67
	v_rcp_f32_e32 v66, v66
	v_rcp_f32_e32 v67, v67
	v_add_u32_e32 v68, 0x80, v132
	v_mad_i64_i32 v[68:69], s[0:1], v68, s27, v[130:131]
	v_pk_mul_f32 v[66:67], v[70:71], v[66:67]
	s_nop 0
	v_pk_mul_f32 v[62:63], v[64:65], v[66:67]
	v_mov_b32_e32 v67, v60
	v_cvt_pk_bf16_f32 v66, v62, v63
	v_mul_f32_e32 v62, 0xbfb8aa3b, v58
	v_exp_f32_e32 v64, v62
	v_mul_f32_e32 v62, 0xbfb8aa3b, v60
	v_exp_f32_e32 v65, v62
	v_lshl_add_u64 v[62:63], v[68:69], 0, v[0:1]
	v_add_f32_e32 v64, 1.0, v64
	v_rcp_f32_e32 v64, v64
	v_add_f32_e32 v65, 1.0, v65
	v_rcp_f32_e32 v65, v65
	global_store_dword v[62:63], v66, off
	v_mov_b32_e32 v66, v58
	v_mov_b32_e32 v60, v59
	v_pk_mul_f32 v[64:65], v[66:67], v[64:65]
	s_nop 0
	v_pk_mul_f32 v[58:59], v[60:61], v[64:65]
	v_mov_b32_e32 v64, v54
	v_cvt_pk_bf16_f32 v58, v58, v59
	global_store_dword v[62:63], v58, off offset:16
	v_mul_f32_e32 v58, 0xbfb8aa3b, v54
	v_mul_f32_e32 v59, 0xbfb8aa3b, v56
	v_exp_f32_e32 v58, v58
	v_exp_f32_e32 v59, v59
	v_mov_b32_e32 v65, v56
	v_mov_b32_e32 v56, v55
	v_add_f32_e32 v58, 1.0, v58
	v_add_f32_e32 v59, 1.0, v59
	v_rcp_f32_e32 v58, v58
	v_rcp_f32_e32 v59, v59
	v_add_u32_e32 v60, 0x90, v132
	v_mad_i64_i32 v[60:61], s[0:1], v60, s27, v[130:131]
	v_pk_mul_f32 v[58:59], v[64:65], v[58:59]
	s_nop 0
	v_pk_mul_f32 v[54:55], v[56:57], v[58:59]
	v_mov_b32_e32 v59, v52
	v_cvt_pk_bf16_f32 v58, v54, v55
	v_mul_f32_e32 v54, 0xbfb8aa3b, v50
	v_exp_f32_e32 v56, v54
	v_mul_f32_e32 v54, 0xbfb8aa3b, v52
	v_exp_f32_e32 v57, v54
	v_lshl_add_u64 v[54:55], v[60:61], 0, v[0:1]
	v_add_f32_e32 v56, 1.0, v56
	v_rcp_f32_e32 v56, v56
	v_add_f32_e32 v57, 1.0, v57
	v_rcp_f32_e32 v57, v57
	global_store_dword v[54:55], v58, off
	v_mov_b32_e32 v58, v50
	v_mov_b32_e32 v52, v51
	v_pk_mul_f32 v[56:57], v[58:59], v[56:57]
	s_nop 0
	v_pk_mul_f32 v[50:51], v[52:53], v[56:57]
	v_mov_b32_e32 v56, v46
	v_cvt_pk_bf16_f32 v50, v50, v51
	global_store_dword v[54:55], v50, off offset:16
	v_mul_f32_e32 v50, 0xbfb8aa3b, v46
	v_mul_f32_e32 v51, 0xbfb8aa3b, v48
	v_exp_f32_e32 v50, v50
	v_exp_f32_e32 v51, v51
	v_mov_b32_e32 v57, v48
	v_mov_b32_e32 v48, v47
	v_add_f32_e32 v50, 1.0, v50
	v_add_f32_e32 v51, 1.0, v51
	v_rcp_f32_e32 v50, v50
	v_rcp_f32_e32 v51, v51
; __device__ __forceinline__ float siluf(float x) { return x * __builtin_amdgcn_rcpf(1.f + __expf(-x)); }
;   __device__ __forceinline__ void operator()(int m, int n, f32x4 v) const {
;     float h0 = siluf(v[0]) * v[1], h1 = siluf(v[2]) * v[3];
;     *(unsigned*)(H + (size_t)m * FFNH + (n >> 1)) = pack2(h0, h1);
;   }
	v_add_u32_e32 v52, 0xa0, v132
	v_mad_i64_i32 v[52:53], s[0:1], v52, s27, v[130:131]
	v_pk_mul_f32 v[50:51], v[56:57], v[50:51]
	s_nop 0
	v_pk_mul_f32 v[46:47], v[48:49], v[50:51]
	v_mov_b32_e32 v51, v44
	v_cvt_pk_bf16_f32 v50, v46, v47
	v_mul_f32_e32 v46, 0xbfb8aa3b, v42
	v_exp_f32_e32 v48, v46
	v_mul_f32_e32 v46, 0xbfb8aa3b, v44
	v_exp_f32_e32 v49, v46
	v_lshl_add_u64 v[46:47], v[52:53], 0, v[0:1]
	v_add_f32_e32 v48, 1.0, v48
	v_rcp_f32_e32 v48, v48
	v_add_f32_e32 v49, 1.0, v49
	v_rcp_f32_e32 v49, v49
	global_store_dword v[46:47], v50, off
	v_mov_b32_e32 v50, v42
	v_mov_b32_e32 v44, v43
	v_pk_mul_f32 v[48:49], v[50:51], v[48:49]
	s_nop 0
	v_pk_mul_f32 v[42:43], v[44:45], v[48:49]
	v_mov_b32_e32 v48, v38
	v_cvt_pk_bf16_f32 v42, v42, v43
	global_store_dword v[46:47], v42, off offset:16
	v_mul_f32_e32 v42, 0xbfb8aa3b, v38
	v_mul_f32_e32 v43, 0xbfb8aa3b, v40
	v_exp_f32_e32 v42, v42
	v_exp_f32_e32 v43, v43
	v_mov_b32_e32 v49, v40
	v_mov_b32_e32 v40, v39
	v_add_f32_e32 v42, 1.0, v42
	v_add_f32_e32 v43, 1.0, v43
	v_rcp_f32_e32 v42, v42
	v_rcp_f32_e32 v43, v43
	v_add_u32_e32 v44, 0xb0, v132
	v_mad_i64_i32 v[44:45], s[0:1], v44, s27, v[130:131]
	v_pk_mul_f32 v[42:43], v[48:49], v[42:43]
	s_nop 0
	v_pk_mul_f32 v[38:39], v[40:41], v[42:43]
	v_mov_b32_e32 v43, v36
	v_cvt_pk_bf16_f32 v42, v38, v39
	v_mul_f32_e32 v38, 0xbfb8aa3b, v34
	v_exp_f32_e32 v40, v38
	v_mul_f32_e32 v38, 0xbfb8aa3b, v36
	v_exp_f32_e32 v41, v38
	v_lshl_add_u64 v[38:39], v[44:45], 0, v[0:1]
	v_add_f32_e32 v0, 1.0, v40
	v_rcp_f32_e32 v40, v0
	v_add_f32_e32 v0, 1.0, v41
	v_rcp_f32_e32 v41, v0
	global_store_dword v[38:39], v42, off
	v_mov_b32_e32 v42, v34
	v_mov_b32_e32 v36, v35
	v_pk_mul_f32 v[40:41], v[42:43], v[40:41]
	v_mul_f32_e32 v0, 0xbfb8aa3b, v30
	v_pk_mul_f32 v[34:35], v[36:37], v[40:41]
	v_exp_f32_e32 v0, v0
	v_mul_f32_e32 v36, 0xbfb8aa3b, v32
	v_exp_f32_e32 v36, v36
	v_cvt_pk_bf16_f32 v37, v34, v35
	v_add_f32_e32 v0, 1.0, v0
	v_rcp_f32_e32 v34, v0
	v_add_f32_e32 v0, 1.0, v36
	v_rcp_f32_e32 v35, v0
	global_store_dword v[38:39], v37, off offset:16
	v_mov_b32_e32 v36, v30
	v_mov_b32_e32 v37, v32
	v_pk_mul_f32 v[34:35], v[36:37], v[34:35]
	v_mov_b32_e32 v32, v31
	v_mul_f32_e32 v0, 0xbfb8aa3b, v26
	v_pk_mul_f32 v[30:31], v[32:33], v[34:35]
	v_exp_f32_e32 v0, v0
	v_mul_f32_e32 v32, 0xbfb8aa3b, v28
	v_exp_f32_e32 v32, v32
	v_cvt_pk_bf16_f32 v33, v30, v31
	v_add_f32_e32 v0, 1.0, v0
	v_rcp_f32_e32 v30, v0
	v_add_f32_e32 v0, 1.0, v32
	v_rcp_f32_e32 v31, v0
	global_store_dword v[62:63], v33, off offset:128
	v_mov_b32_e32 v32, v26
	v_mov_b32_e32 v33, v28
	v_pk_mul_f32 v[30:31], v[32:33], v[30:31]
	v_mov_b32_e32 v28, v27
	v_mul_f32_e32 v0, 0xbfb8aa3b, v22
	v_pk_mul_f32 v[26:27], v[28:29], v[30:31]
	v_exp_f32_e32 v0, v0
	v_mul_f32_e32 v28, 0xbfb8aa3b, v24
	v_exp_f32_e32 v28, v28
	v_cvt_pk_bf16_f32 v29, v26, v27
	v_add_f32_e32 v0, 1.0, v0
	v_rcp_f32_e32 v26, v0
	v_add_f32_e32 v0, 1.0, v28
	v_rcp_f32_e32 v27, v0
	global_store_dword v[62:63], v29, off offset:144
	v_mov_b32_e32 v28, v22
	v_mov_b32_e32 v29, v24
	v_pk_mul_f32 v[26:27], v[28:29], v[26:27]
	v_mov_b32_e32 v24, v23
	v_mul_f32_e32 v0, 0xbfb8aa3b, v18
	v_pk_mul_f32 v[22:23], v[24:25], v[26:27]
	v_exp_f32_e32 v0, v0
	v_mul_f32_e32 v24, 0xbfb8aa3b, v20
	v_exp_f32_e32 v24, v24
	v_cvt_pk_bf16_f32 v25, v22, v23
	v_add_f32_e32 v0, 1.0, v0
	v_rcp_f32_e32 v22, v0
	v_add_f32_e32 v0, 1.0, v24
	v_rcp_f32_e32 v23, v0
	global_store_dword v[54:55], v25, off offset:128
	v_mov_b32_e32 v24, v18
	v_mov_b32_e32 v25, v20
	v_pk_mul_f32 v[22:23], v[24:25], v[22:23]
	v_mov_b32_e32 v20, v19
	v_mul_f32_e32 v0, 0xbfb8aa3b, v14
	v_pk_mul_f32 v[18:19], v[20:21], v[22:23]
	v_exp_f32_e32 v0, v0
	v_mul_f32_e32 v20, 0xbfb8aa3b, v16
	v_exp_f32_e32 v20, v20
	v_cvt_pk_bf16_f32 v21, v18, v19
	v_add_f32_e32 v0, 1.0, v0
	v_rcp_f32_e32 v18, v0
	v_add_f32_e32 v0, 1.0, v20
	v_rcp_f32_e32 v19, v0
	global_store_dword v[54:55], v21, off offset:144
	v_mov_b32_e32 v20, v14
	v_mov_b32_e32 v21, v16
	v_pk_mul_f32 v[18:19], v[20:21], v[18:19]
	v_mov_b32_e32 v16, v15
	v_mul_f32_e32 v0, 0xbfb8aa3b, v10
	v_pk_mul_f32 v[14:15], v[16:17], v[18:19]
	v_exp_f32_e32 v0, v0
	v_mul_f32_e32 v16, 0xbfb8aa3b, v12
	v_exp_f32_e32 v16, v16
	v_cvt_pk_bf16_f32 v17, v14, v15
	v_add_f32_e32 v0, 1.0, v0
	v_rcp_f32_e32 v14, v0
	v_add_f32_e32 v0, 1.0, v16
	v_rcp_f32_e32 v15, v0
	global_store_dword v[46:47], v17, off offset:128
	v_mov_b32_e32 v16, v10
	v_mov_b32_e32 v17, v12
	v_pk_mul_f32 v[14:15], v[16:17], v[14:15]
	v_mov_b32_e32 v12, v11
	v_mul_f32_e32 v0, 0xbfb8aa3b, v6
	v_pk_mul_f32 v[10:11], v[12:13], v[14:15]
	v_exp_f32_e32 v0, v0
	v_mul_f32_e32 v12, 0xbfb8aa3b, v8
	v_exp_f32_e32 v12, v12
	v_cvt_pk_bf16_f32 v13, v10, v11
	v_add_f32_e32 v0, 1.0, v0
	v_rcp_f32_e32 v10, v0
	v_add_f32_e32 v0, 1.0, v12
	v_rcp_f32_e32 v11, v0
	global_store_dword v[46:47], v13, off offset:144
	v_mov_b32_e32 v12, v6
	v_mov_b32_e32 v13, v8
	v_pk_mul_f32 v[10:11], v[12:13], v[10:11]
	v_mov_b32_e32 v8, v7
	v_mul_f32_e32 v0, 0xbfb8aa3b, v2
	v_pk_mul_f32 v[6:7], v[8:9], v[10:11]
	v_exp_f32_e32 v0, v0
	v_mul_f32_e32 v8, 0xbfb8aa3b, v4
	v_exp_f32_e32 v8, v8
	v_cvt_pk_bf16_f32 v9, v6, v7
	v_add_f32_e32 v0, 1.0, v0
	v_rcp_f32_e32 v6, v0
	v_add_f32_e32 v0, 1.0, v8
	v_rcp_f32_e32 v7, v0
	global_store_dword v[38:39], v9, off offset:128
	v_mov_b32_e32 v8, v2
	v_mov_b32_e32 v9, v4
	v_pk_mul_f32 v[6:7], v[8:9], v[6:7]
	v_mov_b32_e32 v4, v3
	v_pk_mul_f32 v[2:3], v[4:5], v[6:7]
	s_nop 0
	v_cvt_pk_bf16_f32 v0, v2, v3
	global_store_dword v[38:39], v0, off offset:144
	s_cbranch_scc1 .LBB0_1744
; __device__ __forceinline__ int get_tid512() { int t = threadIdx.x; asm volatile("" : "+v"(t)); return t; }
; #define STAGE_A(P, hh, kt) do { const u16* ub_ = Ab + ((hh) * ahalf + (unsigned)(kt) * 64u); \
;     __builtin_amdgcn_global_load_lds((const unsigned*)(ub_ + oa0), (unsigned*)((char*)(P) + tid * 16), 16, 0, 0); \
;     __builtin_amdgcn_global_load_lds((const unsigned*)(ub_ + oa1), (unsigned*)((char*)(P) + tid * 16 + 8192), 16, 0, 0); } while (0)
; #define STAGE_B(P, hh, kt) do { const u16* ub_ = Bb + ((hh) * bhalf + (unsigned)(kt) * 64u); \
;     __builtin_amdgcn_global_load_lds((const unsigned*)(ub_ + ob0), (unsigned*)((char*)(P) + tid * 16), 16, 0, 0); \
;     __builtin_amdgcn_global_load_lds((const unsigned*)(ub_ + ob1), (unsigned*)((char*)(P) + tid * 16 + 8192), 16, 0, 0); } while (0)
; #define GBAR __builtin_amdgcn_s_barrier()
; template <class Epi>
; __device__ __forceinline__ void gemm_tile(const u16* __restrict__ A, int lda, const u16* __restrict__ Wt, int K,
;                                           int m0, int n0, char* sbase, const Epi& epi) {
;     ...
;   const int tid = get_tid512(), lane = tid & 63, wid = tid >> 6;
;   const int wr = wid >> 2, wc = wid & 3, fr = lane & 15, fq = lane >> 4;
;   int sr0, sc0, sr1, sc1;
;   g_stage_rc(tid * 16, sr0, sc0);
;   g_stage_rc(tid * 16 + 8192, sr1, sc1);
;   const u16* const Ab = A + (size_t)m0 * lda;
;   const u16* const Bb = Wt + (size_t)n0 * K;
;   const unsigned oa0 = (unsigned)(sr0 * lda + sc0), oa1 = (unsigned)(sr1 * lda + sc1);
;   const unsigned ob0 = (unsigned)(sr0 * K + sc0), ob1 = (unsigned)(sr1 * K + sc1);
;   const unsigned ahalf = (unsigned)(128 * lda), bhalf = (unsigned)(128 * K);
;     ...
;   f32x4 acc[2][2][4][2];
; #pragma unroll
;   for (int a = 0; a < 2; ++a)
; #pragma unroll
;     for (int b = 0; b < 2; ++b)
; #pragma unroll
;       for (int c = 0; c < 4; ++c)
; #pragma unroll
;         for (int d = 0; d < 2; ++d) acc[a][b][c][d] = (f32x4){0.f, 0.f, 0.f, 0.f};
;   bf16x8 At[4][2], B0[2][2], B1[2][2];
;   const int nt = K >> 6;
;   STAGE_B(SB(0, 0), 0, 0); STAGE_A(SA(0, 0), 0, 0);
;   STAGE_B(SB(0, 1), 1, 0); STAGE_A(SA(0, 1), 1, 0);
;   if (wr == 1) GBAR;
.LBB0_1748:
	v_mov_b32_e32 v142, v206
	s_mul_hi_u32 s0, s21, 0xba2e8ba3
	v_ashrrev_i32_e32 v0, 31, v142
	v_lshrrev_b32_e32 v0, 26, v0
	v_add_u32_e32 v0, v142, v0
	v_ashrrev_i32_e32 v10, 6, v0
	v_bfe_i32 v0, v142, 27, 1
	v_lshlrev_b32_e32 v147, 4, v142
	v_lshrrev_b32_e32 v0, 22, v0
	v_add_u32_e32 v0, v147, v0
	v_and_b32_e32 v0, 0xfffffc00, v0
	v_sub_u32_e32 v0, v147, v0
	s_waitcnt lgkmcnt(0)
	v_lshrrev_b32_e32 v2, 4, v0
	v_bitop3_b32 v2, v2, v0, 32 bitop3:0x6c
	v_ashrrev_i32_e32 v0, 31, v0
	v_lshrrev_b32_e32 v0, 26, v0
	v_lshlrev_b32_e32 v3, 3, v10
	v_add_u32_e32 v0, v2, v0
	v_and_b32_e32 v3, 0x3ffff0, v3
	v_ashrrev_i32_e32 v11, 6, v0
	v_add_u32_e32 v0, v11, v3
	v_lshlrev_b32_e32 v3, 5, v10
	v_and_b32_e32 v13, 32, v3
	v_mul_i32_i24_e32 v3, 64, v11
	v_sub_u32_e32 v2, v2, v3
	v_add_u32_e32 v148, 0x2000, v147
	v_ashrrev_i16_sdwa v14, v196, sext(v2) dst_sel:DWORD dst_unused:UNUSED_PAD src0_sel:DWORD src1_sel:BYTE_0
	v_ashrrev_i32_e32 v2, 31, v148
	v_lshrrev_b32_e32 v2, 22, v2
	v_add_u32_e32 v2, v148, v2
	v_ashrrev_i32_e32 v12, 10, v2
	s_lshr_b32 s0, s0, 6
	v_mul_i32_i24_e32 v2, 0x400, v12
	s_lshl_b32 s23, s0, 2
	s_mulk_i32 s0, 0x58
	v_sub_u32_e32 v2, v148, v2
	s_sub_i32 s0, s21, s0
	v_lshrrev_b32_e32 v3, 4, v2
	s_add_i32 s23, s23, s19
	s_and_b32 s45, s0, 3
	v_bitop3_b32 v2, v3, v2, 32 bitop3:0x6c
	s_or_b32 s1, s23, s45
	s_lshl_b32 s0, s0, 6
	v_ashrrev_i32_e32 v4, 31, v2
	s_lshl_b32 s34, s1, 8
	s_and_b32 s22, s0, 0x1f00
	v_lshrrev_b32_e32 v4, 26, v4
	v_lshlrev_b32_e32 v3, 3, v12
	v_add_u32_e32 v4, v2, v4
	s_lshl_b64 s[0:1], s[34:35], 11
	s_lshl_b32 s46, s22, 11
	v_and_b32_e32 v3, 0x3ffff0, v3
	v_ashrrev_i32_e32 v15, 6, v4
	v_lshlrev_b32_e32 v5, 5, v12
	v_and_b32_e32 v4, 0xc0, v4
	s_add_u32 s12, s42, s0
	v_add_u32_e32 v3, v15, v3
	v_and_b32_e32 v16, 32, v5
	v_sub_u32_e32 v2, v2, v4
	v_lshl_or_b32 v0, v0, 10, v13
	s_addc_u32 s13, s43, s1
	v_ashrrev_i16_sdwa v17, v196, sext(v2) dst_sel:DWORD dst_unused:UNUSED_PAD src0_sel:DWORD src1_sel:BYTE_0
	v_lshl_or_b32 v2, v3, 10, v16
	s_add_u32 s0, s10, s46
	v_add_u32_sdwa v0, v0, sext(v14) dst_sel:DWORD dst_unused:UNUSED_PAD src0_sel:DWORD src1_sel:WORD_0
	v_add_u32_e32 v153, 0x10000, v147
	s_addc_u32 s1, s11, 0
	v_add_u32_sdwa v130, v2, sext(v17) dst_sel:DWORD dst_unused:UNUSED_PAD src0_sel:DWORD src1_sel:WORD_0
	v_lshlrev_b64 v[20:21], 1, v[0:1]
	v_readfirstlane_b32 s14, v153
	v_mov_b32_e32 v131, v1
	v_add_u32_e32 v154, 0x12000, v147
	v_lshl_add_u64 v[2:3], s[0:1], 0, v[20:21]
	s_mov_b32 m0, s14
	v_lshlrev_b64 v[22:23], 1, v[130:131]
	v_readfirstlane_b32 s14, v154
	global_load_lds_dwordx4 v[2:3], off
	v_lshl_add_u64 v[6:7], s[0:1], 0, v[22:23]
	s_mov_b32 m0, s14
	v_readfirstlane_b32 s14, v147
	global_load_lds_dwordx4 v[6:7], off
	v_lshl_add_u64 v[8:9], s[12:13], 0, v[20:21]
	s_mov_b32 m0, s14
	v_readfirstlane_b32 s14, v148
	global_load_lds_dwordx4 v[8:9], off
	s_mov_b32 m0, s14
	s_add_u32 s14, s0, 0x40000
	v_add_u32_e32 v156, 0x14000, v147
	v_lshl_add_u64 v[4:5], s[12:13], 0, v[22:23]
	s_addc_u32 s15, s1, 0
	v_readfirstlane_b32 s47, v156
	global_load_lds_dwordx4 v[4:5], off
	v_lshl_add_u64 v[24:25], s[14:15], 0, v[20:21]
	s_mov_b32 m0, s47
	v_add_u32_e32 v157, 0x16000, v147
	global_load_lds_dwordx4 v[24:25], off
	v_lshl_add_u64 v[24:25], s[14:15], 0, v[22:23]
	v_readfirstlane_b32 s14, v157
	s_mov_b32 m0, s14
	s_add_u32 s14, s12, 0x40000
	v_add_u32_e32 v158, 0x4000, v147
	s_addc_u32 s15, s13, 0
	v_readfirstlane_b32 s47, v158
	global_load_lds_dwordx4 v[24:25], off
	v_lshl_add_u64 v[20:21], s[14:15], 0, v[20:21]
	s_mov_b32 m0, s47
	v_add_u32_e32 v159, 0x6000, v147
	global_load_lds_dwordx4 v[20:21], off
	v_lshl_add_u64 v[20:21], s[14:15], 0, v[22:23]
	v_readfirstlane_b32 s14, v159
	s_mov_b32 m0, s14
	v_ashrrev_i32_e32 v18, 8, v142
	global_load_lds_dwordx4 v[20:21], off
	v_cmp_eq_u32_e32 vcc, 1, v18
	s_and_saveexec_b64 s[14:15], vcc
	s_cbranch_execz .LBB0_1750
	s_barrier
; #define STAGE_A(P, hh, kt) do { const u16* ub_ = Ab + ((hh) * ahalf + (unsigned)(kt) * 64u); \
;     __builtin_amdgcn_global_load_lds((const unsigned*)(ub_ + oa0), (unsigned*)((char*)(P) + tid * 16), 16, 0, 0); \
;     __builtin_amdgcn_global_load_lds((const unsigned*)(ub_ + oa1), (unsigned*)((char*)(P) + tid * 16 + 8192), 16, 0, 0); } while (0)
; #define STAGE_B(P, hh, kt) do { const u16* ub_ = Bb + ((hh) * bhalf + (unsigned)(kt) * 64u); \
;     __builtin_amdgcn_global_load_lds((const unsigned*)(ub_ + ob0), (unsigned*)((char*)(P) + tid * 16), 16, 0, 0); \
;     __builtin_amdgcn_global_load_lds((const unsigned*)(ub_ + ob1), (unsigned*)((char*)(P) + tid * 16 + 8192), 16, 0, 0); } while (0)
; #define WAIT_V(n) asm volatile("s_waitcnt vmcnt(" #n ")" ::: "memory")
; #define GBAR __builtin_amdgcn_s_barrier()
; template <class Epi>
; __device__ __forceinline__ void gemm_tile(const u16* __restrict__ A, int lda, const u16* __restrict__ Wt, int K,
;                                           int m0, int n0, char* sbase, const Epi& epi) {
;     ...
;   f32x4 acc[2][2][4][2];
; #pragma unroll
;   for (int a = 0; a < 2; ++a)
; #pragma unroll
;     for (int b = 0; b < 2; ++b)
; #pragma unroll
;       for (int c = 0; c < 4; ++c)
; #pragma unroll
;         for (int d = 0; d < 2; ++d) acc[a][b][c][d] = (f32x4){0.f, 0.f, 0.f, 0.f};
;   bf16x8 At[4][2], B0[2][2], B1[2][2];
;   const int nt = K >> 6;
;   STAGE_B(SB(0, 0), 0, 0); STAGE_A(SA(0, 0), 0, 0);
;   STAGE_B(SB(0, 1), 1, 0); STAGE_A(SA(0, 1), 1, 0);
;   if (wr == 1) GBAR;
;   WAIT_V(4); GBAR;
;   STAGE_B(SB(1, 0), 0, 1); STAGE_A(SA(1, 0), 0, 1); STAGE_B(SB(1, 1), 1, 1);
;   WAIT_V(6); GBAR;
.LBB0_1750:
	s_or_b64 exec, exec, s[14:15]
	v_add_u32_e32 v161, 0x18000, v147
	v_add_u32_e32 v162, 0x1a000, v147
	v_readfirstlane_b32 s14, v161
	v_lshl_add_u64 v[2:3], v[2:3], 0, s[60:61]
	s_mov_b32 m0, s14
	v_readfirstlane_b32 s14, v162
	v_add_u32_e32 v163, 0x8000, v147
	s_waitcnt vmcnt(4)
	s_barrier
	global_load_lds_dwordx4 v[2:3], off
	v_lshl_add_u64 v[2:3], v[6:7], 0, s[60:61]
	s_mov_b32 m0, s14
	v_readfirstlane_b32 s14, v163
	v_add_u32_e32 v164, 0xa000, v147
	global_load_lds_dwordx4 v[2:3], off
	v_lshl_add_u64 v[2:3], v[8:9], 0, s[60:61]
	s_mov_b32 m0, s14
	v_readfirstlane_b32 s14, v164
	s_add_u32 s0, s0, 0x40080
	v_add_u32_e32 v165, 0x1c000, v147
	global_load_lds_dwordx4 v[2:3], off
	v_lshl_add_u64 v[2:3], v[4:5], 0, s[60:61]
	s_mov_b32 m0, s14
	s_addc_u32 s1, s1, 0
	v_readfirstlane_b32 s14, v165
	global_load_lds_dwordx4 v[2:3], off
	v_lshl_add_u64 v[2:3], v[0:1], 1, s[0:1]
	s_mov_b32 m0, s14
	v_add_u32_e32 v166, 0x1e000, v147
	global_load_lds_dwordx4 v[2:3], off
	v_lshl_add_u64 v[2:3], v[130:131], 1, s[0:1]
	v_readfirstlane_b32 s0, v166
	s_mov_b32 m0, s0
	v_and_b32_e32 v145, 15, v142
	global_load_lds_dwordx4 v[2:3], off
	v_bfe_u32 v144, v142, 4, 2
	v_lshlrev_b32_e32 v2, 4, v144
	v_lshlrev_b32_e32 v3, 6, v145
	v_lshlrev_b32_e32 v5, 2, v142
	v_or_b32_e32 v4, v2, v3
	v_and_b32_e32 v5, 32, v5
	s_mov_b32 s0, 0x14000
	v_bitop3_b32 v7, v2, v5, v3 bitop3:0x36
	v_bitop3_b32 v9, v4, s0, v5 bitop3:0xde
	s_mov_b32 s0, 0x18000
	v_lshlrev_b32_e32 v3, 6, v142
	v_bitop3_b32 v19, v4, s0, v5 bitop3:0xde
	s_mov_b32 s0, 0x1c000
	v_and_b32_e32 v3, 0x3c0, v3
	v_bitop3_b32 v8, v4, s74, v5 bitop3:0xde
	v_bitop3_b32 v20, v4, s0, v5 bitop3:0xde
	v_bitop3_b32 v21, v3, v5, v2 bitop3:0x36
	v_lshlrev_b32_e32 v2, 13, v10
	v_lshlrev_b32_e32 v4, 13, v12
	v_and_b32_e32 v2, 0xffffc000, v2
	v_and_b32_e32 v4, 0xffffc000, v4
	v_lshl_add_u32 v2, v11, 10, v2
	v_lshl_add_u32 v4, v15, 10, v4
	v_or_b32_e32 v2, v2, v13
	v_or_b32_e32 v4, v4, v16
	v_add_u32_sdwa v2, v2, sext(v14) dst_sel:DWORD dst_unused:UNUSED_PAD src0_sel:DWORD src1_sel:WORD_0
	v_mov_b32_e32 v3, v1
	s_add_u32 s0, s10, s46
	v_add_u32_sdwa v4, v4, sext(v17) dst_sel:DWORD dst_unused:UNUSED_PAD src0_sel:DWORD src1_sel:WORD_0
	v_mov_b32_e32 v5, v1
	v_lshlrev_b64 v[2:3], 1, v[2:3]
	s_addc_u32 s1, s11, 0
	v_lshlrev_b64 v[4:5], 1, v[4:5]
	s_add_i32 s23, s23, s45
	v_lshl_add_u64 v[132:133], s[0:1], 0, v[2:3]
	v_lshl_add_u64 v[136:137], s[0:1], 0, v[4:5]
	s_lshl_b32 s0, s23, 8
	s_mov_b32 s1, s35
	s_lshl_b64 s[0:1], s[0:1], 11
	s_add_u32 s0, s42, s0
	v_bfe_u32 v143, v142, 6, 2
	s_waitcnt vmcnt(6)
	v_lshlrev_b32_e32 v146, 6, v18
	v_lshlrev_b32_e32 v18, 13, v18
	s_addc_u32 s1, s43, s1
	v_lshlrev_b32_e32 v6, 12, v143
	v_or_b32_e32 v22, 0x800, v18
	v_or_b32_e32 v23, 0x1000, v18
	v_or_b32_e32 v24, 0x1800, v18
	v_lshl_add_u64 v[138:139], s[0:1], 0, v[2:3]
	v_mov_b32_e32 v2, 0
	v_lshl_add_u64 v[140:141], s[0:1], 0, v[4:5]
	s_mov_b32 s0, -2
	s_mov_b64 s[14:15], 0
	v_add_u32_e32 v168, v8, v6
	v_add_u32_e32 v152, v7, v18
	v_add_u32_e32 v151, v21, v22
	v_add_u32_e32 v150, v21, v23
	v_add_u32_e32 v149, v21, v24
	v_add_u32_e32 v167, v9, v6
	v_add_u32_e32 v160, v19, v6
	v_add_u32_e32 v155, v20, v6
	v_mov_b32_e32 v3, v2
	v_mov_b32_e32 v4, v2
	v_mov_b32_e32 v5, v2
	v_mov_b32_e32 v6, v2
	v_mov_b32_e32 v7, v2
	v_mov_b32_e32 v8, v2
	v_mov_b32_e32 v9, v2
	v_mov_b32_e32 v10, v2
	v_mov_b32_e32 v11, v2
	v_mov_b32_e32 v12, v2
	v_mov_b32_e32 v13, v2
	v_mov_b32_e32 v14, v2
	v_mov_b32_e32 v15, v2
	v_mov_b32_e32 v16, v2
	v_mov_b32_e32 v17, v2
	v_mov_b32_e32 v18, v2
	v_mov_b32_e32 v19, v2
	v_mov_b32_e32 v20, v2
	v_mov_b32_e32 v21, v2
	v_mov_b32_e32 v22, v2
	v_mov_b32_e32 v23, v2
	v_mov_b32_e32 v24, v2
	v_mov_b32_e32 v25, v2
	v_mov_b32_e32 v26, v2
	v_mov_b32_e32 v27, v2
	v_mov_b32_e32 v28, v2
	v_mov_b32_e32 v29, v2
	v_mov_b32_e32 v30, v2
	v_mov_b32_e32 v31, v2
	v_mov_b32_e32 v32, v2
	v_mov_b32_e32 v33, v2
	v_mov_b32_e32 v34, v2
	v_mov_b32_e32 v35, v2
	v_mov_b32_e32 v36, v2
	v_mov_b32_e32 v37, v2
	v_mov_b32_e32 v38, v2
	v_mov_b32_e32 v39, v2
	v_mov_b32_e32 v40, v2
	v_mov_b32_e32 v41, v2
	v_mov_b32_e32 v42, v2
	v_mov_b32_e32 v43, v2
	v_mov_b32_e32 v44, v2
	v_mov_b32_e32 v45, v2
	v_mov_b32_e32 v46, v2
	v_mov_b32_e32 v47, v2
	v_mov_b32_e32 v48, v2
	v_mov_b32_e32 v49, v2
	v_mov_b32_e32 v50, v2
	v_mov_b32_e32 v51, v2
	v_mov_b32_e32 v52, v2
	v_mov_b32_e32 v53, v2
	v_mov_b32_e32 v54, v2
	v_mov_b32_e32 v55, v2
	v_mov_b32_e32 v56, v2
	v_mov_b32_e32 v57, v2
	v_mov_b32_e32 v58, v2
	v_mov_b32_e32 v59, v2
	v_mov_b32_e32 v60, v2
	v_mov_b32_e32 v61, v2
	v_mov_b32_e32 v62, v2
	v_mov_b32_e32 v63, v2
	v_mov_b32_e32 v64, v2
	v_mov_b32_e32 v65, v2
	v_mov_b32_e32 v66, v2
	v_mov_b32_e32 v67, v2
	v_mov_b32_e32 v68, v2
	v_mov_b32_e32 v69, v2
	v_mov_b32_e32 v70, v2
	v_mov_b32_e32 v71, v2
	v_mov_b32_e32 v72, v2
	v_mov_b32_e32 v73, v2
	v_mov_b32_e32 v74, v2
	v_mov_b32_e32 v75, v2
	v_mov_b32_e32 v76, v2
	v_mov_b32_e32 v77, v2
	v_mov_b32_e32 v78, v2
	v_mov_b32_e32 v79, v2
	v_mov_b32_e32 v80, v2
	v_mov_b32_e32 v81, v2
	v_mov_b32_e32 v82, v2
	v_mov_b32_e32 v83, v2
	v_mov_b32_e32 v84, v2
	v_mov_b32_e32 v85, v2
	v_mov_b32_e32 v86, v2
	v_mov_b32_e32 v87, v2
	v_mov_b32_e32 v88, v2
	v_mov_b32_e32 v89, v2
	v_mov_b32_e32 v90, v2
	v_mov_b32_e32 v91, v2
	v_mov_b32_e32 v92, v2
	v_mov_b32_e32 v93, v2
	v_mov_b32_e32 v94, v2
	v_mov_b32_e32 v95, v2
	v_mov_b32_e32 v96, v2
	v_mov_b32_e32 v97, v2
	v_mov_b32_e32 v98, v2
	v_mov_b32_e32 v99, v2
	v_mov_b32_e32 v100, v2
	v_mov_b32_e32 v101, v2
	v_mov_b32_e32 v102, v2
	v_mov_b32_e32 v103, v2
	v_mov_b32_e32 v104, v2
	v_mov_b32_e32 v105, v2
	v_mov_b32_e32 v106, v2
	v_mov_b32_e32 v107, v2
	v_mov_b32_e32 v108, v2
	v_mov_b32_e32 v109, v2
	v_mov_b32_e32 v110, v2
	v_mov_b32_e32 v111, v2
	v_mov_b32_e32 v112, v2
	v_mov_b32_e32 v113, v2
	v_mov_b32_e32 v114, v2
	v_mov_b32_e32 v115, v2
	v_mov_b32_e32 v116, v2
	v_mov_b32_e32 v117, v2
	v_mov_b32_e32 v118, v2
	v_mov_b32_e32 v119, v2
	v_mov_b32_e32 v120, v2
	v_mov_b32_e32 v121, v2
	v_mov_b32_e32 v122, v2
	v_mov_b32_e32 v123, v2
	v_mov_b32_e32 v124, v2
	v_mov_b32_e32 v125, v2
	v_mov_b32_e32 v126, v2
	v_mov_b32_e32 v127, v2
	v_mov_b32_e32 v128, v2
	v_mov_b32_e32 v129, v2
	s_barrier

; __device__ __forceinline__ void phase0(const Params& p, char* smem) {
;     ...
;       {
;         const int nn = tid & 63, n = n0 + nn;
;         const bool ok = n < N;
;         const int sc = ok ? perm_col(perm, n) : 0;
; #pragma unroll 4
;         for (int i = 0; i < 16; ++i) {
;           int kk = i * 4 + (tid >> 6);
;           float v = 0.f;
;           if (ok) { v = src[(size_t)(k0 + kk) * N + sc]; if (scale) v *= scale[k0 + kk]; }
;           tile[kk * 65 + nn] = v;
;         }
;       }
.LBB0_1922:
	s_or_b64 exec, exec, s[46:47]
	s_lshl_b32 s18, s18, 6
	s_cmp_lg_u64 s[10:11], 0
	v_mov_b32_e32 v8, s8
	v_mov_b32_e32 v9, s9
	s_cselect_b64 s[8:9], -1, 0
	s_ashr_i32 s19, s18, 31
	v_lshl_add_u64 v[6:7], v[6:7], 2, v[8:9]
	v_mov_b32_e32 v9, s19
	v_or_b32_e32 v8, s18, v4
	v_lshl_or_b32 v10, s80, 6, v4
	s_lshl_b32 s46, s79, 6
	v_lshl_add_u64 v[8:9], v[8:9], 2, s[10:11]
	v_subrev_u32_e32 v20, s46, v10
	v_lshl_add_u64 v[8:9], v[8:9], 0, 32
	s_mov_b32 s48, 0
	v_cndmask_b32_e64 v21, 0, 1, s[8:9]
	v_mov_b32_e32 v22, v19
	s_and_b64 vcc, exec, s[8:9]
	s_cbranch_vccnz .LBB0_1924
	v_mov_b32_e32 v100, 0
	v_mov_b32_e32 v101, 0
	v_mov_b32_e32 v102, 0
	v_mov_b32_e32 v103, 0
	v_mov_b32_e32 v104, 0
	v_mov_b32_e32 v105, 0
	v_mov_b32_e32 v106, 0
	v_mov_b32_e32 v107, 0
	v_mov_b32_e32 v108, 0
	v_mov_b32_e32 v109, 0
	v_mov_b32_e32 v110, 0
	v_mov_b32_e32 v111, 0
	v_mov_b32_e32 v112, 0
	v_mov_b32_e32 v113, 0
	v_mov_b32_e32 v114, 0
	v_mov_b32_e32 v115, 0
	s_and_saveexec_b64 s[46:47], s[6:7]
	s_cbranch_execz .Lp0_fast_done
	v_mad_i64_i32 v[116:117], s[80:81], v20, s17, 0
	s_lshl_b32 s48, s17, 4
	s_mov_b32 s49, 0
	v_lshl_add_u64 v[116:117], v[116:117], 2, v[6:7]
	global_load_dword v100, v[116:117], off
	v_lshl_add_u64 v[116:117], v[116:117], 0, s[48:49]
	global_load_dword v101, v[116:117], off
	v_lshl_add_u64 v[116:117], v[116:117], 0, s[48:49]
	global_load_dword v102, v[116:117], off
	v_lshl_add_u64 v[116:117], v[116:117], 0, s[48:49]
	global_load_dword v103, v[116:117], off
	v_lshl_add_u64 v[116:117], v[116:117], 0, s[48:49]
	global_load_dword v104, v[116:117], off
	v_lshl_add_u64 v[116:117], v[116:117], 0, s[48:49]
	global_load_dword v105, v[116:117], off
	v_lshl_add_u64 v[116:117], v[116:117], 0, s[48:49]
	global_load_dword v106, v[116:117], off
	v_lshl_add_u64 v[116:117], v[116:117], 0, s[48:49]
	global_load_dword v107, v[116:117], off
	v_lshl_add_u64 v[116:117], v[116:117], 0, s[48:49]
	global_load_dword v108, v[116:117], off
	v_lshl_add_u64 v[116:117], v[116:117], 0, s[48:49]
	global_load_dword v109, v[116:117], off
	v_lshl_add_u64 v[116:117], v[116:117], 0, s[48:49]
	global_load_dword v110, v[116:117], off
	v_lshl_add_u64 v[116:117], v[116:117], 0, s[48:49]
	global_load_dword v111, v[116:117], off
	v_lshl_add_u64 v[116:117], v[116:117], 0, s[48:49]
	global_load_dword v112, v[116:117], off
	v_lshl_add_u64 v[116:117], v[116:117], 0, s[48:49]
	global_load_dword v113, v[116:117], off
	v_lshl_add_u64 v[116:117], v[116:117], 0, s[48:49]
	global_load_dword v114, v[116:117], off
	v_lshl_add_u64 v[116:117], v[116:117], 0, s[48:49]
	global_load_dword v115, v[116:117], off
.Lp0_fast_done:
	s_or_b64 exec, exec, s[46:47]
	s_waitcnt vmcnt(0)
	ds_write_b32 v19, v100
	ds_write_b32 v19, v101 offset:1040
	ds_write_b32 v19, v102 offset:2080
	ds_write_b32 v19, v103 offset:3120
	ds_write_b32 v19, v104 offset:4160
	ds_write_b32 v19, v105 offset:5200
	ds_write_b32 v19, v106 offset:6240
	ds_write_b32 v19, v107 offset:7280
	ds_write_b32 v19, v108 offset:8320
	ds_write_b32 v19, v109 offset:9360
	ds_write_b32 v19, v110 offset:10400
	ds_write_b32 v19, v111 offset:11440
	ds_write_b32 v19, v112 offset:12480
	ds_write_b32 v19, v113 offset:13520
	ds_write_b32 v19, v114 offset:14560
	ds_write_b32 v19, v115 offset:15600
	s_branch .LBB0_1936
	s_branch .LBB0_1924
